# prompt attention loops: s_setprio 1 around each 16-MFMA cluster (QK^T, PV), 0 elsewhere
# baseline (speedup 1.0000x reference)
; #define SBAR() __builtin_amdgcn_sched_barrier(0)
; template <int OFF> __device__ __forceinline__ s16x4 tr_read(int vb) { s16x4 r; asm volatile("ds_read_b64_tr_b16 %0, %1 offset:%2" : "=&v"(r) : "v"(vb), "i"(OFF) : "memory"); return r; }
; template <int D0> __device__ __forceinline__ void pv_one(f32x16& od, int vb, bf16x8 pa0, bf16x8 pa1, bf16x8 pa2, bf16x8 pa3) {
;     const s16x4 l0 = tr_read<v_rd_off(D0, 0, 0)>(vb), h0 = tr_read<v_rd_off(D0, 0, 1)>(vb), l1 = tr_read<v_rd_off(D0, 1, 0)>(vb), h1 = tr_read<v_rd_off(D0, 1, 1)>(vb);
;     const s16x4 l2 = tr_read<v_rd_off(D0, 2, 0)>(vb), h2 = tr_read<v_rd_off(D0, 2, 1)>(vb), l3 = tr_read<v_rd_off(D0, 3, 0)>(vb), h3 = tr_read<v_rd_off(D0, 3, 1)>(vb);
;     asm volatile("s_waitcnt lgkmcnt(0)" ::: "memory"); SBAR();
;     ...
;     od = __builtin_amdgcn_mfma_f32_32x32x16_bf16(pa0, PKV(l0, h0), od, 0, 0, 0);
;     od = __builtin_amdgcn_mfma_f32_32x32x16_bf16(pa1, PKV(l1, h1), od, 0, 0, 0);
;     od = __builtin_amdgcn_mfma_f32_32x32x16_bf16(pa2, PKV(l2, h2), od, 0, 0, 0);
;     od = __builtin_amdgcn_mfma_f32_32x32x16_bf16(pa3, PKV(l3, h3), od, 0, 0, 0);
;     ...
; }
; __device__ __forceinline__ void pv_d0(f32x16* o, int vb, bf16x8 pa0, bf16x8 pa1, bf16x8 pa2, bf16x8 pa3) {
;     pv_one<0>(o[0], vb, pa0, pa1, pa2, pa3); pv_one<1>(o[1], vb, pa0, pa1, pa2, pa3); pv_one<2>(o[2], vb, pa0, pa1, pa2, pa3); pv_one<3>(o[3], vb, pa0, pa1, pa2, pa3);
; }
; template <int MODE, bool SAMPLE>
; __device__ __forceinline__ void attn_unit(const Params& p, char* lds, int b, int h, int qb) {
;     ...
;                 { auto rr = __builtin_amdgcn_permlane32_swap(__float_as_uint(ps), __float_as_uint(ps), false, false); ps = __uint_as_float(rr[0]) + __uint_as_float(rr[1]); }
;                 l_reg = l_reg * alpha + ps;
;     ...
;             PK4(p0, 0, pa0); PK4(p0, 8, pa1); PK4(p1, 0, pa2); PK4(p1, 8, pa3);
;             pv_d0(o, vb, pa0, pa1, pa2, pa3);
.LBB0_680:
	v_cvt_pk_bf16_f32 v222, v161, v220
	v_cvt_pk_bf16_f32 v223, v81, v82
	v_cvt_pk_bf16_f32 v224, v83, v84
	v_cvt_pk_bf16_f32 v225, v85, v221
	v_cvt_pk_bf16_f32 v82, v86, v87
	v_cvt_pk_bf16_f32 v83, v88, v89
	v_cvt_pk_bf16_f32 v84, v90, v91
	v_cvt_pk_bf16_f32 v85, v92, v79
	v_cvt_pk_bf16_f32 v64, v64, v65
	v_cvt_pk_bf16_f32 v65, v66, v67
	v_cvt_pk_bf16_f32 v66, v68, v69
	v_cvt_pk_bf16_f32 v67, v70, v80
	v_cvt_pk_bf16_f32 v68, v71, v72
	v_cvt_pk_bf16_f32 v69, v73, v74
	v_cvt_pk_bf16_f32 v70, v75, v76
	v_cvt_pk_bf16_f32 v71, v77, v78
	ds_read_b64_tr_b16 v[72:73], v180 offset:0
	ds_read_b64_tr_b16 v[74:75], v180 offset:0x800
	ds_read_b64_tr_b16 v[76:77], v180 offset:0x1000
	ds_read_b64_tr_b16 v[78:79], v180 offset:0x1800
	ds_read_b64_tr_b16 v[86:87], v180 offset:0x2000
	ds_read_b64_tr_b16 v[88:89], v180 offset:0x2800
	v_add_f32_e32 v94, v94, v95
	ds_read_b64_tr_b16 v[90:91], v180 offset:0x3000
	v_fmac_f32_e32 v94, v219, v93
	ds_read_b64_tr_b16 v[92:93], v180 offset:0x3800
	s_waitcnt lgkmcnt(0)
	v_permlane32_swap_b32_e32 v222, v224
	v_permlane32_swap_b32_e32 v223, v225
	v_permlane32_swap_b32_e32 v82, v84
	v_permlane32_swap_b32_e32 v83, v85
	v_permlane32_swap_b32_e32 v64, v66
	v_permlane32_swap_b32_e32 v65, v67
	v_permlane32_swap_b32_e32 v68, v70
	v_permlane32_swap_b32_e32 v69, v71
	s_setprio 1
	v_mfma_f32_32x32x16_bf16 v[16:31], v[222:225], v[72:75], v[16:31]
	ds_read_b64_tr_b16 v[72:73], v180 offset:0x200
	ds_read_b64_tr_b16 v[74:75], v180 offset:0xa00
	v_mfma_f32_32x32x16_bf16 v[16:31], v[82:85], v[76:79], v[16:31]
	ds_read_b64_tr_b16 v[76:77], v180 offset:0x1200
	ds_read_b64_tr_b16 v[78:79], v180 offset:0x1a00
	v_mfma_f32_32x32x16_bf16 v[16:31], v[64:67], v[86:89], v[16:31]
	ds_read_b64_tr_b16 v[86:87], v180 offset:0x2200
	ds_read_b64_tr_b16 v[88:89], v180 offset:0x2a00
	ds_read_b64_tr_b16 v[226:227], v180 offset:0x3200
	ds_read_b64_tr_b16 v[228:229], v180 offset:0x3a00
	s_waitcnt lgkmcnt(0)
	v_mfma_f32_32x32x16_bf16 v[16:31], v[68:71], v[90:93], v[16:31]
	v_mfma_f32_32x32x16_bf16 v[48:63], v[222:225], v[72:75], v[48:63]
	ds_read_b64_tr_b16 v[72:73], v180 offset:0x400
	ds_read_b64_tr_b16 v[74:75], v180 offset:0xc00
	v_mfma_f32_32x32x16_bf16 v[48:63], v[82:85], v[76:79], v[48:63]
	ds_read_b64_tr_b16 v[76:77], v180 offset:0x1400
	ds_read_b64_tr_b16 v[78:79], v180 offset:0x1c00
	v_mfma_f32_32x32x16_bf16 v[48:63], v[64:67], v[86:89], v[48:63]
	ds_read_b64_tr_b16 v[86:87], v180 offset:0x2400
	ds_read_b64_tr_b16 v[88:89], v180 offset:0x2c00
	ds_read_b64_tr_b16 v[90:91], v180 offset:0x3400
	ds_read_b64_tr_b16 v[92:93], v180 offset:0x3c00
	s_waitcnt lgkmcnt(0)
	v_mfma_f32_32x32x16_bf16 v[48:63], v[68:71], v[226:229], v[48:63]
	v_mfma_f32_32x32x16_bf16 v[32:47], v[222:225], v[72:75], v[32:47]
	ds_read_b64_tr_b16 v[72:73], v180 offset:0x600
	ds_read_b64_tr_b16 v[74:75], v180 offset:0xe00
	v_mfma_f32_32x32x16_bf16 v[32:47], v[82:85], v[76:79], v[32:47]
	ds_read_b64_tr_b16 v[76:77], v180 offset:0x1600
	ds_read_b64_tr_b16 v[78:79], v180 offset:0x1e00
	v_mfma_f32_32x32x16_bf16 v[32:47], v[64:67], v[86:89], v[32:47]
	ds_read_b64_tr_b16 v[86:87], v180 offset:0x2600
	ds_read_b64_tr_b16 v[88:89], v180 offset:0x2e00
	ds_read_b64_tr_b16 v[226:227], v180 offset:0x3600
	ds_read_b64_tr_b16 v[228:229], v180 offset:0x3e00
	s_waitcnt lgkmcnt(0)
	v_mfma_f32_32x32x16_bf16 v[32:47], v[68:71], v[90:93], v[32:47]
	v_mfma_f32_32x32x16_bf16 v[0:15], v[222:225], v[72:75], v[0:15]
	v_mov_b32_e32 v219, v94
	v_mfma_f32_32x32x16_bf16 v[0:15], v[82:85], v[76:79], v[0:15]
	v_mfma_f32_32x32x16_bf16 v[0:15], v[64:67], v[86:89], v[0:15]
	v_mfma_f32_32x32x16_bf16 v[0:15], v[68:71], v[226:229], v[0:15]
	s_setprio 0

; __device__ __forceinline__ int crow(int r, int hi) { return (r & 3) + 8 * (r >> 2) + 4 * hi; }
; __device__ __forceinline__ void qkt(f32x16& p0, f32x16& p1, const char* Ks, const char* Qs, int r32, int hi) {
; #pragma unroll
;     for (int d0 = 0; d0 < 8; ++d0) { const int cb = (d0 * 16 + hi * 8) * 2;
;         const bf16x8 qv = *reinterpret_cast<const bf16x8*>(Qs + KSWZ(r32, cb));
;         const bf16x8 b0 = *reinterpret_cast<const bf16x8*>(Ks + KSWZ(r32, cb));
;         const bf16x8 b1 = *reinterpret_cast<const bf16x8*>(Ks + KSWZ(32 + r32, cb));
;         p0 = __builtin_amdgcn_mfma_f32_32x32x16_bf16(b0, qv, p0, 0, 0, 0);
;         p1 = __builtin_amdgcn_mfma_f32_32x32x16_bf16(b1, qv, p1, 0, 0, 0); }
; }
; template <int MODE, bool SAMPLE>
; __device__ __forceinline__ void attn_unit(const Params& p, char* lds, int b, int h, int qb) {
;     ...
;             if (MODE == 0) {
;                 const float* bt = biasL + j * 64 + 4 * hi;
; #pragma unroll
;                 for (int g = 0; g < 4; ++g) { const f32x4 a = *(const f32x4*)(bt + 8 * g), c = *(const f32x4*)(bt + 32 + 8 * g);
; #pragma unroll
;                     for (int i = 0; i < 4; ++i) { p0[4 * g + i] = a[i]; p1[4 * g + i] = c[i]; } }
;                 qkt(p0, p1, Kt, Qs, r32, hi);
;                 if (j == jd) {
; #pragma unroll
;                     for (int r = 0; r < 16; ++r) { const int kp = j * 64 + crow(r, hi); if (kp > qpos) p0[r] = -1e30f; if (kp + 32 > qpos) p1[r] = -1e30f; } }
.Lstg_0:
	ds_read_b128 v[64:67], v216 offset:256
	ds_read_b128 v[68:71], v216 offset:288
	ds_read_b128 v[80:83], v202 offset:16384
	ds_read_b128 v[72:75], v216 offset:320
	ds_read_b128 v[76:79], v216 offset:352
	v_add_u32_e32 v84, s26, v182
	ds_read_b128 v[220:223], v84
	ds_read_b128 v[224:227], v202 offset:24576
	v_add_u32_e32 v84, s26, v184
	ds_read_b128 v[228:231], v84
	s_waitcnt lgkmcnt(2)
	s_setprio 1
	v_mfma_f32_32x32x16_bf16 v[64:79], v[80:83], v[220:223], v[64:79]
	ds_read_b128 v[80:83], v216 offset:384
	ds_read_b128 v[84:87], v216 offset:416
	ds_read_b128 v[88:91], v216 offset:448
	ds_read_b128 v[92:95], v216 offset:480
	v_add_u32_e32 v161, s26, v185
	s_cmp_lg_u32 s21, s20
	s_waitcnt lgkmcnt(0)
	v_mfma_f32_32x32x16_bf16 v[80:95], v[224:227], v[220:223], v[80:95]
	ds_read_b128 v[220:223], v203 offset:16384
	ds_read_b128 v[224:227], v203 offset:24576
	s_waitcnt lgkmcnt(1)
	v_mfma_f32_32x32x16_bf16 v[64:79], v[220:223], v[228:231], v[64:79]
	ds_read_b128 v[220:223], v204 offset:16384
	s_waitcnt lgkmcnt(1)
	v_mfma_f32_32x32x16_bf16 v[80:95], v[224:227], v[228:231], v[80:95]
	ds_read_b128 v[224:227], v161
	ds_read_b128 v[228:231], v204 offset:24576
	v_add_u32_e32 v161, s26, v186
	ds_read_b128 v[232:235], v161
	v_add_u32_e32 v161, s26, v187
	s_waitcnt lgkmcnt(2)
	v_mfma_f32_32x32x16_bf16 v[64:79], v[220:223], v[224:227], v[64:79]
	s_waitcnt lgkmcnt(1)
	v_mfma_f32_32x32x16_bf16 v[80:95], v[228:231], v[224:227], v[80:95]
	ds_read_b128 v[220:223], v205 offset:16384
	ds_read_b128 v[224:227], v205 offset:24576
	s_waitcnt lgkmcnt(1)
	v_mfma_f32_32x32x16_bf16 v[64:79], v[220:223], v[232:235], v[64:79]
	ds_read_b128 v[220:223], v206 offset:16384
	s_waitcnt lgkmcnt(1)
	v_mfma_f32_32x32x16_bf16 v[80:95], v[224:227], v[232:235], v[80:95]
	ds_read_b128 v[224:227], v161
	ds_read_b128 v[228:231], v206 offset:24576
	v_add_u32_e32 v161, s26, v188
	ds_read_b128 v[232:235], v161
	v_add_u32_e32 v161, s26, v189
	s_waitcnt lgkmcnt(2)
	v_mfma_f32_32x32x16_bf16 v[64:79], v[220:223], v[224:227], v[64:79]
	s_waitcnt lgkmcnt(1)
	v_mfma_f32_32x32x16_bf16 v[80:95], v[228:231], v[224:227], v[80:95]
	ds_read_b128 v[220:223], v207 offset:16384
	ds_read_b128 v[224:227], v207 offset:24576
	s_waitcnt lgkmcnt(1)
	v_mfma_f32_32x32x16_bf16 v[64:79], v[220:223], v[232:235], v[64:79]
	ds_read_b128 v[220:223], v208 offset:16384
	s_waitcnt lgkmcnt(1)
	v_mfma_f32_32x32x16_bf16 v[80:95], v[224:227], v[232:235], v[80:95]
	ds_read_b128 v[224:227], v161
	ds_read_b128 v[228:231], v208 offset:24576
	v_add_u32_e32 v161, s26, v190
	ds_read_b128 v[232:235], v161
	s_waitcnt lgkmcnt(2)
	v_mfma_f32_32x32x16_bf16 v[64:79], v[220:223], v[224:227], v[64:79]
	s_waitcnt lgkmcnt(1)
	v_mfma_f32_32x32x16_bf16 v[80:95], v[228:231], v[224:227], v[80:95]
	ds_read_b128 v[220:223], v209 offset:16384
	ds_read_b128 v[224:227], v209 offset:24576
	s_waitcnt lgkmcnt(1)
	v_mfma_f32_32x32x16_bf16 v[64:79], v[220:223], v[232:235], v[64:79]
	s_waitcnt lgkmcnt(0)
	v_mfma_f32_32x32x16_bf16 v[80:95], v[224:227], v[232:235], v[80:95]
	s_setprio 0
	s_cbranch_scc1 .LBB0_688
	v_add_u32_e32 v161, s16, v218
	v_add_u32_e32 v221, 0x60, v161
	v_add_u32_e32 v220, 64, v161
	v_cmp_le_i32_e32 vcc, v221, v215
	s_nop 6
	v_cndmask_b32_e32 v80, v214, v80, vcc
	v_cmp_lt_i32_e32 vcc, v220, v215
	s_nop 1
	v_cndmask_b32_e32 v65, v214, v65, vcc
	v_cmp_le_i32_e32 vcc, v220, v215
	v_add_u32_e32 v220, 0x61, v161
	s_nop 0
	v_cndmask_b32_e32 v64, v214, v64, vcc
	v_cmp_le_i32_e32 vcc, v220, v215
	v_add_u32_e32 v220, 0x42, v161
	s_nop 0
	v_cndmask_b32_e32 v81, v214, v81, vcc
	v_cmp_le_i32_e32 vcc, v220, v215
	v_add_u32_e32 v220, 0x62, v161
	s_nop 0
	v_cndmask_b32_e32 v66, v214, v66, vcc
	v_cmp_le_i32_e32 vcc, v220, v215
	v_add_u32_e32 v220, 0x43, v161
	s_nop 0
	v_cndmask_b32_e32 v82, v214, v82, vcc
	v_cmp_le_i32_e32 vcc, v220, v215
	v_add_u32_e32 v220, 0x63, v161
	s_nop 0
	v_cndmask_b32_e32 v67, v214, v67, vcc
	v_cmp_le_i32_e32 vcc, v220, v215
	v_add_u32_e32 v220, 0x48, v161
	s_nop 0
	v_cndmask_b32_e32 v83, v214, v83, vcc
	v_cmp_le_i32_e32 vcc, v220, v215
	v_add_u32_e32 v220, 0x68, v161
	s_nop 0
	v_cndmask_b32_e32 v68, v214, v68, vcc
	v_cmp_le_i32_e32 vcc, v220, v215
	v_add_u32_e32 v220, 0x49, v161
	s_nop 0
	v_cndmask_b32_e32 v84, v214, v84, vcc
	v_cmp_le_i32_e32 vcc, v220, v215
	v_add_u32_e32 v220, 0x69, v161
	s_nop 0
	v_cndmask_b32_e32 v69, v214, v69, vcc
	v_cmp_le_i32_e32 vcc, v220, v215
	v_add_u32_e32 v220, 0x4a, v161
	s_nop 0
	v_cndmask_b32_e32 v85, v214, v85, vcc
	v_cmp_le_i32_e32 vcc, v220, v215
	v_add_u32_e32 v220, 0x6a, v161
	s_nop 0
	v_cndmask_b32_e32 v70, v214, v70, vcc
	v_cmp_le_i32_e32 vcc, v220, v215
	v_add_u32_e32 v220, 0x4b, v161
	s_nop 0
	v_cndmask_b32_e32 v86, v214, v86, vcc
	v_cmp_le_i32_e32 vcc, v220, v215
	v_add_u32_e32 v220, 0x6b, v161
	s_nop 0
	v_cndmask_b32_e32 v71, v214, v71, vcc
	v_cmp_le_i32_e32 vcc, v220, v215
	v_add_u32_e32 v220, 0x50, v161
	s_nop 0
	v_cndmask_b32_e32 v87, v214, v87, vcc
	v_cmp_le_i32_e32 vcc, v220, v215
	v_add_u32_e32 v220, 0x70, v161
	s_nop 0
	v_cndmask_b32_e32 v72, v214, v72, vcc
	v_cmp_le_i32_e32 vcc, v220, v215
	v_add_u32_e32 v220, 0x51, v161
	s_nop 0
	v_cndmask_b32_e32 v88, v214, v88, vcc
	v_cmp_le_i32_e32 vcc, v220, v215
	v_add_u32_e32 v220, 0x71, v161
	s_nop 0
	v_cndmask_b32_e32 v73, v214, v73, vcc
	v_cmp_le_i32_e32 vcc, v220, v215
	v_add_u32_e32 v220, 0x52, v161
	s_nop 0
	v_cndmask_b32_e32 v89, v214, v89, vcc
	v_cmp_le_i32_e32 vcc, v220, v215
	v_add_u32_e32 v220, 0x72, v161
	s_nop 0
	v_cndmask_b32_e32 v74, v214, v74, vcc
	v_cmp_le_i32_e32 vcc, v220, v215
	v_add_u32_e32 v220, 0x53, v161
	s_nop 0
	v_cndmask_b32_e32 v90, v214, v90, vcc
	v_cmp_le_i32_e32 vcc, v220, v215
	v_add_u32_e32 v220, 0x73, v161
	s_nop 0
	v_cndmask_b32_e32 v75, v214, v75, vcc
	v_cmp_le_i32_e32 vcc, v220, v215
	v_add_u32_e32 v220, 0x58, v161
	s_nop 0
	v_cndmask_b32_e32 v91, v214, v91, vcc
	v_cmp_le_i32_e32 vcc, v220, v215
	v_add_u32_e32 v220, 0x78, v161
	s_nop 0
	v_cndmask_b32_e32 v76, v214, v76, vcc
	v_cmp_le_i32_e32 vcc, v220, v215
	v_add_u32_e32 v220, 0x59, v161
	s_nop 0
	v_cndmask_b32_e32 v92, v214, v92, vcc
	v_cmp_le_i32_e32 vcc, v220, v215
	v_add_u32_e32 v220, 0x79, v161
	s_nop 0
	v_cndmask_b32_e32 v77, v214, v77, vcc
	v_cmp_le_i32_e32 vcc, v220, v215
	v_add_u32_e32 v220, 0x5a, v161
	s_nop 0
	v_cndmask_b32_e32 v93, v214, v93, vcc
	v_cmp_le_i32_e32 vcc, v220, v215
	v_add_u32_e32 v220, 0x7a, v161
	s_nop 0
	v_cndmask_b32_e32 v78, v214, v78, vcc
	v_cmp_le_i32_e32 vcc, v220, v215
	v_add_u32_e32 v220, 0x5b, v161
	v_add_u32_e32 v161, 0x7b, v161
	v_cndmask_b32_e32 v94, v214, v94, vcc
	v_cmp_le_i32_e32 vcc, v220, v215
	s_nop 1
	v_cndmask_b32_e32 v79, v214, v79, vcc
	v_cmp_le_i32_e32 vcc, v161, v215
	s_nop 1
	v_cndmask_b32_e32 v95, v214, v95, vcc

; #define SBAR() __builtin_amdgcn_sched_barrier(0)
; template <int OFF> __device__ __forceinline__ s16x4 tr_read(int vb) { s16x4 r; asm volatile("ds_read_b64_tr_b16 %0, %1 offset:%2" : "=&v"(r) : "v"(vb), "i"(OFF) : "memory"); return r; }
; template <int D0> __device__ __forceinline__ void pv_one(f32x16& od, int vb, bf16x8 pa0, bf16x8 pa1, bf16x8 pa2, bf16x8 pa3) {
;     const s16x4 l0 = tr_read<v_rd_off(D0, 0, 0)>(vb), h0 = tr_read<v_rd_off(D0, 0, 1)>(vb), l1 = tr_read<v_rd_off(D0, 1, 0)>(vb), h1 = tr_read<v_rd_off(D0, 1, 1)>(vb);
;     const s16x4 l2 = tr_read<v_rd_off(D0, 2, 0)>(vb), h2 = tr_read<v_rd_off(D0, 2, 1)>(vb), l3 = tr_read<v_rd_off(D0, 3, 0)>(vb), h3 = tr_read<v_rd_off(D0, 3, 1)>(vb);
;     asm volatile("s_waitcnt lgkmcnt(0)" ::: "memory"); SBAR();
;     ...
;     od = __builtin_amdgcn_mfma_f32_32x32x16_bf16(pa0, PKV(l0, h0), od, 0, 0, 0);
;     od = __builtin_amdgcn_mfma_f32_32x32x16_bf16(pa1, PKV(l1, h1), od, 0, 0, 0);
;     od = __builtin_amdgcn_mfma_f32_32x32x16_bf16(pa2, PKV(l2, h2), od, 0, 0, 0);
;     od = __builtin_amdgcn_mfma_f32_32x32x16_bf16(pa3, PKV(l3, h3), od, 0, 0, 0);
;     ...
; }
; __device__ __forceinline__ void pv_d0(f32x16* o, int vb, bf16x8 pa0, bf16x8 pa1, bf16x8 pa2, bf16x8 pa3) {
;     pv_one<0>(o[0], vb, pa0, pa1, pa2, pa3); pv_one<1>(o[1], vb, pa0, pa1, pa2, pa3); pv_one<2>(o[2], vb, pa0, pa1, pa2, pa3); pv_one<3>(o[3], vb, pa0, pa1, pa2, pa3);
; }
; template <int MODE, bool SAMPLE>
; __device__ __forceinline__ void attn_unit(const Params& p, char* lds, int b, int h, int qb) {
;     ...
;             PK4(p0, 0, pa0); PK4(p0, 8, pa1); PK4(p1, 0, pa2); PK4(p1, 8, pa3);
;             pv_d0(o, vb, pa0, pa1, pa2, pa3);
.LBB0_692:
	v_cvt_pk_bf16_f32 v222, v161, v220
	v_cvt_pk_bf16_f32 v223, v81, v82
	v_cvt_pk_bf16_f32 v224, v83, v84
	v_cvt_pk_bf16_f32 v225, v85, v221
	v_cvt_pk_bf16_f32 v82, v86, v87
	v_cvt_pk_bf16_f32 v83, v88, v89
	v_cvt_pk_bf16_f32 v84, v90, v91
	v_cvt_pk_bf16_f32 v85, v92, v79
	v_cvt_pk_bf16_f32 v64, v64, v65
	v_cvt_pk_bf16_f32 v65, v66, v67
	v_cvt_pk_bf16_f32 v66, v68, v69
	v_cvt_pk_bf16_f32 v67, v70, v80
	v_cvt_pk_bf16_f32 v68, v71, v72
	v_cvt_pk_bf16_f32 v69, v73, v74
	v_cvt_pk_bf16_f32 v70, v75, v76
	v_cvt_pk_bf16_f32 v71, v77, v78
	ds_read_b64_tr_b16 v[72:73], v191 offset:0
	ds_read_b64_tr_b16 v[74:75], v191 offset:0x800
	ds_read_b64_tr_b16 v[76:77], v191 offset:0x1000
	ds_read_b64_tr_b16 v[78:79], v191 offset:0x1800
	ds_read_b64_tr_b16 v[86:87], v191 offset:0x2000
	ds_read_b64_tr_b16 v[88:89], v191 offset:0x2800
	v_add_f32_e32 v94, v94, v95
	ds_read_b64_tr_b16 v[90:91], v191 offset:0x3000
	v_fmac_f32_e32 v94, v219, v93
	ds_read_b64_tr_b16 v[92:93], v191 offset:0x3800
	s_waitcnt lgkmcnt(0)
	v_permlane32_swap_b32_e32 v222, v224
	v_permlane32_swap_b32_e32 v223, v225
	v_permlane32_swap_b32_e32 v82, v84
	v_permlane32_swap_b32_e32 v83, v85
	v_permlane32_swap_b32_e32 v64, v66
	v_permlane32_swap_b32_e32 v65, v67
	v_permlane32_swap_b32_e32 v68, v70
	v_permlane32_swap_b32_e32 v69, v71
	s_setprio 1
	v_mfma_f32_32x32x16_bf16 v[16:31], v[222:225], v[72:75], v[16:31]
	ds_read_b64_tr_b16 v[72:73], v191 offset:0x200
	ds_read_b64_tr_b16 v[74:75], v191 offset:0xa00
	v_mfma_f32_32x32x16_bf16 v[16:31], v[82:85], v[76:79], v[16:31]
	ds_read_b64_tr_b16 v[76:77], v191 offset:0x1200
	ds_read_b64_tr_b16 v[78:79], v191 offset:0x1a00
	v_mfma_f32_32x32x16_bf16 v[16:31], v[64:67], v[86:89], v[16:31]
	ds_read_b64_tr_b16 v[86:87], v191 offset:0x2200
	ds_read_b64_tr_b16 v[88:89], v191 offset:0x2a00
	ds_read_b64_tr_b16 v[226:227], v191 offset:0x3200
	ds_read_b64_tr_b16 v[228:229], v191 offset:0x3a00
	s_waitcnt lgkmcnt(0)
	v_mfma_f32_32x32x16_bf16 v[16:31], v[68:71], v[90:93], v[16:31]
	v_mfma_f32_32x32x16_bf16 v[48:63], v[222:225], v[72:75], v[48:63]
	ds_read_b64_tr_b16 v[72:73], v191 offset:0x400
	ds_read_b64_tr_b16 v[74:75], v191 offset:0xc00
	v_mfma_f32_32x32x16_bf16 v[48:63], v[82:85], v[76:79], v[48:63]
	ds_read_b64_tr_b16 v[76:77], v191 offset:0x1400
	ds_read_b64_tr_b16 v[78:79], v191 offset:0x1c00
	v_mfma_f32_32x32x16_bf16 v[48:63], v[64:67], v[86:89], v[48:63]
	ds_read_b64_tr_b16 v[86:87], v191 offset:0x2400
	ds_read_b64_tr_b16 v[88:89], v191 offset:0x2c00
	ds_read_b64_tr_b16 v[90:91], v191 offset:0x3400
	ds_read_b64_tr_b16 v[92:93], v191 offset:0x3c00
	s_waitcnt lgkmcnt(0)
	v_mfma_f32_32x32x16_bf16 v[48:63], v[68:71], v[226:229], v[48:63]
	v_mfma_f32_32x32x16_bf16 v[32:47], v[222:225], v[72:75], v[32:47]
	ds_read_b64_tr_b16 v[72:73], v191 offset:0x600
	ds_read_b64_tr_b16 v[74:75], v191 offset:0xe00
	v_mfma_f32_32x32x16_bf16 v[32:47], v[82:85], v[76:79], v[32:47]
	ds_read_b64_tr_b16 v[76:77], v191 offset:0x1600
	ds_read_b64_tr_b16 v[78:79], v191 offset:0x1e00
	v_mfma_f32_32x32x16_bf16 v[32:47], v[64:67], v[86:89], v[32:47]
	ds_read_b64_tr_b16 v[86:87], v191 offset:0x2600
	ds_read_b64_tr_b16 v[88:89], v191 offset:0x2e00
	ds_read_b64_tr_b16 v[226:227], v191 offset:0x3600
	ds_read_b64_tr_b16 v[228:229], v191 offset:0x3e00
	s_waitcnt lgkmcnt(0)
	v_mfma_f32_32x32x16_bf16 v[32:47], v[68:71], v[90:93], v[32:47]
	v_mfma_f32_32x32x16_bf16 v[0:15], v[222:225], v[72:75], v[0:15]
	v_mov_b32_e32 v219, v94
	v_mfma_f32_32x32x16_bf16 v[0:15], v[82:85], v[76:79], v[0:15]
	v_mfma_f32_32x32x16_bf16 v[0:15], v[64:67], v[86:89], v[0:15]
	v_mfma_f32_32x32x16_bf16 v[0:15], v[68:71], v[226:229], v[0:15]
	s_setprio 0

; __device__ __forceinline__ int crow(int r, int hi) { return (r & 3) + 8 * (r >> 2) + 4 * hi; }
; __device__ __forceinline__ void qkt(f32x16& p0, f32x16& p1, const char* Ks, const char* Qs, int r32, int hi) {
; #pragma unroll
;     for (int d0 = 0; d0 < 8; ++d0) { const int cb = (d0 * 16 + hi * 8) * 2;
;         const bf16x8 qv = *reinterpret_cast<const bf16x8*>(Qs + KSWZ(r32, cb));
;         const bf16x8 b0 = *reinterpret_cast<const bf16x8*>(Ks + KSWZ(r32, cb));
;         const bf16x8 b1 = *reinterpret_cast<const bf16x8*>(Ks + KSWZ(32 + r32, cb));
;         p0 = __builtin_amdgcn_mfma_f32_32x32x16_bf16(b0, qv, p0, 0, 0, 0);
;         p1 = __builtin_amdgcn_mfma_f32_32x32x16_bf16(b1, qv, p1, 0, 0, 0); }
; }
; template <int MODE, bool SAMPLE>
; __device__ __forceinline__ void attn_unit(const Params& p, char* lds, int b, int h, int qb) {
;     ...
;             if (MODE == 0) {
;                 const float* bt = biasL + j * 64 + 4 * hi;
; #pragma unroll
;                 for (int g = 0; g < 4; ++g) { const f32x4 a = *(const f32x4*)(bt + 8 * g), c = *(const f32x4*)(bt + 32 + 8 * g);
; #pragma unroll
;                     for (int i = 0; i < 4; ++i) { p0[4 * g + i] = a[i]; p1[4 * g + i] = c[i]; } }
;                 qkt(p0, p1, Kt, Qs, r32, hi);
;                 if (j == jd) {
; #pragma unroll
;                     for (int r = 0; r < 16; ++r) { const int kp = j * 64 + crow(r, hi); if (kp > qpos) p0[r] = -1e30f; if (kp + 32 > qpos) p1[r] = -1e30f; } }
.Lstg_1:
	ds_read_b128 v[64:67], v216
	ds_read_b128 v[68:71], v216 offset:32
	ds_read_b128 v[80:83], v202
	ds_read_b128 v[72:75], v216 offset:64
	ds_read_b128 v[76:79], v216 offset:96
	v_add_u32_e32 v84, s26, v182
	ds_read_b128 v[220:223], v84
	ds_read_b128 v[224:227], v202 offset:8192
	v_add_u32_e32 v84, s26, v184
	ds_read_b128 v[228:231], v84
	s_waitcnt lgkmcnt(2)
	s_setprio 1
	v_mfma_f32_32x32x16_bf16 v[64:79], v[80:83], v[220:223], v[64:79]
	ds_read_b128 v[80:83], v216 offset:128
	ds_read_b128 v[84:87], v216 offset:160
	ds_read_b128 v[88:91], v216 offset:192
	ds_read_b128 v[92:95], v216 offset:224
	v_add_u32_e32 v161, s26, v185
	s_cmp_lg_u32 s13, s20
	s_waitcnt lgkmcnt(0)
	v_mfma_f32_32x32x16_bf16 v[80:95], v[224:227], v[220:223], v[80:95]
	ds_read_b128 v[220:223], v203
	ds_read_b128 v[224:227], v203 offset:8192
	s_waitcnt lgkmcnt(1)
	v_mfma_f32_32x32x16_bf16 v[64:79], v[220:223], v[228:231], v[64:79]
	ds_read_b128 v[220:223], v204
	s_waitcnt lgkmcnt(1)
	v_mfma_f32_32x32x16_bf16 v[80:95], v[224:227], v[228:231], v[80:95]
	ds_read_b128 v[224:227], v161
	ds_read_b128 v[228:231], v204 offset:8192
	v_add_u32_e32 v161, s26, v186
	ds_read_b128 v[232:235], v161
	v_add_u32_e32 v161, s26, v187
	s_waitcnt lgkmcnt(2)
	v_mfma_f32_32x32x16_bf16 v[64:79], v[220:223], v[224:227], v[64:79]
	s_waitcnt lgkmcnt(1)
	v_mfma_f32_32x32x16_bf16 v[80:95], v[228:231], v[224:227], v[80:95]
	ds_read_b128 v[220:223], v205
	ds_read_b128 v[224:227], v205 offset:8192
	s_waitcnt lgkmcnt(1)
	v_mfma_f32_32x32x16_bf16 v[64:79], v[220:223], v[232:235], v[64:79]
	ds_read_b128 v[220:223], v206
	s_waitcnt lgkmcnt(1)
	v_mfma_f32_32x32x16_bf16 v[80:95], v[224:227], v[232:235], v[80:95]
	ds_read_b128 v[224:227], v161
	ds_read_b128 v[228:231], v206 offset:8192
	v_add_u32_e32 v161, s26, v188
	ds_read_b128 v[232:235], v161
	v_add_u32_e32 v161, s26, v189
	s_waitcnt lgkmcnt(2)
	v_mfma_f32_32x32x16_bf16 v[64:79], v[220:223], v[224:227], v[64:79]
	s_waitcnt lgkmcnt(1)
	v_mfma_f32_32x32x16_bf16 v[80:95], v[228:231], v[224:227], v[80:95]
	ds_read_b128 v[220:223], v207
	ds_read_b128 v[224:227], v207 offset:8192
	s_waitcnt lgkmcnt(1)
	v_mfma_f32_32x32x16_bf16 v[64:79], v[220:223], v[232:235], v[64:79]
	ds_read_b128 v[220:223], v208
	s_waitcnt lgkmcnt(1)
	v_mfma_f32_32x32x16_bf16 v[80:95], v[224:227], v[232:235], v[80:95]
	ds_read_b128 v[224:227], v161
	ds_read_b128 v[228:231], v208 offset:8192
	v_add_u32_e32 v161, s26, v190
	ds_read_b128 v[232:235], v161
	s_waitcnt lgkmcnt(2)
	v_mfma_f32_32x32x16_bf16 v[64:79], v[220:223], v[224:227], v[64:79]
	s_waitcnt lgkmcnt(1)
	v_mfma_f32_32x32x16_bf16 v[80:95], v[228:231], v[224:227], v[80:95]
	ds_read_b128 v[220:223], v209
	ds_read_b128 v[224:227], v209 offset:8192
	s_waitcnt lgkmcnt(1)
	v_mfma_f32_32x32x16_bf16 v[64:79], v[220:223], v[232:235], v[64:79]
	s_waitcnt lgkmcnt(0)
	v_mfma_f32_32x32x16_bf16 v[80:95], v[224:227], v[232:235], v[80:95]
	s_setprio 0
	s_cbranch_scc1 .LBB0_699
	v_add_u32_e32 v161, s16, v218
	v_add_u32_e32 v220, 32, v161
	v_cmp_le_i32_e32 vcc, v220, v215
	v_add_u32_e32 v220, 33, v161
	s_nop 6
	v_cndmask_b32_e32 v80, v214, v80, vcc
	v_cmp_lt_i32_e32 vcc, v161, v215
	s_nop 1
	v_cndmask_b32_e32 v65, v214, v65, vcc
	v_cmp_le_i32_e32 vcc, v161, v215
	s_nop 1
	v_cndmask_b32_e32 v64, v214, v64, vcc
	v_cmp_le_i32_e32 vcc, v220, v215
	v_add_u32_e32 v220, 2, v161
	s_nop 0
	v_cndmask_b32_e32 v81, v214, v81, vcc
	v_cmp_le_i32_e32 vcc, v220, v215
	v_add_u32_e32 v220, 34, v161
	s_nop 0
	v_cndmask_b32_e32 v66, v214, v66, vcc
	v_cmp_le_i32_e32 vcc, v220, v215
	v_add_u32_e32 v220, 3, v161
	s_nop 0
	v_cndmask_b32_e32 v82, v214, v82, vcc
	v_cmp_le_i32_e32 vcc, v220, v215
	v_add_u32_e32 v220, 35, v161
	s_nop 0
	v_cndmask_b32_e32 v67, v214, v67, vcc
	v_cmp_le_i32_e32 vcc, v220, v215
	v_add_u32_e32 v220, 8, v161
	s_nop 0
	v_cndmask_b32_e32 v83, v214, v83, vcc
	v_cmp_le_i32_e32 vcc, v220, v215
	v_add_u32_e32 v220, 40, v161
	s_nop 0
	v_cndmask_b32_e32 v68, v214, v68, vcc
	v_cmp_le_i32_e32 vcc, v220, v215
	v_add_u32_e32 v220, 9, v161
	s_nop 0
	v_cndmask_b32_e32 v84, v214, v84, vcc
	v_cmp_le_i32_e32 vcc, v220, v215
	v_add_u32_e32 v220, 41, v161
	s_nop 0
	v_cndmask_b32_e32 v69, v214, v69, vcc
	v_cmp_le_i32_e32 vcc, v220, v215
	v_add_u32_e32 v220, 10, v161
	s_nop 0
	v_cndmask_b32_e32 v85, v214, v85, vcc
	v_cmp_le_i32_e32 vcc, v220, v215
	v_add_u32_e32 v220, 42, v161
	s_nop 0
	v_cndmask_b32_e32 v70, v214, v70, vcc
	v_cmp_le_i32_e32 vcc, v220, v215
	v_add_u32_e32 v220, 11, v161
	s_nop 0
	v_cndmask_b32_e32 v86, v214, v86, vcc
	v_cmp_le_i32_e32 vcc, v220, v215
	v_add_u32_e32 v220, 43, v161
	s_nop 0
	v_cndmask_b32_e32 v71, v214, v71, vcc
	v_cmp_le_i32_e32 vcc, v220, v215
	v_add_u32_e32 v220, 16, v161
	s_nop 0
	v_cndmask_b32_e32 v87, v214, v87, vcc
	v_cmp_le_i32_e32 vcc, v220, v215
	v_add_u32_e32 v220, 48, v161
	s_nop 0
	v_cndmask_b32_e32 v72, v214, v72, vcc
	v_cmp_le_i32_e32 vcc, v220, v215
	v_add_u32_e32 v220, 17, v161
	s_nop 0
	v_cndmask_b32_e32 v88, v214, v88, vcc
	v_cmp_le_i32_e32 vcc, v220, v215
	v_add_u32_e32 v220, 49, v161
	s_nop 0
	v_cndmask_b32_e32 v73, v214, v73, vcc
	v_cmp_le_i32_e32 vcc, v220, v215
	v_add_u32_e32 v220, 18, v161
	s_nop 0
	v_cndmask_b32_e32 v89, v214, v89, vcc
	v_cmp_le_i32_e32 vcc, v220, v215
	v_add_u32_e32 v220, 50, v161
	s_nop 0
	v_cndmask_b32_e32 v74, v214, v74, vcc
	v_cmp_le_i32_e32 vcc, v220, v215
	v_add_u32_e32 v220, 19, v161
	s_nop 0
	v_cndmask_b32_e32 v90, v214, v90, vcc
	v_cmp_le_i32_e32 vcc, v220, v215
	v_add_u32_e32 v220, 51, v161
	s_nop 0
	v_cndmask_b32_e32 v75, v214, v75, vcc
	v_cmp_le_i32_e32 vcc, v220, v215
	v_add_u32_e32 v220, 24, v161
	s_nop 0
	v_cndmask_b32_e32 v91, v214, v91, vcc
	v_cmp_le_i32_e32 vcc, v220, v215
	v_add_u32_e32 v220, 56, v161
	s_nop 0
	v_cndmask_b32_e32 v76, v214, v76, vcc
	v_cmp_le_i32_e32 vcc, v220, v215
	v_add_u32_e32 v220, 25, v161
	s_nop 0
	v_cndmask_b32_e32 v92, v214, v92, vcc
	v_cmp_le_i32_e32 vcc, v220, v215
	v_add_u32_e32 v220, 57, v161
	s_nop 0
	v_cndmask_b32_e32 v77, v214, v77, vcc
	v_cmp_le_i32_e32 vcc, v220, v215
	v_add_u32_e32 v220, 26, v161
	s_nop 0
	v_cndmask_b32_e32 v93, v214, v93, vcc
	v_cmp_le_i32_e32 vcc, v220, v215
	v_add_u32_e32 v220, 58, v161
	s_nop 0
	v_cndmask_b32_e32 v78, v214, v78, vcc
	v_cmp_le_i32_e32 vcc, v220, v215
	v_add_u32_e32 v220, 27, v161
	v_add_u32_e32 v161, 59, v161
	v_cndmask_b32_e32 v94, v214, v94, vcc
	v_cmp_le_i32_e32 vcc, v220, v215
	s_nop 1
	v_cndmask_b32_e32 v79, v214, v79, vcc
	v_cmp_le_i32_e32 vcc, v161, v215
	s_nop 1
	v_cndmask_b32_e32 v95, v214, v95, vcc

; template <int MODE, bool SAMPLE>
; __device__ __forceinline__ void attn_unit(const Params& p, char* lds, int b, int h, int qb) {
;     ...
;                 f32x16 s0, s1;
; #pragma unroll
;                 for (int r = 0; r < 16; ++r) { p0[r] = __builtin_amdgcn_exp2f(fminf(p0[r], 100.f)); p1[r] = __builtin_amdgcn_exp2f(fminf(p1[r], 100.f));
;                     s0[r] = __builtin_amdgcn_rcpf(1.f + p0[r]); s1[r] = __builtin_amdgcn_rcpf(1.f + p1[r]); }
;                 float run = carry, bs[8];
; #pragma unroll
;                 for (int i = 7; i >= 0; --i) { const f32x16& S = (i >= 4) ? s1 : s0; const int rb = 4 * (i & 3);
;                     const float gs = (S[rb] * S[rb + 1]) * (S[rb + 2] * S[rb + 3]);
;                     auto rr = __builtin_amdgcn_permlane32_swap(__float_as_uint(gs), __float_as_uint(gs), false, false);
;                     const float glo = __uint_as_float(rr[0]), ghi = __uint_as_float(rr[1]);
;                     const float exH = run; run *= ghi; const float exL = run; run *= glo;
;                     bs[i] = hi ? exH : exL; }
;                 carry = run;
.LBB0_706:
	s_nop 7
	v_max_f32_e32 v67, v67, v67
	v_min_f32_e32 v67, 0x42c80000, v67
	v_exp_f32_e32 v219, v67
	v_max_f32_e32 v67, v83, v83
	v_min_f32_e32 v67, 0x42c80000, v67
	v_exp_f32_e32 v83, v67
	v_max_f32_e32 v67, v68, v68
	v_max_f32_e32 v68, v69, v69
	v_max_f32_e32 v69, v70, v70
	v_max_f32_e32 v70, v71, v71
	v_max_f32_e32 v71, v72, v72
	v_max_f32_e32 v72, v73, v73
	v_max_f32_e32 v73, v74, v74
	v_max_f32_e32 v74, v75, v75
	v_max_f32_e32 v75, v76, v76
	v_min_f32_e32 v75, 0x42c80000, v75
	v_max_f32_e32 v76, v77, v77
	v_max_f32_e32 v77, v78, v78
	v_exp_f32_e32 v237, v75
	v_max_f32_e32 v75, v92, v92
	v_min_f32_e32 v77, 0x42c80000, v77
	v_min_f32_e32 v75, 0x42c80000, v75
	v_min_f32_e32 v76, 0x42c80000, v76
	v_exp_f32_e32 v241, v77
	v_max_f32_e32 v77, v94, v94
	v_exp_f32_e32 v92, v75
	v_exp_f32_e32 v239, v76
	v_max_f32_e32 v76, v93, v93
	v_min_f32_e32 v77, 0x42c80000, v77
	v_max_f32_e32 v78, v79, v79
	v_max_f32_e32 v79, v95, v95
	v_min_f32_e32 v76, 0x42c80000, v76
	v_exp_f32_e32 v94, v77
	v_min_f32_e32 v79, 0x42c80000, v79
	v_min_f32_e32 v71, 0x42c80000, v71
	v_exp_f32_e32 v93, v76
	v_exp_f32_e32 v95, v79
	v_exp_f32_e32 v229, v71
	v_max_f32_e32 v71, v88, v88
	v_min_f32_e32 v71, 0x42c80000, v71
	v_min_f32_e32 v72, 0x42c80000, v72
	v_min_f32_e32 v73, 0x42c80000, v73
	v_min_f32_e32 v74, 0x42c80000, v74
	v_add_f32_e32 v75, 1.0, v92
	v_exp_f32_e32 v88, v71
	v_exp_f32_e32 v231, v72
	v_max_f32_e32 v72, v89, v89
	v_exp_f32_e32 v233, v73
	v_max_f32_e32 v73, v90, v90
	v_exp_f32_e32 v235, v74
	v_max_f32_e32 v74, v91, v91
	v_rcp_f32_e32 v240, v75
	v_add_f32_e32 v75, 1.0, v239
	v_add_f32_e32 v77, 1.0, v94
	v_min_f32_e32 v72, 0x42c80000, v72
	v_min_f32_e32 v73, 0x42c80000, v73
	v_min_f32_e32 v74, 0x42c80000, v74
	v_rcp_f32_e32 v76, v75
	v_add_f32_e32 v75, 1.0, v93
	v_rcp_f32_e32 v244, v77
	v_add_f32_e32 v77, 1.0, v95
	v_min_f32_e32 v67, 0x42c80000, v67
	v_exp_f32_e32 v89, v72
	v_exp_f32_e32 v90, v73
	v_exp_f32_e32 v91, v74
	v_rcp_f32_e32 v242, v75
	v_rcp_f32_e32 v245, v77
	v_exp_f32_e32 v221, v67
	v_max_f32_e32 v67, v84, v84
	v_min_f32_e32 v67, 0x42c80000, v67
	v_min_f32_e32 v68, 0x42c80000, v68
	v_min_f32_e32 v69, 0x42c80000, v69
	v_min_f32_e32 v70, 0x42c80000, v70
	v_add_f32_e32 v71, 1.0, v88
	v_exp_f32_e32 v84, v67
	v_exp_f32_e32 v223, v68
	v_max_f32_e32 v68, v85, v85
	v_exp_f32_e32 v225, v69
	v_max_f32_e32 v69, v86, v86
	v_exp_f32_e32 v227, v70
	v_max_f32_e32 v70, v87, v87
	v_rcp_f32_e32 v232, v71
	v_add_f32_e32 v71, 1.0, v231
	v_min_f32_e32 v78, 0x42c80000, v78
	v_max_f32_e32 v66, v66, v66
	v_min_f32_e32 v68, 0x42c80000, v68
	v_min_f32_e32 v69, 0x42c80000, v69
	v_min_f32_e32 v70, 0x42c80000, v70
	v_rcp_f32_e32 v72, v71
	v_add_f32_e32 v71, 1.0, v89
	v_add_f32_e32 v73, 1.0, v90
	v_add_f32_e32 v74, 1.0, v91
	v_exp_f32_e32 v243, v78
	v_mul_f32_e32 v78, v240, v242
	v_mul_f32_e32 v79, v244, v245
	v_max_f32_e32 v64, v64, v64
	v_min_f32_e32 v66, 0x42c80000, v66
	v_exp_f32_e32 v85, v68
	v_exp_f32_e32 v86, v69
	v_exp_f32_e32 v87, v70
	v_rcp_f32_e32 v234, v71
	v_rcp_f32_e32 v236, v73
	v_rcp_f32_e32 v238, v74
	v_mul_f32_e32 v78, v78, v79
	v_min_f32_e32 v64, 0x42c80000, v64
	v_max_f32_e32 v65, v65, v65
	v_exp_f32_e32 v217, v66
	v_max_f32_e32 v66, v82, v82
	v_mov_b32_e32 v79, v78
	v_exp_f32_e32 v147, v64
	v_max_f32_e32 v64, v80, v80
	v_min_f32_e32 v65, 0x42c80000, v65
	v_min_f32_e32 v66, 0x42c80000, v66
	v_add_f32_e32 v67, 1.0, v84
	v_permlane32_swap_b32_e32 v78, v79
	v_min_f32_e32 v64, 0x42c80000, v64
	v_exp_f32_e32 v170, v65
	v_max_f32_e32 v65, v81, v81
	v_exp_f32_e32 v82, v66
	v_rcp_f32_e32 v224, v67
	v_add_f32_e32 v67, 1.0, v223
	v_mul_f32_e32 v79, v145, v79
	v_exp_f32_e32 v161, v64
	v_min_f32_e32 v65, 0x42c80000, v65
	v_rcp_f32_e32 v68, v67
	v_add_f32_e32 v67, 1.0, v85
	v_add_f32_e32 v69, 1.0, v86
	v_add_f32_e32 v70, 1.0, v87
	v_mul_f32_e32 v78, v79, v78
	v_cndmask_b32_e64 v145, v145, v79, s[14:15]
	v_mul_f32_e32 v79, v232, v234
	v_mul_f32_e32 v246, v236, v238
	v_exp_f32_e32 v215, v65
	v_rcp_f32_e32 v226, v67
	v_rcp_f32_e32 v228, v69
	v_rcp_f32_e32 v230, v70
	v_mul_f32_e32 v79, v79, v246
	v_mov_b32_e32 v246, v79
	v_add_f32_e32 v66, 1.0, v82
	s_nop 0
	v_permlane32_swap_b32_e32 v79, v246
	v_add_f32_e32 v80, 1.0, v161
	v_add_f32_e32 v65, 1.0, v170
	v_rcp_f32_e32 v220, v66
	v_add_f32_e32 v66, 1.0, v219
	v_mul_f32_e32 v246, v78, v246
	v_rcp_f32_e32 v216, v80
	v_rcp_f32_e32 v80, v65
	v_add_f32_e32 v65, 1.0, v215
	v_rcp_f32_e32 v81, v66
	v_add_f32_e32 v66, 1.0, v83
	v_mul_f32_e32 v79, v246, v79
	v_cndmask_b32_e64 v246, v78, v246, s[14:15]
	v_mul_f32_e32 v78, v224, v226
	v_mul_f32_e32 v247, v228, v230
	v_rcp_f32_e32 v218, v65
	v_rcp_f32_e32 v222, v66
	v_mul_f32_e32 v78, v78, v247
	v_mov_b32_e32 v247, v78
	s_nop 1
	v_permlane32_swap_b32_e32 v78, v247
	v_mul_f32_e32 v247, v79, v247
	v_add_f32_e32 v74, 1.0, v237
	v_add_f32_e32 v75, 1.0, v241
	v_add_f32_e32 v77, 1.0, v243
	v_mul_f32_e32 v78, v247, v78
	v_cndmask_b32_e64 v247, v79, v247, s[14:15]
	v_mul_f32_e32 v79, v216, v218
	v_mul_f32_e32 v248, v220, v222
	v_rcp_f32_e32 v74, v74
	v_rcp_f32_e32 v75, v75
	v_rcp_f32_e32 v77, v77
	v_mul_f32_e32 v79, v79, v248
	v_mov_b32_e32 v248, v79
	s_nop 1
	v_permlane32_swap_b32_e32 v79, v248
	v_mul_f32_e32 v248, v78, v248
	v_add_f32_e32 v70, 1.0, v229
	v_add_f32_e32 v71, 1.0, v233
	v_add_f32_e32 v73, 1.0, v235
	v_mul_f32_e32 v249, v248, v79
	v_cndmask_b32_e64 v248, v78, v248, s[14:15]
	v_pk_mul_f32 v[78:79], v[74:75], v[76:77]
	v_rcp_f32_e32 v70, v70
	v_rcp_f32_e32 v71, v71
	v_rcp_f32_e32 v73, v73
	v_pk_mul_f32 v[78:79], v[78:79], v[78:79] op_sel:[0,1] op_sel_hi:[1,0]
	v_add_f32_e32 v66, 1.0, v221
	v_mov_b32_e32 v79, v78
	s_nop 1
	v_permlane32_swap_b32_e32 v78, v79
; #define SBAR() __builtin_amdgcn_sched_barrier(0)
; template <int OFF> __device__ __forceinline__ s16x4 tr_read(int vb) { s16x4 r; asm volatile("ds_read_b64_tr_b16 %0, %1 offset:%2" : "=&v"(r) : "v"(vb), "i"(OFF) : "memory"); return r; }
; template <int D0> __device__ __forceinline__ void pv_one(f32x16& od, int vb, bf16x8 pa0, bf16x8 pa1, bf16x8 pa2, bf16x8 pa3) {
;     const s16x4 l0 = tr_read<v_rd_off(D0, 0, 0)>(vb), h0 = tr_read<v_rd_off(D0, 0, 1)>(vb), l1 = tr_read<v_rd_off(D0, 1, 0)>(vb), h1 = tr_read<v_rd_off(D0, 1, 1)>(vb);
;     const s16x4 l2 = tr_read<v_rd_off(D0, 2, 0)>(vb), h2 = tr_read<v_rd_off(D0, 2, 1)>(vb), l3 = tr_read<v_rd_off(D0, 3, 0)>(vb), h3 = tr_read<v_rd_off(D0, 3, 1)>(vb);
;     asm volatile("s_waitcnt lgkmcnt(0)" ::: "memory"); SBAR();
;     ...
;     od = __builtin_amdgcn_mfma_f32_32x32x16_bf16(pa0, PKV(l0, h0), od, 0, 0, 0);
;     od = __builtin_amdgcn_mfma_f32_32x32x16_bf16(pa1, PKV(l1, h1), od, 0, 0, 0);
;     od = __builtin_amdgcn_mfma_f32_32x32x16_bf16(pa2, PKV(l2, h2), od, 0, 0, 0);
;     od = __builtin_amdgcn_mfma_f32_32x32x16_bf16(pa3, PKV(l3, h3), od, 0, 0, 0);
;     ...
; }
; __device__ __forceinline__ void pv_d0(f32x16* o, int vb, bf16x8 pa0, bf16x8 pa1, bf16x8 pa2, bf16x8 pa3) {
;     pv_one<0>(o[0], vb, pa0, pa1, pa2, pa3); pv_one<1>(o[1], vb, pa0, pa1, pa2, pa3); pv_one<2>(o[2], vb, pa0, pa1, pa2, pa3); pv_one<3>(o[3], vb, pa0, pa1, pa2, pa3);
; }
; template <int MODE, bool SAMPLE>
; __device__ __forceinline__ void attn_unit(const Params& p, char* lds, int b, int h, int qb) {
;     ...
;                 carry = run;
; #pragma unroll
;                 for (int i = 0; i < 8; ++i) { f32x16& S = (i >= 4) ? s1 : s0; f32x16& Z = (i >= 4) ? p1 : p0; const int rb = 4 * (i & 3);
;                     const float i3 = bs[i] * S[rb + 3], i2 = i3 * S[rb + 2], i1 = i2 * S[rb + 1], i0 = i1 * S[rb];
;                     Z[rb + 3] *= i3; Z[rb + 2] *= i2; Z[rb + 1] *= i1; Z[rb] *= i0; }
;             }
;             PK4(p0, 0, pa0); PK4(p0, 8, pa1); PK4(p1, 0, pa2); PK4(p1, 8, pa3);
;             pv_d0(o, vb, pa0, pa1, pa2, pa3);
	v_mul_f32_e32 v79, v249, v79
	v_add_f32_e32 v67, 1.0, v225
	v_add_f32_e32 v69, 1.0, v227
	v_mul_f32_e32 v250, v79, v78
	v_cndmask_b32_e64 v249, v249, v79, s[14:15]
	v_pk_mul_f32 v[78:79], v[70:71], v[72:73]
	v_rcp_f32_e32 v66, v66
	v_rcp_f32_e32 v67, v67
	v_rcp_f32_e32 v69, v69
	v_pk_mul_f32 v[78:79], v[78:79], v[78:79] op_sel:[0,1] op_sel_hi:[1,0]
	v_add_f32_e32 v64, 1.0, v147
	v_mov_b32_e32 v79, v78
	s_nop 1
	v_permlane32_swap_b32_e32 v78, v79
	v_mul_f32_e32 v79, v250, v79
	v_add_f32_e32 v65, 1.0, v217
	v_mul_f32_e32 v251, v79, v78
	v_cndmask_b32_e64 v250, v250, v79, s[14:15]
	v_pk_mul_f32 v[78:79], v[66:67], v[68:69]
	v_rcp_f32_e32 v64, v64
	v_rcp_f32_e32 v65, v65
	v_pk_mul_f32 v[78:79], v[78:79], v[78:79] op_sel:[0,1] op_sel_hi:[1,0]
	v_mul_f32_e32 v73, v73, v250
	v_mov_b32_e32 v79, v78
	s_nop 1
	v_permlane32_swap_b32_e32 v78, v79
	v_mul_f32_e32 v79, v251, v79
	v_mul_f32_e32 v252, v79, v78
	v_cndmask_b32_e64 v251, v251, v79, s[14:15]
	v_pk_mul_f32 v[78:79], v[64:65], v[80:81]
	v_mul_f32_e32 v69, v69, v251
	v_pk_mul_f32 v[78:79], v[78:79], v[78:79] op_sel:[0,1] op_sel_hi:[1,0]
	v_mul_f32_e32 v77, v77, v249
	v_mov_b32_e32 v79, v78
	s_nop 1
	v_permlane32_swap_b32_e32 v78, v79
	v_mul_f32_e32 v79, v252, v79
	v_cndmask_b32_e64 v252, v252, v79, s[14:15]
	v_mul_f32_e32 v81, v81, v252
	v_mul_f32_e32 v65, v65, v81
	v_mul_f32_e32 v80, v80, v65
	v_mul_f32_e32 v64, v64, v80
	v_mul_f32_e32 v64, v147, v64
	v_mul_f32_e32 v147, v222, v248
	v_mul_f32_e32 v80, v170, v80
	v_mul_f32_e32 v170, v220, v147
	v_mul_f32_e32 v65, v217, v65
	v_mul_f32_e32 v217, v218, v170
	v_mul_f32_e32 v82, v82, v170
	v_mul_f32_e32 v170, v230, v247
	v_mul_f32_e32 v67, v67, v69
	v_mul_f32_e32 v71, v71, v73
	v_mul_f32_e32 v75, v75, v77
	v_mul_f32_e32 v216, v216, v217
	v_mul_f32_e32 v83, v83, v147
	v_mul_f32_e32 v147, v215, v217
	v_mul_f32_e32 v215, v228, v170
	v_mul_f32_e32 v87, v87, v170
	v_mul_f32_e32 v170, v238, v246
	v_mul_f32_e32 v145, v245, v145
	v_mul_f32_e32 v68, v68, v67
	v_mul_f32_e32 v72, v72, v71
	v_mul_f32_e32 v76, v76, v75
	v_mul_f32_e32 v161, v161, v216
	v_mul_f32_e32 v216, v226, v215
	v_mul_f32_e32 v86, v86, v215
	v_mul_f32_e32 v215, v236, v170
	v_mul_f32_e32 v91, v91, v170
	v_mul_f32_e32 v170, v244, v145
	v_mul_f32_e32 v66, v66, v68
	v_mul_f32_e32 v70, v70, v72
	v_mul_f32_e32 v74, v74, v76
	v_mul_f32_e32 v217, v224, v216
	v_mul_f32_e32 v85, v85, v216
	v_mul_f32_e32 v216, v234, v215
	v_mul_f32_e32 v90, v90, v215
	v_mul_f32_e32 v215, v242, v170
	v_mul_f32_e32 v81, v219, v81
	v_mul_f32_e32 v69, v227, v69
	v_mul_f32_e32 v67, v225, v67
	v_mul_f32_e32 v68, v223, v68
	v_mul_f32_e32 v66, v221, v66
	v_mul_f32_e32 v73, v235, v73
	v_mul_f32_e32 v71, v233, v71
	v_mul_f32_e32 v72, v231, v72
	v_mul_f32_e32 v70, v229, v70
	v_mul_f32_e32 v77, v243, v77
	v_mul_f32_e32 v75, v241, v75
	v_mul_f32_e32 v76, v239, v76
	v_mul_f32_e32 v74, v237, v74
	v_mul_f32_e32 v84, v84, v217
	v_mul_f32_e32 v217, v232, v216
	v_mul_f32_e32 v89, v89, v216
	v_mul_f32_e32 v216, v240, v215
	v_mul_f32_e32 v88, v88, v217
	v_mul_f32_e32 v95, v95, v145
	v_mul_f32_e32 v94, v94, v170
	v_mul_f32_e32 v93, v93, v215
	v_mul_f32_e32 v92, v92, v216
	v_mul_f32_e32 v145, v79, v78
	v_cvt_pk_bf16_f32 v64, v64, v80
	v_cvt_pk_bf16_f32 v65, v65, v81
	v_cvt_pk_bf16_f32 v66, v66, v68
	v_cvt_pk_bf16_f32 v67, v67, v69
	v_cvt_pk_bf16_f32 v68, v70, v72
	v_cvt_pk_bf16_f32 v69, v71, v73
	v_cvt_pk_bf16_f32 v70, v74, v76
	v_cvt_pk_bf16_f32 v71, v75, v77
	v_cvt_pk_bf16_f32 v72, v161, v147
	v_cvt_pk_bf16_f32 v73, v82, v83
	v_cvt_pk_bf16_f32 v74, v84, v85
	v_cvt_pk_bf16_f32 v75, v86, v87
	v_cvt_pk_bf16_f32 v76, v88, v89
	v_cvt_pk_bf16_f32 v77, v90, v91
	v_cvt_pk_bf16_f32 v78, v92, v93
	v_cvt_pk_bf16_f32 v79, v94, v95
	ds_read_b64_tr_b16 v[80:81], v180 offset:0
	ds_read_b64_tr_b16 v[82:83], v180 offset:0x800
	ds_read_b64_tr_b16 v[84:85], v180 offset:0x1000
	ds_read_b64_tr_b16 v[86:87], v180 offset:0x1800
	ds_read_b64_tr_b16 v[88:89], v180 offset:0x2000
	ds_read_b64_tr_b16 v[90:91], v180 offset:0x2800
	ds_read_b64_tr_b16 v[92:93], v180 offset:0x3000
	ds_read_b64_tr_b16 v[94:95], v180 offset:0x3800
	s_waitcnt lgkmcnt(0)
	s_nop 0
	v_permlane32_swap_b32_e32 v64, v66
	v_permlane32_swap_b32_e32 v65, v67
	v_permlane32_swap_b32_e32 v68, v70
	v_permlane32_swap_b32_e32 v69, v71
	v_permlane32_swap_b32_e32 v72, v74
	v_permlane32_swap_b32_e32 v73, v75
	v_permlane32_swap_b32_e32 v76, v78
	v_permlane32_swap_b32_e32 v77, v79
	s_setprio 1
	v_mfma_f32_32x32x16_bf16 v[48:63], v[64:67], v[80:83], v[48:63]
	ds_read_b64_tr_b16 v[80:81], v180 offset:0x200
	ds_read_b64_tr_b16 v[82:83], v180 offset:0xa00
	v_mfma_f32_32x32x16_bf16 v[48:63], v[68:71], v[84:87], v[48:63]
	ds_read_b64_tr_b16 v[84:85], v180 offset:0x1200
	ds_read_b64_tr_b16 v[86:87], v180 offset:0x1a00
	v_mfma_f32_32x32x16_bf16 v[48:63], v[72:75], v[88:91], v[48:63]
	ds_read_b64_tr_b16 v[88:89], v180 offset:0x2200
	ds_read_b64_tr_b16 v[90:91], v180 offset:0x2a00
	v_mfma_f32_32x32x16_bf16 v[48:63], v[76:79], v[92:95], v[48:63]
	ds_read_b64_tr_b16 v[92:93], v180 offset:0x3200
	ds_read_b64_tr_b16 v[94:95], v180 offset:0x3a00
	s_waitcnt lgkmcnt(0)
	v_mfma_f32_32x32x16_bf16 v[32:47], v[64:67], v[80:83], v[32:47]
	ds_read_b64_tr_b16 v[80:81], v180 offset:0x400
	ds_read_b64_tr_b16 v[82:83], v180 offset:0xc00
	v_mfma_f32_32x32x16_bf16 v[32:47], v[68:71], v[84:87], v[32:47]
	ds_read_b64_tr_b16 v[84:85], v180 offset:0x1400
	ds_read_b64_tr_b16 v[86:87], v180 offset:0x1c00
	v_mfma_f32_32x32x16_bf16 v[32:47], v[72:75], v[88:91], v[32:47]
	ds_read_b64_tr_b16 v[88:89], v180 offset:0x2400
	ds_read_b64_tr_b16 v[90:91], v180 offset:0x2c00
	v_mfma_f32_32x32x16_bf16 v[32:47], v[76:79], v[92:95], v[32:47]
	ds_read_b64_tr_b16 v[92:93], v180 offset:0x3400
	ds_read_b64_tr_b16 v[94:95], v180 offset:0x3c00
	s_waitcnt lgkmcnt(0)
	v_mfma_f32_32x32x16_bf16 v[16:31], v[64:67], v[80:83], v[16:31]
	ds_read_b64_tr_b16 v[80:81], v180 offset:0x600
	ds_read_b64_tr_b16 v[82:83], v180 offset:0xe00
	v_mfma_f32_32x32x16_bf16 v[16:31], v[68:71], v[84:87], v[16:31]
	ds_read_b64_tr_b16 v[84:85], v180 offset:0x1600
	ds_read_b64_tr_b16 v[86:87], v180 offset:0x1e00
	v_mfma_f32_32x32x16_bf16 v[16:31], v[72:75], v[88:91], v[16:31]
	ds_read_b64_tr_b16 v[88:89], v180 offset:0x2600
	ds_read_b64_tr_b16 v[90:91], v180 offset:0x2e00
	v_mfma_f32_32x32x16_bf16 v[16:31], v[76:79], v[92:95], v[16:31]
	ds_read_b64_tr_b16 v[92:93], v180 offset:0x3600
	ds_read_b64_tr_b16 v[94:95], v180 offset:0x3e00
	s_waitcnt lgkmcnt(0)
	v_mfma_f32_32x32x16_bf16 v[0:15], v[64:67], v[80:83], v[0:15]
	v_mfma_f32_32x32x16_bf16 v[0:15], v[68:71], v[84:87], v[0:15]
	v_mfma_f32_32x32x16_bf16 v[0:15], v[72:75], v[88:91], v[0:15]
	v_mfma_f32_32x32x16_bf16 v[0:15], v[76:79], v[92:95], v[0:15]
	s_setprio 0

; __device__ __forceinline__ int crow(int r, int hi) { return (r & 3) + 8 * (r >> 2) + 4 * hi; }
; __device__ __forceinline__ void qkt(f32x16& p0, f32x16& p1, const char* Ks, const char* Qs, int r32, int hi) {
; #pragma unroll
;     for (int d0 = 0; d0 < 8; ++d0) { const int cb = (d0 * 16 + hi * 8) * 2;
;         const bf16x8 qv = *reinterpret_cast<const bf16x8*>(Qs + KSWZ(r32, cb));
;         const bf16x8 b0 = *reinterpret_cast<const bf16x8*>(Ks + KSWZ(r32, cb));
;         const bf16x8 b1 = *reinterpret_cast<const bf16x8*>(Ks + KSWZ(32 + r32, cb));
;         p0 = __builtin_amdgcn_mfma_f32_32x32x16_bf16(b0, qv, p0, 0, 0, 0);
;         p1 = __builtin_amdgcn_mfma_f32_32x32x16_bf16(b1, qv, p1, 0, 0, 0); }
; }
; template <int MODE, bool SAMPLE>
; __device__ __forceinline__ void attn_unit(const Params& p, char* lds, int b, int h, int qb) {
;     ...
;                 p0 = f32x16{}; p1 = f32x16{};
;                 qkt(p0, p1, Kt, Qs, r32, hi);
;                 if (j == jd) {
; #pragma unroll
;                     for (int r = 0; r < 16; ++r) { const int kp = j * 64 + crow(r, hi); if (kp >= qpos) p0[r] = -1e30f; if (kp + 32 >= qpos) p1[r] = -1e30f; } }
.Lstg_2:
	ds_read_b128 v[64:67], v202 offset:16384
	ds_read_b128 v[84:87], v202 offset:24576
	v_add_u32_e32 v68, s12, v182
	ds_read_b128 v[80:83], v68
	ds_read_b128 v[216:219], v203 offset:16384
	v_add_u32_e32 v147, s12, v184
	ds_read_b128 v[220:223], v147
	v_add_u32_e32 v147, s12, v185
	s_cmp_lg_u32 s6, s33
	s_waitcnt lgkmcnt(2)
	s_setprio 1
	v_mfma_f32_32x32x16_bf16 v[64:79], v[64:67], v[80:83], 0
	s_waitcnt lgkmcnt(0)
	v_mfma_f32_32x32x16_bf16 v[64:79], v[216:219], v[220:223], v[64:79]
	ds_read_b128 v[216:219], v203 offset:24576
	v_mfma_f32_32x32x16_bf16 v[80:95], v[84:87], v[80:83], 0
	s_waitcnt lgkmcnt(0)
	v_mfma_f32_32x32x16_bf16 v[80:95], v[216:219], v[220:223], v[80:95]
	ds_read_b128 v[216:219], v204 offset:16384
	ds_read_b128 v[220:223], v147
	v_add_u32_e32 v147, s12, v186
	s_waitcnt lgkmcnt(0)
	v_mfma_f32_32x32x16_bf16 v[64:79], v[216:219], v[220:223], v[64:79]
	ds_read_b128 v[216:219], v204 offset:24576
	s_waitcnt lgkmcnt(0)
	v_mfma_f32_32x32x16_bf16 v[80:95], v[216:219], v[220:223], v[80:95]
	ds_read_b128 v[216:219], v205 offset:16384
	ds_read_b128 v[220:223], v147
	v_add_u32_e32 v147, s12, v187
	s_waitcnt lgkmcnt(0)
	v_mfma_f32_32x32x16_bf16 v[64:79], v[216:219], v[220:223], v[64:79]
	ds_read_b128 v[216:219], v205 offset:24576
	s_waitcnt lgkmcnt(0)
	v_mfma_f32_32x32x16_bf16 v[80:95], v[216:219], v[220:223], v[80:95]
	ds_read_b128 v[216:219], v206 offset:16384
	ds_read_b128 v[220:223], v147
	v_add_u32_e32 v147, s12, v188
	s_waitcnt lgkmcnt(0)
	v_mfma_f32_32x32x16_bf16 v[64:79], v[216:219], v[220:223], v[64:79]
	ds_read_b128 v[216:219], v206 offset:24576
	s_waitcnt lgkmcnt(0)
	v_mfma_f32_32x32x16_bf16 v[80:95], v[216:219], v[220:223], v[80:95]
	ds_read_b128 v[216:219], v207 offset:16384
	ds_read_b128 v[220:223], v147
	v_add_u32_e32 v147, s12, v189
	s_waitcnt lgkmcnt(0)
	v_mfma_f32_32x32x16_bf16 v[64:79], v[216:219], v[220:223], v[64:79]
	ds_read_b128 v[216:219], v207 offset:24576
	s_waitcnt lgkmcnt(0)
	v_mfma_f32_32x32x16_bf16 v[80:95], v[216:219], v[220:223], v[80:95]
	ds_read_b128 v[216:219], v208 offset:16384
	ds_read_b128 v[220:223], v147
	v_add_u32_e32 v147, s12, v190
	s_waitcnt lgkmcnt(0)
	v_mfma_f32_32x32x16_bf16 v[64:79], v[216:219], v[220:223], v[64:79]
	ds_read_b128 v[216:219], v208 offset:24576
	s_waitcnt lgkmcnt(0)
	v_mfma_f32_32x32x16_bf16 v[80:95], v[216:219], v[220:223], v[80:95]
	ds_read_b128 v[216:219], v209 offset:16384
	ds_read_b128 v[220:223], v147
	s_waitcnt lgkmcnt(0)
	v_mfma_f32_32x32x16_bf16 v[64:79], v[216:219], v[220:223], v[64:79]
	ds_read_b128 v[216:219], v209 offset:24576
	s_waitcnt lgkmcnt(0)
	v_mfma_f32_32x32x16_bf16 v[80:95], v[216:219], v[220:223], v[80:95]
	s_setprio 0
	s_cbranch_scc1 .LBB0_714
	s_or_b64 s[80:81], s[76:77], s[72:73]
	s_nop 6
	v_cndmask_b32_e64 v78, v214, v78, s[80:81]
	s_or_b64 s[80:81], s[80:81], s[68:69]
	v_cndmask_b32_e64 v77, v214, v77, s[80:81]
	s_or_b64 s[80:81], s[80:81], s[64:65]
	v_cndmask_b32_e64 v76, v214, v76, s[80:81]
	s_or_b64 s[80:81], s[80:81], s[60:61]
	v_cndmask_b32_e64 v75, v214, v75, s[80:81]
	s_or_b64 s[80:81], s[80:81], s[56:57]
	v_cndmask_b32_e64 v74, v214, v74, s[80:81]
	s_or_b64 s[80:81], s[80:81], s[52:53]
	v_cndmask_b32_e64 v73, v214, v73, s[80:81]
	s_or_b64 s[80:81], s[80:81], s[48:49]
	v_cndmask_b32_e64 v72, v214, v72, s[80:81]
	s_or_b64 s[80:81], s[80:81], s[44:45]
	v_cndmask_b32_e64 v71, v214, v71, s[80:81]
	s_or_b64 s[80:81], s[80:81], s[40:41]
	v_cndmask_b32_e64 v70, v214, v70, s[80:81]
	s_or_b64 s[80:81], s[80:81], s[36:37]
	v_cndmask_b32_e64 v69, v214, v69, s[80:81]
	s_or_b64 s[80:81], s[80:81], s[30:31]
	v_cndmask_b32_e64 v68, v214, v68, s[80:81]
	s_or_b64 s[80:81], s[80:81], s[26:27]
	v_cndmask_b32_e64 v67, v214, v67, s[80:81]
	s_or_b64 s[80:81], s[80:81], s[22:23]
	v_cndmask_b32_e64 v66, v214, v66, s[80:81]
	s_or_b64 s[80:81], s[80:81], s[18:19]
	v_cndmask_b32_e64 v65, v214, v65, s[80:81]
	s_or_b64 s[80:81], s[80:81], vcc
	v_cndmask_b32_e64 v64, v214, v64, s[80:81]
	s_or_b64 s[80:81], s[78:79], s[74:75]
	v_cndmask_b32_e64 v94, v214, v94, s[80:81]
	s_or_b64 s[80:81], s[80:81], s[70:71]
	v_cndmask_b32_e64 v93, v214, v93, s[80:81]
	s_or_b64 s[80:81], s[80:81], s[66:67]
	v_cndmask_b32_e64 v92, v214, v92, s[80:81]
	s_or_b64 s[80:81], s[80:81], s[62:63]
	v_cndmask_b32_e64 v91, v214, v91, s[80:81]
	s_or_b64 s[80:81], s[80:81], s[58:59]
	v_cndmask_b32_e64 v90, v214, v90, s[80:81]
	s_or_b64 s[80:81], s[80:81], s[54:55]
	v_cndmask_b32_e64 v89, v214, v89, s[80:81]
	s_or_b64 s[80:81], s[80:81], s[50:51]
	v_cndmask_b32_e64 v88, v214, v88, s[80:81]
	s_or_b64 s[80:81], s[80:81], s[46:47]
	v_cndmask_b32_e64 v87, v214, v87, s[80:81]
	s_or_b64 s[80:81], s[80:81], s[42:43]
	v_cndmask_b32_e64 v86, v214, v86, s[80:81]
	s_or_b64 s[80:81], s[80:81], s[38:39]
	v_cndmask_b32_e64 v85, v214, v85, s[80:81]
	s_or_b64 s[80:81], s[80:81], s[34:35]
	v_cndmask_b32_e64 v84, v214, v84, s[80:81]
	s_or_b64 s[80:81], s[80:81], s[28:29]
	v_cndmask_b32_e64 v83, v214, v83, s[80:81]
	s_or_b64 s[80:81], s[80:81], s[24:25]
	v_cndmask_b32_e64 v82, v214, v82, s[80:81]
	s_or_b64 s[80:81], s[80:81], s[20:21]
	v_cndmask_b32_e64 v81, v214, v81, s[80:81]
	s_or_b64 s[80:81], s[80:81], s[0:1]
	v_cndmask_b32_e64 v79, v214, v79, s[76:77]
	v_cndmask_b32_e64 v95, v214, v95, s[78:79]
	v_cndmask_b32_e64 v80, v214, v80, s[80:81]
; template <int MODE, bool SAMPLE>
; __device__ __forceinline__ void attn_unit(const Params& p, char* lds, int b, int h, int qb) {
;     ...
;                 f32x16 s0, s1;
; #pragma unroll
;                 for (int r = 0; r < 16; ++r) { p0[r] = __builtin_amdgcn_exp2f(fminf(p0[r], 100.f)); p1[r] = __builtin_amdgcn_exp2f(fminf(p1[r], 100.f));
;                     s0[r] = __builtin_amdgcn_rcpf(1.f + p0[r]); s1[r] = __builtin_amdgcn_rcpf(1.f + p1[r]); }
;                 float run = carry, bs[8];
; #pragma unroll
;                 for (int i = 7; i >= 0; --i) { const f32x16& S = (i >= 4) ? s1 : s0; const int rb = 4 * (i & 3);
;                     const float gs = (S[rb] * S[rb + 1]) * (S[rb + 2] * S[rb + 3]);
;                     auto rr = __builtin_amdgcn_permlane32_swap(__float_as_uint(gs), __float_as_uint(gs), false, false);
;                     const float glo = __uint_as_float(rr[0]), ghi = __uint_as_float(rr[1]);
;                     const float exH = run; run *= ghi; const float exL = run; run *= glo;
;                     bs[i] = hi ? exH : exL; }
;                 carry = run;
.LBB0_714:
	s_nop 7
	v_max_f32_e32 v67, v67, v67
	v_min_f32_e32 v67, 0x42c80000, v67
	v_exp_f32_e32 v220, v67
	v_max_f32_e32 v67, v83, v83
	v_min_f32_e32 v67, 0x42c80000, v67
	v_exp_f32_e32 v83, v67
	v_max_f32_e32 v67, v68, v68
	v_max_f32_e32 v68, v69, v69
	v_max_f32_e32 v69, v70, v70
	v_max_f32_e32 v70, v71, v71
	v_max_f32_e32 v71, v72, v72
	v_max_f32_e32 v72, v73, v73
	v_max_f32_e32 v73, v74, v74
	v_max_f32_e32 v74, v75, v75
	v_max_f32_e32 v75, v76, v76
	v_min_f32_e32 v75, 0x42c80000, v75
	v_max_f32_e32 v76, v77, v77
	v_max_f32_e32 v77, v78, v78
	v_exp_f32_e32 v238, v75
	v_max_f32_e32 v75, v92, v92
	v_min_f32_e32 v77, 0x42c80000, v77
	v_min_f32_e32 v75, 0x42c80000, v75
	v_min_f32_e32 v76, 0x42c80000, v76
	v_exp_f32_e32 v242, v77
	v_max_f32_e32 v77, v94, v94
	v_exp_f32_e32 v92, v75
	v_exp_f32_e32 v240, v76
	v_max_f32_e32 v76, v93, v93
	v_min_f32_e32 v77, 0x42c80000, v77
	v_max_f32_e32 v78, v79, v79
	v_max_f32_e32 v79, v95, v95
	v_min_f32_e32 v76, 0x42c80000, v76
	v_exp_f32_e32 v94, v77
	v_min_f32_e32 v79, 0x42c80000, v79
	v_min_f32_e32 v71, 0x42c80000, v71
	v_exp_f32_e32 v93, v76
	v_exp_f32_e32 v95, v79
	v_exp_f32_e32 v230, v71
	v_max_f32_e32 v71, v88, v88
	v_min_f32_e32 v71, 0x42c80000, v71
	v_min_f32_e32 v72, 0x42c80000, v72
	v_min_f32_e32 v73, 0x42c80000, v73
	v_min_f32_e32 v74, 0x42c80000, v74
	v_add_f32_e32 v75, 1.0, v92
	v_exp_f32_e32 v88, v71
	v_exp_f32_e32 v232, v72
	v_max_f32_e32 v72, v89, v89
	v_exp_f32_e32 v234, v73
	v_max_f32_e32 v73, v90, v90
	v_exp_f32_e32 v236, v74
	v_max_f32_e32 v74, v91, v91
	v_rcp_f32_e32 v241, v75
	v_add_f32_e32 v75, 1.0, v240
	v_add_f32_e32 v77, 1.0, v94
	v_min_f32_e32 v72, 0x42c80000, v72
	v_min_f32_e32 v73, 0x42c80000, v73
	v_min_f32_e32 v74, 0x42c80000, v74
	v_rcp_f32_e32 v76, v75
	v_add_f32_e32 v75, 1.0, v93
	v_rcp_f32_e32 v245, v77
	v_add_f32_e32 v77, 1.0, v95
	v_min_f32_e32 v67, 0x42c80000, v67
	v_exp_f32_e32 v89, v72
	v_exp_f32_e32 v90, v73
	v_exp_f32_e32 v91, v74
	v_rcp_f32_e32 v243, v75
	v_rcp_f32_e32 v246, v77
	v_exp_f32_e32 v222, v67
	v_max_f32_e32 v67, v84, v84
	v_min_f32_e32 v67, 0x42c80000, v67
	v_min_f32_e32 v68, 0x42c80000, v68
	v_min_f32_e32 v69, 0x42c80000, v69
	v_min_f32_e32 v70, 0x42c80000, v70
	v_add_f32_e32 v71, 1.0, v88
	v_exp_f32_e32 v84, v67
	v_exp_f32_e32 v224, v68
	v_max_f32_e32 v68, v85, v85
	v_exp_f32_e32 v226, v69
	v_max_f32_e32 v69, v86, v86
	v_exp_f32_e32 v228, v70
	v_max_f32_e32 v70, v87, v87
	v_rcp_f32_e32 v233, v71
	v_add_f32_e32 v71, 1.0, v232
	v_min_f32_e32 v78, 0x42c80000, v78
	v_max_f32_e32 v66, v66, v66
	v_min_f32_e32 v68, 0x42c80000, v68
	v_min_f32_e32 v69, 0x42c80000, v69
	v_min_f32_e32 v70, 0x42c80000, v70
	v_rcp_f32_e32 v72, v71
	v_add_f32_e32 v71, 1.0, v89
	v_add_f32_e32 v73, 1.0, v90
	v_add_f32_e32 v74, 1.0, v91
	v_exp_f32_e32 v244, v78
	v_mul_f32_e32 v78, v241, v243
	v_mul_f32_e32 v79, v245, v246
	v_max_f32_e32 v64, v64, v64
	v_min_f32_e32 v66, 0x42c80000, v66
	v_exp_f32_e32 v85, v68
	v_exp_f32_e32 v86, v69
	v_exp_f32_e32 v87, v70
	v_rcp_f32_e32 v235, v71
	v_rcp_f32_e32 v237, v73
	v_rcp_f32_e32 v239, v74
	v_mul_f32_e32 v78, v78, v79
	v_min_f32_e32 v64, 0x42c80000, v64
	v_max_f32_e32 v65, v65, v65
	v_exp_f32_e32 v218, v66
	v_max_f32_e32 v66, v82, v82
	v_mov_b32_e32 v79, v78
	v_exp_f32_e32 v147, v64
	v_max_f32_e32 v64, v80, v80
	v_min_f32_e32 v65, 0x42c80000, v65
	v_min_f32_e32 v66, 0x42c80000, v66
	v_add_f32_e32 v67, 1.0, v84
	v_permlane32_swap_b32_e32 v78, v79
	v_min_f32_e32 v64, 0x42c80000, v64
	v_exp_f32_e32 v215, v65
	v_max_f32_e32 v65, v81, v81
	v_exp_f32_e32 v82, v66
	v_rcp_f32_e32 v225, v67
	v_add_f32_e32 v67, 1.0, v224
	v_mul_f32_e32 v79, v145, v79
	v_exp_f32_e32 v161, v64
	v_min_f32_e32 v65, 0x42c80000, v65
	v_rcp_f32_e32 v68, v67
	v_add_f32_e32 v67, 1.0, v85
	v_add_f32_e32 v69, 1.0, v86
	v_add_f32_e32 v70, 1.0, v87
	v_mul_f32_e32 v78, v79, v78
	v_cndmask_b32_e64 v145, v145, v79, s[14:15]
	v_mul_f32_e32 v79, v233, v235
	v_mul_f32_e32 v247, v237, v239
	v_exp_f32_e32 v216, v65
	v_rcp_f32_e32 v227, v67
	v_rcp_f32_e32 v229, v69
	v_rcp_f32_e32 v231, v70
	v_mul_f32_e32 v79, v79, v247
	v_mov_b32_e32 v247, v79
	v_add_f32_e32 v66, 1.0, v82
	s_nop 0
	v_permlane32_swap_b32_e32 v79, v247
	v_add_f32_e32 v80, 1.0, v161
	v_add_f32_e32 v65, 1.0, v215
	v_rcp_f32_e32 v221, v66
	v_add_f32_e32 v66, 1.0, v220
	v_mul_f32_e32 v247, v78, v247
	v_rcp_f32_e32 v217, v80
	v_rcp_f32_e32 v80, v65
	v_add_f32_e32 v65, 1.0, v216
	v_rcp_f32_e32 v81, v66
	v_add_f32_e32 v66, 1.0, v83
	v_mul_f32_e32 v79, v247, v79
	v_cndmask_b32_e64 v247, v78, v247, s[14:15]
	v_mul_f32_e32 v78, v225, v227
	v_mul_f32_e32 v248, v229, v231
	v_rcp_f32_e32 v219, v65
	v_rcp_f32_e32 v223, v66
	v_mul_f32_e32 v78, v78, v248
	v_mov_b32_e32 v248, v78
	s_nop 1
	v_permlane32_swap_b32_e32 v78, v248
	v_mul_f32_e32 v248, v79, v248
	v_add_f32_e32 v74, 1.0, v238
	v_add_f32_e32 v75, 1.0, v242
	v_add_f32_e32 v77, 1.0, v244
	v_mul_f32_e32 v78, v248, v78
	v_cndmask_b32_e64 v248, v79, v248, s[14:15]
	v_mul_f32_e32 v79, v217, v219
	v_mul_f32_e32 v249, v221, v223
	v_rcp_f32_e32 v74, v74
	v_rcp_f32_e32 v75, v75
	v_rcp_f32_e32 v77, v77
	v_mul_f32_e32 v79, v79, v249
	v_mov_b32_e32 v249, v79
	s_nop 1
	v_permlane32_swap_b32_e32 v79, v249
	v_mul_f32_e32 v249, v78, v249
	v_add_f32_e32 v70, 1.0, v230
	v_add_f32_e32 v71, 1.0, v234
	v_add_f32_e32 v73, 1.0, v236
	v_mul_f32_e32 v250, v249, v79
	v_cndmask_b32_e64 v249, v78, v249, s[14:15]
	v_pk_mul_f32 v[78:79], v[74:75], v[76:77]
	v_rcp_f32_e32 v70, v70
	v_rcp_f32_e32 v71, v71
	v_rcp_f32_e32 v73, v73
	v_pk_mul_f32 v[78:79], v[78:79], v[78:79] op_sel:[0,1] op_sel_hi:[1,0]
	v_add_f32_e32 v66, 1.0, v222
	v_mov_b32_e32 v79, v78
	s_nop 1
	v_permlane32_swap_b32_e32 v78, v79
; #define SBAR() __builtin_amdgcn_sched_barrier(0)
; template <int OFF> __device__ __forceinline__ s16x4 tr_read(int vb) { s16x4 r; asm volatile("ds_read_b64_tr_b16 %0, %1 offset:%2" : "=&v"(r) : "v"(vb), "i"(OFF) : "memory"); return r; }
; template <int D0> __device__ __forceinline__ void pv_one(f32x16& od, int vb, bf16x8 pa0, bf16x8 pa1, bf16x8 pa2, bf16x8 pa3) {
;     const s16x4 l0 = tr_read<v_rd_off(D0, 0, 0)>(vb), h0 = tr_read<v_rd_off(D0, 0, 1)>(vb), l1 = tr_read<v_rd_off(D0, 1, 0)>(vb), h1 = tr_read<v_rd_off(D0, 1, 1)>(vb);
;     const s16x4 l2 = tr_read<v_rd_off(D0, 2, 0)>(vb), h2 = tr_read<v_rd_off(D0, 2, 1)>(vb), l3 = tr_read<v_rd_off(D0, 3, 0)>(vb), h3 = tr_read<v_rd_off(D0, 3, 1)>(vb);
;     asm volatile("s_waitcnt lgkmcnt(0)" ::: "memory"); SBAR();
;     ...
;     od = __builtin_amdgcn_mfma_f32_32x32x16_bf16(pa0, PKV(l0, h0), od, 0, 0, 0);
;     od = __builtin_amdgcn_mfma_f32_32x32x16_bf16(pa1, PKV(l1, h1), od, 0, 0, 0);
;     od = __builtin_amdgcn_mfma_f32_32x32x16_bf16(pa2, PKV(l2, h2), od, 0, 0, 0);
;     od = __builtin_amdgcn_mfma_f32_32x32x16_bf16(pa3, PKV(l3, h3), od, 0, 0, 0);
;     ...
; }
; __device__ __forceinline__ void pv_d0(f32x16* o, int vb, bf16x8 pa0, bf16x8 pa1, bf16x8 pa2, bf16x8 pa3) {
;     pv_one<0>(o[0], vb, pa0, pa1, pa2, pa3); pv_one<1>(o[1], vb, pa0, pa1, pa2, pa3); pv_one<2>(o[2], vb, pa0, pa1, pa2, pa3); pv_one<3>(o[3], vb, pa0, pa1, pa2, pa3);
; }
; template <int MODE, bool SAMPLE>
; __device__ __forceinline__ void attn_unit(const Params& p, char* lds, int b, int h, int qb) {
;     ...
;                 carry = run;
; #pragma unroll
;                 for (int i = 0; i < 8; ++i) { f32x16& S = (i >= 4) ? s1 : s0; f32x16& Z = (i >= 4) ? p1 : p0; const int rb = 4 * (i & 3);
;                     const float i3 = bs[i] * S[rb + 3], i2 = i3 * S[rb + 2], i1 = i2 * S[rb + 1], i0 = i1 * S[rb];
;                     Z[rb + 3] *= i3; Z[rb + 2] *= i2; Z[rb + 1] *= i1; Z[rb] *= i0; }
;             }
;             PK4(p0, 0, pa0); PK4(p0, 8, pa1); PK4(p1, 0, pa2); PK4(p1, 8, pa3);
;             pv_d0(o, vb, pa0, pa1, pa2, pa3);
	v_mul_f32_e32 v79, v250, v79
	v_add_f32_e32 v67, 1.0, v226
	v_add_f32_e32 v69, 1.0, v228
	v_mul_f32_e32 v251, v79, v78
	v_cndmask_b32_e64 v250, v250, v79, s[14:15]
	v_pk_mul_f32 v[78:79], v[70:71], v[72:73]
	v_rcp_f32_e32 v66, v66
	v_rcp_f32_e32 v67, v67
	v_rcp_f32_e32 v69, v69
	v_pk_mul_f32 v[78:79], v[78:79], v[78:79] op_sel:[0,1] op_sel_hi:[1,0]
	v_add_f32_e32 v64, 1.0, v147
	v_mov_b32_e32 v79, v78
	s_nop 1
	v_permlane32_swap_b32_e32 v78, v79
	v_mul_f32_e32 v79, v251, v79
	v_add_f32_e32 v65, 1.0, v218
	v_mul_f32_e32 v252, v79, v78
	v_cndmask_b32_e64 v251, v251, v79, s[14:15]
	v_pk_mul_f32 v[78:79], v[66:67], v[68:69]
	v_rcp_f32_e32 v64, v64
	v_rcp_f32_e32 v65, v65
	v_pk_mul_f32 v[78:79], v[78:79], v[78:79] op_sel:[0,1] op_sel_hi:[1,0]
	v_mul_f32_e32 v73, v73, v251
	v_mov_b32_e32 v79, v78
	s_nop 1
	v_permlane32_swap_b32_e32 v78, v79
	v_mul_f32_e32 v79, v252, v79
	v_mul_f32_e32 v170, v79, v78
	v_cndmask_b32_e64 v252, v252, v79, s[14:15]
	v_pk_mul_f32 v[78:79], v[64:65], v[80:81]
	v_mul_f32_e32 v69, v69, v252
	v_pk_mul_f32 v[78:79], v[78:79], v[78:79] op_sel:[0,1] op_sel_hi:[1,0]
	v_mul_f32_e32 v77, v77, v250
	v_mov_b32_e32 v79, v78
	s_nop 1
	v_permlane32_swap_b32_e32 v78, v79
	v_mul_f32_e32 v79, v170, v79
	v_cndmask_b32_e64 v170, v170, v79, s[14:15]
	v_mul_f32_e32 v81, v81, v170
	v_mul_f32_e32 v65, v65, v81
	v_mul_f32_e32 v80, v80, v65
	v_mul_f32_e32 v64, v64, v80
	v_mul_f32_e32 v64, v147, v64
	v_mul_f32_e32 v147, v223, v249
	v_mul_f32_e32 v170, v221, v147
	v_mul_f32_e32 v80, v215, v80
	v_mul_f32_e32 v215, v219, v170
	v_mul_f32_e32 v82, v82, v170
	v_mul_f32_e32 v170, v231, v248
	v_mul_f32_e32 v67, v67, v69
	v_mul_f32_e32 v71, v71, v73
	v_mul_f32_e32 v75, v75, v77
	v_mul_f32_e32 v217, v217, v215
	v_mul_f32_e32 v83, v83, v147
	v_mul_f32_e32 v147, v216, v215
	v_mul_f32_e32 v215, v229, v170
	v_mul_f32_e32 v87, v87, v170
	v_mul_f32_e32 v170, v239, v247
	v_mul_f32_e32 v145, v246, v145
	v_mul_f32_e32 v68, v68, v67
	v_mul_f32_e32 v72, v72, v71
	v_mul_f32_e32 v76, v76, v75
	v_mul_f32_e32 v216, v227, v215
	v_mul_f32_e32 v86, v86, v215
	v_mul_f32_e32 v215, v237, v170
	v_mul_f32_e32 v91, v91, v170
	v_mul_f32_e32 v170, v245, v145
	v_mul_f32_e32 v66, v66, v68
	v_mul_f32_e32 v70, v70, v72
	v_mul_f32_e32 v74, v74, v76
	v_mul_f32_e32 v161, v161, v217
	v_mul_f32_e32 v217, v225, v216
	v_mul_f32_e32 v85, v85, v216
	v_mul_f32_e32 v216, v235, v215
	v_mul_f32_e32 v90, v90, v215
	v_mul_f32_e32 v215, v243, v170
	v_mul_f32_e32 v81, v220, v81
	v_mul_f32_e32 v65, v218, v65
	v_mul_f32_e32 v69, v228, v69
	v_mul_f32_e32 v67, v226, v67
	v_mul_f32_e32 v68, v224, v68
	v_mul_f32_e32 v66, v222, v66
	v_mul_f32_e32 v73, v236, v73
	v_mul_f32_e32 v71, v234, v71
	v_mul_f32_e32 v72, v232, v72
	v_mul_f32_e32 v70, v230, v70
	v_mul_f32_e32 v77, v244, v77
	v_mul_f32_e32 v75, v242, v75
	v_mul_f32_e32 v76, v240, v76
	v_mul_f32_e32 v74, v238, v74
	v_mul_f32_e32 v84, v84, v217
	v_mul_f32_e32 v217, v233, v216
	v_mul_f32_e32 v89, v89, v216
	v_mul_f32_e32 v216, v241, v215
	v_mul_f32_e32 v88, v88, v217
	v_mul_f32_e32 v95, v95, v145
	v_mul_f32_e32 v94, v94, v170
	v_mul_f32_e32 v93, v93, v215
	v_mul_f32_e32 v92, v92, v216
	v_mul_f32_e32 v145, v79, v78
	v_cvt_pk_bf16_f32 v64, v64, v80
	v_cvt_pk_bf16_f32 v65, v65, v81
	v_cvt_pk_bf16_f32 v66, v66, v68
	v_cvt_pk_bf16_f32 v67, v67, v69
	v_cvt_pk_bf16_f32 v68, v70, v72
	v_cvt_pk_bf16_f32 v69, v71, v73
	v_cvt_pk_bf16_f32 v70, v74, v76
	v_cvt_pk_bf16_f32 v71, v75, v77
	v_cvt_pk_bf16_f32 v72, v161, v147
	v_cvt_pk_bf16_f32 v73, v82, v83
	v_cvt_pk_bf16_f32 v74, v84, v85
	v_cvt_pk_bf16_f32 v75, v86, v87
	v_cvt_pk_bf16_f32 v76, v88, v89
	v_cvt_pk_bf16_f32 v77, v90, v91
	v_cvt_pk_bf16_f32 v78, v92, v93
	v_cvt_pk_bf16_f32 v79, v94, v95
	ds_read_b64_tr_b16 v[80:81], v191 offset:0
	ds_read_b64_tr_b16 v[82:83], v191 offset:0x800
	ds_read_b64_tr_b16 v[84:85], v191 offset:0x1000
	ds_read_b64_tr_b16 v[86:87], v191 offset:0x1800
	ds_read_b64_tr_b16 v[88:89], v191 offset:0x2000
	ds_read_b64_tr_b16 v[90:91], v191 offset:0x2800
	ds_read_b64_tr_b16 v[92:93], v191 offset:0x3000
	ds_read_b64_tr_b16 v[94:95], v191 offset:0x3800
	s_waitcnt lgkmcnt(0)
	s_nop 0
	v_permlane32_swap_b32_e32 v64, v66
	v_permlane32_swap_b32_e32 v65, v67
	v_permlane32_swap_b32_e32 v68, v70
	v_permlane32_swap_b32_e32 v69, v71
	v_permlane32_swap_b32_e32 v72, v74
	v_permlane32_swap_b32_e32 v73, v75
	v_permlane32_swap_b32_e32 v76, v78
	v_permlane32_swap_b32_e32 v77, v79
	s_setprio 1
	v_mfma_f32_32x32x16_bf16 v[48:63], v[64:67], v[80:83], v[48:63]
	ds_read_b64_tr_b16 v[80:81], v191 offset:0x200
	ds_read_b64_tr_b16 v[82:83], v191 offset:0xa00
	v_mfma_f32_32x32x16_bf16 v[48:63], v[68:71], v[84:87], v[48:63]
	ds_read_b64_tr_b16 v[84:85], v191 offset:0x1200
	ds_read_b64_tr_b16 v[86:87], v191 offset:0x1a00
	v_mfma_f32_32x32x16_bf16 v[48:63], v[72:75], v[88:91], v[48:63]
	ds_read_b64_tr_b16 v[88:89], v191 offset:0x2200
	ds_read_b64_tr_b16 v[90:91], v191 offset:0x2a00
	v_mfma_f32_32x32x16_bf16 v[48:63], v[76:79], v[92:95], v[48:63]
	ds_read_b64_tr_b16 v[92:93], v191 offset:0x3200
	ds_read_b64_tr_b16 v[94:95], v191 offset:0x3a00
	s_waitcnt lgkmcnt(0)
	v_mfma_f32_32x32x16_bf16 v[32:47], v[64:67], v[80:83], v[32:47]
	ds_read_b64_tr_b16 v[80:81], v191 offset:0x400
	ds_read_b64_tr_b16 v[82:83], v191 offset:0xc00
	v_mfma_f32_32x32x16_bf16 v[32:47], v[68:71], v[84:87], v[32:47]
	ds_read_b64_tr_b16 v[84:85], v191 offset:0x1400
	ds_read_b64_tr_b16 v[86:87], v191 offset:0x1c00
	v_mfma_f32_32x32x16_bf16 v[32:47], v[72:75], v[88:91], v[32:47]
	ds_read_b64_tr_b16 v[88:89], v191 offset:0x2400
	ds_read_b64_tr_b16 v[90:91], v191 offset:0x2c00
	v_mfma_f32_32x32x16_bf16 v[32:47], v[76:79], v[92:95], v[32:47]
	ds_read_b64_tr_b16 v[92:93], v191 offset:0x3400
	ds_read_b64_tr_b16 v[94:95], v191 offset:0x3c00
	s_waitcnt lgkmcnt(0)
	v_mfma_f32_32x32x16_bf16 v[16:31], v[64:67], v[80:83], v[16:31]
	ds_read_b64_tr_b16 v[80:81], v191 offset:0x600
	ds_read_b64_tr_b16 v[82:83], v191 offset:0xe00
	v_mfma_f32_32x32x16_bf16 v[16:31], v[68:71], v[84:87], v[16:31]
	ds_read_b64_tr_b16 v[84:85], v191 offset:0x1600
	ds_read_b64_tr_b16 v[86:87], v191 offset:0x1e00
	v_mfma_f32_32x32x16_bf16 v[16:31], v[72:75], v[88:91], v[16:31]
	ds_read_b64_tr_b16 v[88:89], v191 offset:0x2600
	ds_read_b64_tr_b16 v[90:91], v191 offset:0x2e00
	v_mfma_f32_32x32x16_bf16 v[16:31], v[76:79], v[92:95], v[16:31]
	ds_read_b64_tr_b16 v[92:93], v191 offset:0x3600
	ds_read_b64_tr_b16 v[94:95], v191 offset:0x3e00
	s_waitcnt lgkmcnt(0)
	v_mfma_f32_32x32x16_bf16 v[0:15], v[64:67], v[80:83], v[0:15]
	v_mfma_f32_32x32x16_bf16 v[0:15], v[68:71], v[84:87], v[0:15]
	v_mfma_f32_32x32x16_bf16 v[0:15], v[72:75], v[88:91], v[0:15]
	v_mfma_f32_32x32x16_bf16 v[0:15], v[76:79], v[92:95], v[0:15]
	s_setprio 0

; __device__ __forceinline__ int crow(int r, int hi) { return (r & 3) + 8 * (r >> 2) + 4 * hi; }
; __device__ __forceinline__ void qkt(f32x16& p0, f32x16& p1, const char* Ks, const char* Qs, int r32, int hi) {
; #pragma unroll
;     for (int d0 = 0; d0 < 8; ++d0) { const int cb = (d0 * 16 + hi * 8) * 2;
;         const bf16x8 qv = *reinterpret_cast<const bf16x8*>(Qs + KSWZ(r32, cb));
;         const bf16x8 b0 = *reinterpret_cast<const bf16x8*>(Ks + KSWZ(r32, cb));
;         const bf16x8 b1 = *reinterpret_cast<const bf16x8*>(Ks + KSWZ(32 + r32, cb));
;         p0 = __builtin_amdgcn_mfma_f32_32x32x16_bf16(b0, qv, p0, 0, 0, 0);
;         p1 = __builtin_amdgcn_mfma_f32_32x32x16_bf16(b1, qv, p1, 0, 0, 0); }
; }
; template <int MODE, bool SAMPLE>
; __device__ __forceinline__ void attn_unit(const Params& p, char* lds, int b, int h, int qb) {
;     ...
;                 p0 = f32x16{}; p1 = f32x16{};
;                 qkt(p0, p1, Kt, Qs, r32, hi);
;                 if (j == jd) {
; #pragma unroll
;                     for (int r = 0; r < 16; ++r) { const int kp = j * 64 + crow(r, hi); if (kp >= qpos) p0[r] = -1e30f; if (kp + 32 >= qpos) p1[r] = -1e30f; } }
.Lstg_3:
	ds_read_b128 v[64:67], v202
	ds_read_b128 v[84:87], v202 offset:8192
	v_add_u32_e32 v68, s12, v182
	ds_read_b128 v[80:83], v68
	ds_read_b128 v[216:219], v203
	v_add_u32_e32 v147, s12, v184
	ds_read_b128 v[220:223], v147
	v_add_u32_e32 v147, s12, v185
	s_cmp_lg_u32 s13, s33
	s_waitcnt lgkmcnt(2)
	s_setprio 1
	v_mfma_f32_32x32x16_bf16 v[64:79], v[64:67], v[80:83], 0
	s_waitcnt lgkmcnt(0)
	v_mfma_f32_32x32x16_bf16 v[64:79], v[216:219], v[220:223], v[64:79]
	ds_read_b128 v[216:219], v203 offset:8192
	v_mfma_f32_32x32x16_bf16 v[80:95], v[84:87], v[80:83], 0
	s_waitcnt lgkmcnt(0)
	v_mfma_f32_32x32x16_bf16 v[80:95], v[216:219], v[220:223], v[80:95]
	ds_read_b128 v[216:219], v204
	ds_read_b128 v[220:223], v147
	v_add_u32_e32 v147, s12, v186
	s_waitcnt lgkmcnt(0)
	v_mfma_f32_32x32x16_bf16 v[64:79], v[216:219], v[220:223], v[64:79]
	ds_read_b128 v[216:219], v204 offset:8192
	s_waitcnt lgkmcnt(0)
	v_mfma_f32_32x32x16_bf16 v[80:95], v[216:219], v[220:223], v[80:95]
	ds_read_b128 v[216:219], v205
	ds_read_b128 v[220:223], v147
	v_add_u32_e32 v147, s12, v187
	s_waitcnt lgkmcnt(0)
	v_mfma_f32_32x32x16_bf16 v[64:79], v[216:219], v[220:223], v[64:79]
	ds_read_b128 v[216:219], v205 offset:8192
	s_waitcnt lgkmcnt(0)
	v_mfma_f32_32x32x16_bf16 v[80:95], v[216:219], v[220:223], v[80:95]
	ds_read_b128 v[216:219], v206
	ds_read_b128 v[220:223], v147
	v_add_u32_e32 v147, s12, v188
	s_waitcnt lgkmcnt(0)
	v_mfma_f32_32x32x16_bf16 v[64:79], v[216:219], v[220:223], v[64:79]
	ds_read_b128 v[216:219], v206 offset:8192
	s_waitcnt lgkmcnt(0)
	v_mfma_f32_32x32x16_bf16 v[80:95], v[216:219], v[220:223], v[80:95]
	ds_read_b128 v[216:219], v207
	ds_read_b128 v[220:223], v147
	v_add_u32_e32 v147, s12, v189
	s_waitcnt lgkmcnt(0)
	v_mfma_f32_32x32x16_bf16 v[64:79], v[216:219], v[220:223], v[64:79]
	ds_read_b128 v[216:219], v207 offset:8192
	s_waitcnt lgkmcnt(0)
	v_mfma_f32_32x32x16_bf16 v[80:95], v[216:219], v[220:223], v[80:95]
	ds_read_b128 v[216:219], v208
	ds_read_b128 v[220:223], v147
	v_add_u32_e32 v147, s12, v190
	s_waitcnt lgkmcnt(0)
	v_mfma_f32_32x32x16_bf16 v[64:79], v[216:219], v[220:223], v[64:79]
	ds_read_b128 v[216:219], v208 offset:8192
	s_waitcnt lgkmcnt(0)
	v_mfma_f32_32x32x16_bf16 v[80:95], v[216:219], v[220:223], v[80:95]
	ds_read_b128 v[216:219], v209
	ds_read_b128 v[220:223], v147
	s_waitcnt lgkmcnt(0)
	v_mfma_f32_32x32x16_bf16 v[64:79], v[216:219], v[220:223], v[64:79]
	ds_read_b128 v[216:219], v209 offset:8192
	s_waitcnt lgkmcnt(0)
	v_mfma_f32_32x32x16_bf16 v[80:95], v[216:219], v[220:223], v[80:95]
	s_setprio 0
	s_cbranch_scc1 .LBB0_706
	s_or_b64 s[80:81], s[76:77], s[72:73]
	s_nop 6
	v_cndmask_b32_e64 v78, v214, v78, s[80:81]
	s_or_b64 s[80:81], s[80:81], s[68:69]
	v_cndmask_b32_e64 v77, v214, v77, s[80:81]
	s_or_b64 s[80:81], s[80:81], s[64:65]
	v_cndmask_b32_e64 v76, v214, v76, s[80:81]
	s_or_b64 s[80:81], s[80:81], s[60:61]
	v_cndmask_b32_e64 v75, v214, v75, s[80:81]
	s_or_b64 s[80:81], s[80:81], s[56:57]
	v_cndmask_b32_e64 v74, v214, v74, s[80:81]
	s_or_b64 s[80:81], s[80:81], s[52:53]
	v_cndmask_b32_e64 v73, v214, v73, s[80:81]
	s_or_b64 s[80:81], s[80:81], s[48:49]
	v_cndmask_b32_e64 v72, v214, v72, s[80:81]
	s_or_b64 s[80:81], s[80:81], s[44:45]
	v_cndmask_b32_e64 v71, v214, v71, s[80:81]
	s_or_b64 s[80:81], s[80:81], s[40:41]
	v_cndmask_b32_e64 v70, v214, v70, s[80:81]
	s_or_b64 s[80:81], s[80:81], s[36:37]
	v_cndmask_b32_e64 v69, v214, v69, s[80:81]
	s_or_b64 s[80:81], s[80:81], s[30:31]
	v_cndmask_b32_e64 v68, v214, v68, s[80:81]
	s_or_b64 s[80:81], s[80:81], s[26:27]
	v_cndmask_b32_e64 v67, v214, v67, s[80:81]
	s_or_b64 s[80:81], s[80:81], s[22:23]
	v_cndmask_b32_e64 v66, v214, v66, s[80:81]
	s_or_b64 s[80:81], s[80:81], s[18:19]
	v_cndmask_b32_e64 v65, v214, v65, s[80:81]
	s_or_b64 s[80:81], s[80:81], vcc
	v_cndmask_b32_e64 v64, v214, v64, s[80:81]
	s_or_b64 s[80:81], s[78:79], s[74:75]
	v_cndmask_b32_e64 v94, v214, v94, s[80:81]
	s_or_b64 s[80:81], s[80:81], s[70:71]
	v_cndmask_b32_e64 v93, v214, v93, s[80:81]
	s_or_b64 s[80:81], s[80:81], s[66:67]
	v_cndmask_b32_e64 v92, v214, v92, s[80:81]
	s_or_b64 s[80:81], s[80:81], s[62:63]
	v_cndmask_b32_e64 v91, v214, v91, s[80:81]
	s_or_b64 s[80:81], s[80:81], s[58:59]
	v_cndmask_b32_e64 v90, v214, v90, s[80:81]
	s_or_b64 s[80:81], s[80:81], s[54:55]
	v_cndmask_b32_e64 v89, v214, v89, s[80:81]
	s_or_b64 s[80:81], s[80:81], s[50:51]
	v_cndmask_b32_e64 v88, v214, v88, s[80:81]
	s_or_b64 s[80:81], s[80:81], s[46:47]
	v_cndmask_b32_e64 v87, v214, v87, s[80:81]
	s_or_b64 s[80:81], s[80:81], s[42:43]
	v_cndmask_b32_e64 v86, v214, v86, s[80:81]
	s_or_b64 s[80:81], s[80:81], s[38:39]
	v_cndmask_b32_e64 v85, v214, v85, s[80:81]
	s_or_b64 s[80:81], s[80:81], s[34:35]
	v_cndmask_b32_e64 v84, v214, v84, s[80:81]
	s_or_b64 s[80:81], s[80:81], s[28:29]
	v_cndmask_b32_e64 v83, v214, v83, s[80:81]
	s_or_b64 s[80:81], s[80:81], s[24:25]
	v_cndmask_b32_e64 v82, v214, v82, s[80:81]
	s_or_b64 s[80:81], s[80:81], s[20:21]
	v_cndmask_b32_e64 v81, v214, v81, s[80:81]
	s_or_b64 s[80:81], s[80:81], s[0:1]
	v_cndmask_b32_e64 v79, v214, v79, s[76:77]
	v_cndmask_b32_e64 v95, v214, v95, s[78:79]
	v_cndmask_b32_e64 v80, v214, v80, s[80:81]
	s_branch .LBB0_706

; #define SBAR() __builtin_amdgcn_sched_barrier(0)
; template <int OFF> __device__ __forceinline__ s16x4 tr_read(int vb) { s16x4 r; asm volatile("ds_read_b64_tr_b16 %0, %1 offset:%2" : "=&v"(r) : "v"(vb), "i"(OFF) : "memory"); return r; }
; template <int D0> __device__ __forceinline__ void pv_one(f32x16& od, int vb, bf16x8 pa0, bf16x8 pa1, bf16x8 pa2, bf16x8 pa3) {
;     const s16x4 l0 = tr_read<v_rd_off(D0, 0, 0)>(vb), h0 = tr_read<v_rd_off(D0, 0, 1)>(vb), l1 = tr_read<v_rd_off(D0, 1, 0)>(vb), h1 = tr_read<v_rd_off(D0, 1, 1)>(vb);
;     const s16x4 l2 = tr_read<v_rd_off(D0, 2, 0)>(vb), h2 = tr_read<v_rd_off(D0, 2, 1)>(vb), l3 = tr_read<v_rd_off(D0, 3, 0)>(vb), h3 = tr_read<v_rd_off(D0, 3, 1)>(vb);
;     asm volatile("s_waitcnt lgkmcnt(0)" ::: "memory"); SBAR();
;     ...
;     od = __builtin_amdgcn_mfma_f32_32x32x16_bf16(pa0, PKV(l0, h0), od, 0, 0, 0);
;     od = __builtin_amdgcn_mfma_f32_32x32x16_bf16(pa1, PKV(l1, h1), od, 0, 0, 0);
;     od = __builtin_amdgcn_mfma_f32_32x32x16_bf16(pa2, PKV(l2, h2), od, 0, 0, 0);
;     od = __builtin_amdgcn_mfma_f32_32x32x16_bf16(pa3, PKV(l3, h3), od, 0, 0, 0);
;     ...
; }
; __device__ __forceinline__ void pv_d0(f32x16* o, int vb, bf16x8 pa0, bf16x8 pa1, bf16x8 pa2, bf16x8 pa3) {
;     pv_one<0>(o[0], vb, pa0, pa1, pa2, pa3); pv_one<1>(o[1], vb, pa0, pa1, pa2, pa3); pv_one<2>(o[2], vb, pa0, pa1, pa2, pa3); pv_one<3>(o[3], vb, pa0, pa1, pa2, pa3);
; }
; template <int MODE, bool SAMPLE>
; __device__ __forceinline__ void attn_unit(const Params& p, char* lds, int b, int h, int qb) {
;     ...
;             PK4(p0, 0, pa0); PK4(p0, 8, pa1); PK4(p1, 0, pa2); PK4(p1, 8, pa3);
;             pv_d0(o, vb, pa0, pa1, pa2, pa3);
.LBB0_755:
	v_cvt_pk_bf16_f32 v218, v159, v215
	v_cvt_pk_bf16_f32 v219, v81, v82
	v_cvt_pk_bf16_f32 v220, v83, v84
	v_cvt_pk_bf16_f32 v221, v85, v216
	v_cvt_pk_bf16_f32 v82, v86, v87
	v_cvt_pk_bf16_f32 v83, v88, v89
	v_cvt_pk_bf16_f32 v84, v90, v91
	v_cvt_pk_bf16_f32 v85, v92, v79
	v_cvt_pk_bf16_f32 v64, v64, v65
	v_cvt_pk_bf16_f32 v65, v66, v67
	v_cvt_pk_bf16_f32 v66, v68, v69
	v_cvt_pk_bf16_f32 v67, v70, v80
	v_cvt_pk_bf16_f32 v68, v71, v72
	v_cvt_pk_bf16_f32 v69, v73, v74
	v_cvt_pk_bf16_f32 v70, v75, v76
	v_cvt_pk_bf16_f32 v71, v77, v78
	ds_read_b64_tr_b16 v[72:73], v179 offset:0
	ds_read_b64_tr_b16 v[74:75], v179 offset:0x800
	ds_read_b64_tr_b16 v[76:77], v179 offset:0x1000
	ds_read_b64_tr_b16 v[78:79], v179 offset:0x1800
	ds_read_b64_tr_b16 v[86:87], v179 offset:0x2000
	ds_read_b64_tr_b16 v[88:89], v179 offset:0x2800
	v_add_f32_e32 v94, v94, v95
	ds_read_b64_tr_b16 v[90:91], v179 offset:0x3000
	v_fmac_f32_e32 v94, v214, v93
	ds_read_b64_tr_b16 v[92:93], v179 offset:0x3800
	s_waitcnt lgkmcnt(0)
	v_permlane32_swap_b32_e32 v218, v220
	v_permlane32_swap_b32_e32 v219, v221
	v_permlane32_swap_b32_e32 v82, v84
	v_permlane32_swap_b32_e32 v83, v85
	v_permlane32_swap_b32_e32 v64, v66
	v_permlane32_swap_b32_e32 v65, v67
	v_permlane32_swap_b32_e32 v68, v70
	v_permlane32_swap_b32_e32 v69, v71
	s_setprio 1
	v_mfma_f32_32x32x16_bf16 v[16:31], v[218:221], v[72:75], v[16:31]
	ds_read_b64_tr_b16 v[72:73], v179 offset:0x200
	ds_read_b64_tr_b16 v[74:75], v179 offset:0xa00
	v_mfma_f32_32x32x16_bf16 v[16:31], v[82:85], v[76:79], v[16:31]
	ds_read_b64_tr_b16 v[76:77], v179 offset:0x1200
	ds_read_b64_tr_b16 v[78:79], v179 offset:0x1a00
	v_mfma_f32_32x32x16_bf16 v[16:31], v[64:67], v[86:89], v[16:31]
	ds_read_b64_tr_b16 v[86:87], v179 offset:0x2200
	ds_read_b64_tr_b16 v[88:89], v179 offset:0x2a00
	ds_read_b64_tr_b16 v[214:215], v179 offset:0x3200
	ds_read_b64_tr_b16 v[216:217], v179 offset:0x3a00
	s_waitcnt lgkmcnt(0)
	v_mfma_f32_32x32x16_bf16 v[16:31], v[68:71], v[90:93], v[16:31]
	v_mfma_f32_32x32x16_bf16 v[48:63], v[218:221], v[72:75], v[48:63]
	ds_read_b64_tr_b16 v[72:73], v179 offset:0x400
	ds_read_b64_tr_b16 v[74:75], v179 offset:0xc00
	v_mfma_f32_32x32x16_bf16 v[48:63], v[82:85], v[76:79], v[48:63]
	ds_read_b64_tr_b16 v[76:77], v179 offset:0x1400
	ds_read_b64_tr_b16 v[78:79], v179 offset:0x1c00
	v_mfma_f32_32x32x16_bf16 v[48:63], v[64:67], v[86:89], v[48:63]
	ds_read_b64_tr_b16 v[86:87], v179 offset:0x2400
	ds_read_b64_tr_b16 v[88:89], v179 offset:0x2c00
	ds_read_b64_tr_b16 v[90:91], v179 offset:0x3400
	ds_read_b64_tr_b16 v[92:93], v179 offset:0x3c00
	s_waitcnt lgkmcnt(0)
	v_mfma_f32_32x32x16_bf16 v[48:63], v[68:71], v[214:217], v[48:63]
	v_mfma_f32_32x32x16_bf16 v[32:47], v[218:221], v[72:75], v[32:47]
	ds_read_b64_tr_b16 v[72:73], v179 offset:0x600
	ds_read_b64_tr_b16 v[74:75], v179 offset:0xe00
	v_mfma_f32_32x32x16_bf16 v[32:47], v[82:85], v[76:79], v[32:47]
	ds_read_b64_tr_b16 v[76:77], v179 offset:0x1600
	ds_read_b64_tr_b16 v[78:79], v179 offset:0x1e00
	v_mfma_f32_32x32x16_bf16 v[32:47], v[64:67], v[86:89], v[32:47]
	ds_read_b64_tr_b16 v[86:87], v179 offset:0x2600
	ds_read_b64_tr_b16 v[88:89], v179 offset:0x2e00
	ds_read_b64_tr_b16 v[222:223], v179 offset:0x3600
	ds_read_b64_tr_b16 v[224:225], v179 offset:0x3e00
	s_waitcnt lgkmcnt(0)
	v_mfma_f32_32x32x16_bf16 v[32:47], v[68:71], v[90:93], v[32:47]
	v_mfma_f32_32x32x16_bf16 v[0:15], v[218:221], v[72:75], v[0:15]
	v_mov_b32_e32 v214, v94
	v_mfma_f32_32x32x16_bf16 v[0:15], v[82:85], v[76:79], v[0:15]
	v_mfma_f32_32x32x16_bf16 v[0:15], v[64:67], v[86:89], v[0:15]
	v_mfma_f32_32x32x16_bf16 v[0:15], v[68:71], v[222:225], v[0:15]
	s_setprio 0

; __device__ __forceinline__ int crow(int r, int hi) { return (r & 3) + 8 * (r >> 2) + 4 * hi; }
; __device__ __forceinline__ void qkt(f32x16& p0, f32x16& p1, const char* Ks, const char* Qs, int r32, int hi) {
; #pragma unroll
;     for (int d0 = 0; d0 < 8; ++d0) { const int cb = (d0 * 16 + hi * 8) * 2;
;         const bf16x8 qv = *reinterpret_cast<const bf16x8*>(Qs + KSWZ(r32, cb));
;         const bf16x8 b0 = *reinterpret_cast<const bf16x8*>(Ks + KSWZ(r32, cb));
;         const bf16x8 b1 = *reinterpret_cast<const bf16x8*>(Ks + KSWZ(32 + r32, cb));
;         p0 = __builtin_amdgcn_mfma_f32_32x32x16_bf16(b0, qv, p0, 0, 0, 0);
;         p1 = __builtin_amdgcn_mfma_f32_32x32x16_bf16(b1, qv, p1, 0, 0, 0); }
; }
; template <int MODE, bool SAMPLE>
; __device__ __forceinline__ void attn_unit(const Params& p, char* lds, int b, int h, int qb) {
;     ...
;         if (wact && j <= jd && var < 2) {
;             const char* Kt = K_lds + buf * 16384; const int vb = vb0 + buf * 16384;
;             f32x16 p0, p1; bf16x8 pa0, pa1, pa2, pa3;
;             if (MODE == 0) {
;                 const float* bt = biasL + j * 64 + 4 * hi;
; #pragma unroll
;                 for (int g = 0; g < 4; ++g) { const f32x4 a = *(const f32x4*)(bt + 8 * g), c = *(const f32x4*)(bt + 32 + 8 * g);
; #pragma unroll
;                     for (int i = 0; i < 4; ++i) { p0[4 * g + i] = a[i]; p1[4 * g + i] = c[i]; } }
;                 qkt(p0, p1, Kt, Qs, r32, hi);
;                 if (j == jd) {
; #pragma unroll
;                     for (int r = 0; r < 16; ++r) { const int kp = j * 64 + crow(r, hi); if (kp > qpos) p0[r] = -1e30f; if (kp + 32 > qpos) p1[r] = -1e30f; } }
.Lstg_4:
	v_add_u32_e32 v64, s24, v181
	v_add_u32_e32 v84, 0, v181
	ds_read_b128 v[216:219], v64
	ds_read_b128 v[80:83], v84 offset:16384
	ds_read_b128 v[64:67], v199 offset:256
	ds_read_b128 v[68:71], v199 offset:288
	ds_read_b128 v[72:75], v199 offset:320
	ds_read_b128 v[76:79], v199 offset:352
	ds_read_b128 v[220:223], v84 offset:24576
	v_add_u32_e32 v159, s24, v182
	v_add_u32_e32 v215, s24, v184
	s_waitcnt lgkmcnt(1)
	s_setprio 1
	v_mfma_f32_32x32x16_bf16 v[64:79], v[80:83], v[216:219], v[64:79]
	ds_read_b128 v[80:83], v199 offset:384
	ds_read_b128 v[84:87], v199 offset:416
	ds_read_b128 v[88:91], v199 offset:448
	ds_read_b128 v[92:95], v199 offset:480
	ds_read_b128 v[224:227], v159
	v_add_u32_e32 v159, 0, v182
	s_cmp_lg_u32 s19, s18
	s_waitcnt lgkmcnt(1)
	v_mfma_f32_32x32x16_bf16 v[80:95], v[220:223], v[216:219], v[80:95]
	ds_read_b128 v[216:219], v159 offset:16384
	ds_read_b128 v[220:223], v159 offset:24576
	v_add_u32_e32 v159, 0, v184
	s_waitcnt lgkmcnt(1)
	v_mfma_f32_32x32x16_bf16 v[64:79], v[216:219], v[224:227], v[64:79]
	ds_read_b128 v[216:219], v159 offset:16384
	s_waitcnt lgkmcnt(1)
	v_mfma_f32_32x32x16_bf16 v[80:95], v[220:223], v[224:227], v[80:95]
	ds_read_b128 v[220:223], v215
	v_add_u32_e32 v215, s24, v186
	s_waitcnt lgkmcnt(0)
	v_mfma_f32_32x32x16_bf16 v[64:79], v[216:219], v[220:223], v[64:79]
	ds_read_b128 v[216:219], v159 offset:24576
	v_add_u32_e32 v159, s24, v185
	ds_read_b128 v[224:227], v159
	v_add_u32_e32 v159, 0, v185
	s_waitcnt lgkmcnt(1)
	v_mfma_f32_32x32x16_bf16 v[80:95], v[216:219], v[220:223], v[80:95]
	ds_read_b128 v[216:219], v159 offset:16384
	ds_read_b128 v[220:223], v159 offset:24576
	v_add_u32_e32 v159, 0, v186
	s_waitcnt lgkmcnt(1)
	v_mfma_f32_32x32x16_bf16 v[64:79], v[216:219], v[224:227], v[64:79]
	ds_read_b128 v[216:219], v159 offset:16384
	s_waitcnt lgkmcnt(1)
	v_mfma_f32_32x32x16_bf16 v[80:95], v[220:223], v[224:227], v[80:95]
	ds_read_b128 v[220:223], v215
	v_add_u32_e32 v215, s24, v188
	s_waitcnt lgkmcnt(0)
	v_mfma_f32_32x32x16_bf16 v[64:79], v[216:219], v[220:223], v[64:79]
	ds_read_b128 v[216:219], v159 offset:24576
	v_add_u32_e32 v159, s24, v187
	ds_read_b128 v[224:227], v159
	v_add_u32_e32 v159, 0, v187
	s_waitcnt lgkmcnt(1)
	v_mfma_f32_32x32x16_bf16 v[80:95], v[216:219], v[220:223], v[80:95]
	ds_read_b128 v[216:219], v159 offset:16384
	ds_read_b128 v[220:223], v159 offset:24576
	v_add_u32_e32 v159, 0, v188
	s_waitcnt lgkmcnt(1)
	v_mfma_f32_32x32x16_bf16 v[64:79], v[216:219], v[224:227], v[64:79]
	ds_read_b128 v[216:219], v159 offset:16384
	s_waitcnt lgkmcnt(1)
	v_mfma_f32_32x32x16_bf16 v[80:95], v[220:223], v[224:227], v[80:95]
	ds_read_b128 v[220:223], v215
	s_waitcnt lgkmcnt(0)
	v_mfma_f32_32x32x16_bf16 v[64:79], v[216:219], v[220:223], v[64:79]
	ds_read_b128 v[216:219], v159 offset:24576
	v_add_u32_e32 v159, s24, v189
	ds_read_b128 v[224:227], v159
	v_add_u32_e32 v159, 0, v189
	s_waitcnt lgkmcnt(1)
	v_mfma_f32_32x32x16_bf16 v[80:95], v[216:219], v[220:223], v[80:95]
	ds_read_b128 v[216:219], v159 offset:16384
	ds_read_b128 v[220:223], v159 offset:24576
	s_waitcnt lgkmcnt(1)
	v_mfma_f32_32x32x16_bf16 v[64:79], v[216:219], v[224:227], v[64:79]
	s_waitcnt lgkmcnt(0)
	v_mfma_f32_32x32x16_bf16 v[80:95], v[220:223], v[224:227], v[80:95]
	s_setprio 0
	s_cbranch_scc1 .LBB0_763
	v_add_u32_e32 v159, s14, v201
	v_add_u32_e32 v216, 0x60, v159
	v_add_u32_e32 v215, 64, v159
	v_cmp_le_i32_e32 vcc, v216, v198
	s_nop 6
	v_cndmask_b32_e32 v80, v213, v80, vcc
	v_cmp_lt_i32_e32 vcc, v215, v198
	s_nop 1
	v_cndmask_b32_e32 v65, v213, v65, vcc
	v_cmp_le_i32_e32 vcc, v215, v198
	v_add_u32_e32 v215, 0x61, v159
	s_nop 0
	v_cndmask_b32_e32 v64, v213, v64, vcc
	v_cmp_le_i32_e32 vcc, v215, v198
	v_add_u32_e32 v215, 0x42, v159
	s_nop 0
	v_cndmask_b32_e32 v81, v213, v81, vcc
	v_cmp_le_i32_e32 vcc, v215, v198
	v_add_u32_e32 v215, 0x62, v159
	s_nop 0
	v_cndmask_b32_e32 v66, v213, v66, vcc
	v_cmp_le_i32_e32 vcc, v215, v198
	v_add_u32_e32 v215, 0x43, v159
	s_nop 0
	v_cndmask_b32_e32 v82, v213, v82, vcc
	v_cmp_le_i32_e32 vcc, v215, v198
	v_add_u32_e32 v215, 0x63, v159
	s_nop 0
	v_cndmask_b32_e32 v67, v213, v67, vcc
	v_cmp_le_i32_e32 vcc, v215, v198
	v_add_u32_e32 v215, 0x48, v159
	s_nop 0
	v_cndmask_b32_e32 v83, v213, v83, vcc
	v_cmp_le_i32_e32 vcc, v215, v198
	v_add_u32_e32 v215, 0x68, v159
	s_nop 0
	v_cndmask_b32_e32 v68, v213, v68, vcc
	v_cmp_le_i32_e32 vcc, v215, v198
	v_add_u32_e32 v215, 0x49, v159
	s_nop 0
	v_cndmask_b32_e32 v84, v213, v84, vcc
	v_cmp_le_i32_e32 vcc, v215, v198
	v_add_u32_e32 v215, 0x69, v159
	s_nop 0
	v_cndmask_b32_e32 v69, v213, v69, vcc
	v_cmp_le_i32_e32 vcc, v215, v198
	v_add_u32_e32 v215, 0x4a, v159
	s_nop 0
	v_cndmask_b32_e32 v85, v213, v85, vcc
	v_cmp_le_i32_e32 vcc, v215, v198
	v_add_u32_e32 v215, 0x6a, v159
	s_nop 0
	v_cndmask_b32_e32 v70, v213, v70, vcc
	v_cmp_le_i32_e32 vcc, v215, v198
	v_add_u32_e32 v215, 0x4b, v159
	s_nop 0
	v_cndmask_b32_e32 v86, v213, v86, vcc
	v_cmp_le_i32_e32 vcc, v215, v198
	v_add_u32_e32 v215, 0x6b, v159
	s_nop 0
	v_cndmask_b32_e32 v71, v213, v71, vcc
	v_cmp_le_i32_e32 vcc, v215, v198
	v_add_u32_e32 v215, 0x50, v159
	s_nop 0
	v_cndmask_b32_e32 v87, v213, v87, vcc
	v_cmp_le_i32_e32 vcc, v215, v198
	v_add_u32_e32 v215, 0x70, v159
	s_nop 0
	v_cndmask_b32_e32 v72, v213, v72, vcc
	v_cmp_le_i32_e32 vcc, v215, v198
	v_add_u32_e32 v215, 0x51, v159
	s_nop 0
	v_cndmask_b32_e32 v88, v213, v88, vcc
	v_cmp_le_i32_e32 vcc, v215, v198
	v_add_u32_e32 v215, 0x71, v159
	s_nop 0
	v_cndmask_b32_e32 v73, v213, v73, vcc
	v_cmp_le_i32_e32 vcc, v215, v198
	v_add_u32_e32 v215, 0x52, v159
	s_nop 0
	v_cndmask_b32_e32 v89, v213, v89, vcc
	v_cmp_le_i32_e32 vcc, v215, v198
	v_add_u32_e32 v215, 0x72, v159
	s_nop 0
	v_cndmask_b32_e32 v74, v213, v74, vcc
	v_cmp_le_i32_e32 vcc, v215, v198
	v_add_u32_e32 v215, 0x53, v159
	s_nop 0
	v_cndmask_b32_e32 v90, v213, v90, vcc
	v_cmp_le_i32_e32 vcc, v215, v198
	v_add_u32_e32 v215, 0x73, v159
	s_nop 0
	v_cndmask_b32_e32 v75, v213, v75, vcc
	v_cmp_le_i32_e32 vcc, v215, v198
	v_add_u32_e32 v215, 0x58, v159
	s_nop 0
	v_cndmask_b32_e32 v91, v213, v91, vcc
	v_cmp_le_i32_e32 vcc, v215, v198
	v_add_u32_e32 v215, 0x78, v159
	s_nop 0
	v_cndmask_b32_e32 v76, v213, v76, vcc
	v_cmp_le_i32_e32 vcc, v215, v198
	v_add_u32_e32 v215, 0x59, v159
	s_nop 0
	v_cndmask_b32_e32 v92, v213, v92, vcc
	v_cmp_le_i32_e32 vcc, v215, v198
	v_add_u32_e32 v215, 0x79, v159
	s_nop 0
	v_cndmask_b32_e32 v77, v213, v77, vcc
	v_cmp_le_i32_e32 vcc, v215, v198
	v_add_u32_e32 v215, 0x5a, v159
	s_nop 0
	v_cndmask_b32_e32 v93, v213, v93, vcc
	v_cmp_le_i32_e32 vcc, v215, v198
	v_add_u32_e32 v215, 0x7a, v159
	s_nop 0
	v_cndmask_b32_e32 v78, v213, v78, vcc
	v_cmp_le_i32_e32 vcc, v215, v198
	v_add_u32_e32 v215, 0x5b, v159
	v_add_u32_e32 v159, 0x7b, v159
	v_cndmask_b32_e32 v94, v213, v94, vcc
	v_cmp_le_i32_e32 vcc, v215, v198
	s_nop 1
	v_cndmask_b32_e32 v79, v213, v79, vcc
	v_cmp_le_i32_e32 vcc, v159, v198
	s_nop 1
	v_cndmask_b32_e32 v95, v213, v95, vcc

; #define SBAR() __builtin_amdgcn_sched_barrier(0)
; template <int OFF> __device__ __forceinline__ s16x4 tr_read(int vb) { s16x4 r; asm volatile("ds_read_b64_tr_b16 %0, %1 offset:%2" : "=&v"(r) : "v"(vb), "i"(OFF) : "memory"); return r; }
; template <int D0> __device__ __forceinline__ void pv_one(f32x16& od, int vb, bf16x8 pa0, bf16x8 pa1, bf16x8 pa2, bf16x8 pa3) {
;     const s16x4 l0 = tr_read<v_rd_off(D0, 0, 0)>(vb), h0 = tr_read<v_rd_off(D0, 0, 1)>(vb), l1 = tr_read<v_rd_off(D0, 1, 0)>(vb), h1 = tr_read<v_rd_off(D0, 1, 1)>(vb);
;     const s16x4 l2 = tr_read<v_rd_off(D0, 2, 0)>(vb), h2 = tr_read<v_rd_off(D0, 2, 1)>(vb), l3 = tr_read<v_rd_off(D0, 3, 0)>(vb), h3 = tr_read<v_rd_off(D0, 3, 1)>(vb);
;     asm volatile("s_waitcnt lgkmcnt(0)" ::: "memory"); SBAR();
;     ...
;     od = __builtin_amdgcn_mfma_f32_32x32x16_bf16(pa0, PKV(l0, h0), od, 0, 0, 0);
;     od = __builtin_amdgcn_mfma_f32_32x32x16_bf16(pa1, PKV(l1, h1), od, 0, 0, 0);
;     od = __builtin_amdgcn_mfma_f32_32x32x16_bf16(pa2, PKV(l2, h2), od, 0, 0, 0);
;     od = __builtin_amdgcn_mfma_f32_32x32x16_bf16(pa3, PKV(l3, h3), od, 0, 0, 0);
;     ...
; }
; __device__ __forceinline__ void pv_d0(f32x16* o, int vb, bf16x8 pa0, bf16x8 pa1, bf16x8 pa2, bf16x8 pa3) {
;     pv_one<0>(o[0], vb, pa0, pa1, pa2, pa3); pv_one<1>(o[1], vb, pa0, pa1, pa2, pa3); pv_one<2>(o[2], vb, pa0, pa1, pa2, pa3); pv_one<3>(o[3], vb, pa0, pa1, pa2, pa3);
; }
; template <int MODE, bool SAMPLE>
; __device__ __forceinline__ void attn_unit(const Params& p, char* lds, int b, int h, int qb) {
;     ...
;             PK4(p0, 0, pa0); PK4(p0, 8, pa1); PK4(p1, 0, pa2); PK4(p1, 8, pa3);
;             pv_d0(o, vb, pa0, pa1, pa2, pa3);
.LBB0_767:
	v_cvt_pk_bf16_f32 v218, v159, v215
	v_cvt_pk_bf16_f32 v219, v81, v82
	v_cvt_pk_bf16_f32 v220, v83, v84
	v_cvt_pk_bf16_f32 v221, v85, v216
	v_cvt_pk_bf16_f32 v82, v86, v87
	v_cvt_pk_bf16_f32 v83, v88, v89
	v_cvt_pk_bf16_f32 v84, v90, v91
	v_cvt_pk_bf16_f32 v85, v92, v79
	v_cvt_pk_bf16_f32 v64, v64, v65
	v_cvt_pk_bf16_f32 v65, v66, v67
	v_cvt_pk_bf16_f32 v66, v68, v69
	v_cvt_pk_bf16_f32 v67, v70, v80
	v_cvt_pk_bf16_f32 v68, v71, v72
	v_cvt_pk_bf16_f32 v69, v73, v74
	v_cvt_pk_bf16_f32 v70, v75, v76
	v_cvt_pk_bf16_f32 v71, v77, v78
	ds_read_b64_tr_b16 v[72:73], v190 offset:0
	ds_read_b64_tr_b16 v[74:75], v190 offset:0x800
	ds_read_b64_tr_b16 v[76:77], v190 offset:0x1000
	ds_read_b64_tr_b16 v[78:79], v190 offset:0x1800
	ds_read_b64_tr_b16 v[86:87], v190 offset:0x2000
	ds_read_b64_tr_b16 v[88:89], v190 offset:0x2800
	v_add_f32_e32 v94, v94, v95
	ds_read_b64_tr_b16 v[90:91], v190 offset:0x3000
	v_fmac_f32_e32 v94, v214, v93
	ds_read_b64_tr_b16 v[92:93], v190 offset:0x3800
	s_waitcnt lgkmcnt(0)
	v_permlane32_swap_b32_e32 v218, v220
	v_permlane32_swap_b32_e32 v219, v221
	v_permlane32_swap_b32_e32 v82, v84
	v_permlane32_swap_b32_e32 v83, v85
	v_permlane32_swap_b32_e32 v64, v66
	v_permlane32_swap_b32_e32 v65, v67
	v_permlane32_swap_b32_e32 v68, v70
	v_permlane32_swap_b32_e32 v69, v71
	s_setprio 1
	v_mfma_f32_32x32x16_bf16 v[16:31], v[218:221], v[72:75], v[16:31]
	ds_read_b64_tr_b16 v[72:73], v190 offset:0x200
	ds_read_b64_tr_b16 v[74:75], v190 offset:0xa00
	v_mfma_f32_32x32x16_bf16 v[16:31], v[82:85], v[76:79], v[16:31]
	ds_read_b64_tr_b16 v[76:77], v190 offset:0x1200
	ds_read_b64_tr_b16 v[78:79], v190 offset:0x1a00
	v_mfma_f32_32x32x16_bf16 v[16:31], v[64:67], v[86:89], v[16:31]
	ds_read_b64_tr_b16 v[86:87], v190 offset:0x2200
	ds_read_b64_tr_b16 v[88:89], v190 offset:0x2a00
	ds_read_b64_tr_b16 v[214:215], v190 offset:0x3200
	ds_read_b64_tr_b16 v[216:217], v190 offset:0x3a00
	s_waitcnt lgkmcnt(0)
	v_mfma_f32_32x32x16_bf16 v[16:31], v[68:71], v[90:93], v[16:31]
	v_mfma_f32_32x32x16_bf16 v[48:63], v[218:221], v[72:75], v[48:63]
	ds_read_b64_tr_b16 v[72:73], v190 offset:0x400
	ds_read_b64_tr_b16 v[74:75], v190 offset:0xc00
	v_mfma_f32_32x32x16_bf16 v[48:63], v[82:85], v[76:79], v[48:63]
	ds_read_b64_tr_b16 v[76:77], v190 offset:0x1400
	ds_read_b64_tr_b16 v[78:79], v190 offset:0x1c00
	v_mfma_f32_32x32x16_bf16 v[48:63], v[64:67], v[86:89], v[48:63]
	ds_read_b64_tr_b16 v[86:87], v190 offset:0x2400
	ds_read_b64_tr_b16 v[88:89], v190 offset:0x2c00
	ds_read_b64_tr_b16 v[90:91], v190 offset:0x3400
	ds_read_b64_tr_b16 v[92:93], v190 offset:0x3c00
	s_waitcnt lgkmcnt(0)
	v_mfma_f32_32x32x16_bf16 v[48:63], v[68:71], v[214:217], v[48:63]
	v_mfma_f32_32x32x16_bf16 v[32:47], v[218:221], v[72:75], v[32:47]
	ds_read_b64_tr_b16 v[72:73], v190 offset:0x600
	ds_read_b64_tr_b16 v[74:75], v190 offset:0xe00
	v_mfma_f32_32x32x16_bf16 v[32:47], v[82:85], v[76:79], v[32:47]
	ds_read_b64_tr_b16 v[76:77], v190 offset:0x1600
	ds_read_b64_tr_b16 v[78:79], v190 offset:0x1e00
	v_mfma_f32_32x32x16_bf16 v[32:47], v[64:67], v[86:89], v[32:47]
	ds_read_b64_tr_b16 v[86:87], v190 offset:0x2600
	ds_read_b64_tr_b16 v[88:89], v190 offset:0x2e00
	ds_read_b64_tr_b16 v[222:223], v190 offset:0x3600
	ds_read_b64_tr_b16 v[224:225], v190 offset:0x3e00
	s_waitcnt lgkmcnt(0)
	v_mfma_f32_32x32x16_bf16 v[32:47], v[68:71], v[90:93], v[32:47]
	v_mfma_f32_32x32x16_bf16 v[0:15], v[218:221], v[72:75], v[0:15]
	v_mov_b32_e32 v214, v94
	v_mfma_f32_32x32x16_bf16 v[0:15], v[82:85], v[76:79], v[0:15]
	v_mfma_f32_32x32x16_bf16 v[0:15], v[64:67], v[86:89], v[0:15]
	v_mfma_f32_32x32x16_bf16 v[0:15], v[68:71], v[222:225], v[0:15]
	s_setprio 0

; __device__ __forceinline__ int crow(int r, int hi) { return (r & 3) + 8 * (r >> 2) + 4 * hi; }
; __device__ __forceinline__ void qkt(f32x16& p0, f32x16& p1, const char* Ks, const char* Qs, int r32, int hi) {
; #pragma unroll
;     for (int d0 = 0; d0 < 8; ++d0) { const int cb = (d0 * 16 + hi * 8) * 2;
;         const bf16x8 qv = *reinterpret_cast<const bf16x8*>(Qs + KSWZ(r32, cb));
;         const bf16x8 b0 = *reinterpret_cast<const bf16x8*>(Ks + KSWZ(r32, cb));
;         const bf16x8 b1 = *reinterpret_cast<const bf16x8*>(Ks + KSWZ(32 + r32, cb));
;         p0 = __builtin_amdgcn_mfma_f32_32x32x16_bf16(b0, qv, p0, 0, 0, 0);
;         p1 = __builtin_amdgcn_mfma_f32_32x32x16_bf16(b1, qv, p1, 0, 0, 0); }
; }
; template <int MODE, bool SAMPLE>
; __device__ __forceinline__ void attn_unit(const Params& p, char* lds, int b, int h, int qb) {
;     ...
;         if (wact && j <= jd && var < 2) {
;             const char* Kt = K_lds + buf * 16384; const int vb = vb0 + buf * 16384;
;             f32x16 p0, p1; bf16x8 pa0, pa1, pa2, pa3;
;             if (MODE == 0) {
;                 const float* bt = biasL + j * 64 + 4 * hi;
; #pragma unroll
;                 for (int g = 0; g < 4; ++g) { const f32x4 a = *(const f32x4*)(bt + 8 * g), c = *(const f32x4*)(bt + 32 + 8 * g);
; #pragma unroll
;                     for (int i = 0; i < 4; ++i) { p0[4 * g + i] = a[i]; p1[4 * g + i] = c[i]; } }
;                 qkt(p0, p1, Kt, Qs, r32, hi);
;                 if (j == jd) {
; #pragma unroll
;                     for (int r = 0; r < 16; ++r) { const int kp = j * 64 + crow(r, hi); if (kp > qpos) p0[r] = -1e30f; if (kp + 32 > qpos) p1[r] = -1e30f; } }
.Lstg_5:
	v_add_u32_e32 v64, s24, v181
	v_add_u32_e32 v84, 0, v181
	ds_read_b128 v[216:219], v64
	ds_read_b128 v[80:83], v84
	ds_read_b128 v[64:67], v199
	ds_read_b128 v[68:71], v199 offset:32
	ds_read_b128 v[72:75], v199 offset:64
	ds_read_b128 v[76:79], v199 offset:96
	ds_read_b128 v[220:223], v84 offset:8192
	v_add_u32_e32 v159, s24, v182
	v_add_u32_e32 v215, s24, v184
	s_waitcnt lgkmcnt(1)
	s_setprio 1
	v_mfma_f32_32x32x16_bf16 v[64:79], v[80:83], v[216:219], v[64:79]
	ds_read_b128 v[80:83], v199 offset:128
	ds_read_b128 v[84:87], v199 offset:160
	ds_read_b128 v[88:91], v199 offset:192
	ds_read_b128 v[92:95], v199 offset:224
	ds_read_b128 v[224:227], v159
	v_add_u32_e32 v159, 0, v182
	s_cmp_lg_u32 s11, s18
	s_waitcnt lgkmcnt(1)
	v_mfma_f32_32x32x16_bf16 v[80:95], v[220:223], v[216:219], v[80:95]
	ds_read_b128 v[216:219], v159
	ds_read_b128 v[220:223], v159 offset:8192
	v_add_u32_e32 v159, 0, v184
	s_waitcnt lgkmcnt(1)
	v_mfma_f32_32x32x16_bf16 v[64:79], v[216:219], v[224:227], v[64:79]
	ds_read_b128 v[216:219], v159
	s_waitcnt lgkmcnt(1)
	v_mfma_f32_32x32x16_bf16 v[80:95], v[220:223], v[224:227], v[80:95]
	ds_read_b128 v[220:223], v215
	v_add_u32_e32 v215, s24, v186
	s_waitcnt lgkmcnt(0)
	v_mfma_f32_32x32x16_bf16 v[64:79], v[216:219], v[220:223], v[64:79]
	ds_read_b128 v[216:219], v159 offset:8192
	v_add_u32_e32 v159, s24, v185
	ds_read_b128 v[224:227], v159
	v_add_u32_e32 v159, 0, v185
	s_waitcnt lgkmcnt(1)
	v_mfma_f32_32x32x16_bf16 v[80:95], v[216:219], v[220:223], v[80:95]
	ds_read_b128 v[216:219], v159
	ds_read_b128 v[220:223], v159 offset:8192
	v_add_u32_e32 v159, 0, v186
	s_waitcnt lgkmcnt(1)
	v_mfma_f32_32x32x16_bf16 v[64:79], v[216:219], v[224:227], v[64:79]
	ds_read_b128 v[216:219], v159
	s_waitcnt lgkmcnt(1)
	v_mfma_f32_32x32x16_bf16 v[80:95], v[220:223], v[224:227], v[80:95]
	ds_read_b128 v[220:223], v215
	v_add_u32_e32 v215, s24, v188
	s_waitcnt lgkmcnt(0)
	v_mfma_f32_32x32x16_bf16 v[64:79], v[216:219], v[220:223], v[64:79]
	ds_read_b128 v[216:219], v159 offset:8192
	v_add_u32_e32 v159, s24, v187
	ds_read_b128 v[224:227], v159
	v_add_u32_e32 v159, 0, v187
	s_waitcnt lgkmcnt(1)
	v_mfma_f32_32x32x16_bf16 v[80:95], v[216:219], v[220:223], v[80:95]
	ds_read_b128 v[216:219], v159
	ds_read_b128 v[220:223], v159 offset:8192
	v_add_u32_e32 v159, 0, v188
	s_waitcnt lgkmcnt(1)
	v_mfma_f32_32x32x16_bf16 v[64:79], v[216:219], v[224:227], v[64:79]
	ds_read_b128 v[216:219], v159
	s_waitcnt lgkmcnt(1)
	v_mfma_f32_32x32x16_bf16 v[80:95], v[220:223], v[224:227], v[80:95]
	ds_read_b128 v[220:223], v215
	s_waitcnt lgkmcnt(0)
	v_mfma_f32_32x32x16_bf16 v[64:79], v[216:219], v[220:223], v[64:79]
	ds_read_b128 v[216:219], v159 offset:8192
	v_add_u32_e32 v159, s24, v189
	ds_read_b128 v[224:227], v159
	v_add_u32_e32 v159, 0, v189
	s_waitcnt lgkmcnt(1)
	v_mfma_f32_32x32x16_bf16 v[80:95], v[216:219], v[220:223], v[80:95]
	ds_read_b128 v[216:219], v159
	ds_read_b128 v[220:223], v159 offset:8192
	s_waitcnt lgkmcnt(1)
	v_mfma_f32_32x32x16_bf16 v[64:79], v[216:219], v[224:227], v[64:79]
	s_waitcnt lgkmcnt(0)
	v_mfma_f32_32x32x16_bf16 v[80:95], v[220:223], v[224:227], v[80:95]
	s_setprio 0
	s_cbranch_scc1 .LBB0_774
	v_add_u32_e32 v159, s14, v201
	v_add_u32_e32 v215, 32, v159
	v_cmp_le_i32_e32 vcc, v215, v198
	v_add_u32_e32 v215, 33, v159
	s_nop 6
	v_cndmask_b32_e32 v80, v213, v80, vcc
	v_cmp_lt_i32_e32 vcc, v159, v198
	s_nop 1
	v_cndmask_b32_e32 v65, v213, v65, vcc
	v_cmp_le_i32_e32 vcc, v159, v198
	s_nop 1
	v_cndmask_b32_e32 v64, v213, v64, vcc
	v_cmp_le_i32_e32 vcc, v215, v198
	v_add_u32_e32 v215, 2, v159
	s_nop 0
	v_cndmask_b32_e32 v81, v213, v81, vcc
	v_cmp_le_i32_e32 vcc, v215, v198
	v_add_u32_e32 v215, 34, v159
	s_nop 0
	v_cndmask_b32_e32 v66, v213, v66, vcc
	v_cmp_le_i32_e32 vcc, v215, v198
	v_add_u32_e32 v215, 3, v159
	s_nop 0
	v_cndmask_b32_e32 v82, v213, v82, vcc
	v_cmp_le_i32_e32 vcc, v215, v198
	v_add_u32_e32 v215, 35, v159
	s_nop 0
	v_cndmask_b32_e32 v67, v213, v67, vcc
	v_cmp_le_i32_e32 vcc, v215, v198
	v_add_u32_e32 v215, 8, v159
	s_nop 0
	v_cndmask_b32_e32 v83, v213, v83, vcc
	v_cmp_le_i32_e32 vcc, v215, v198
	v_add_u32_e32 v215, 40, v159
	s_nop 0
	v_cndmask_b32_e32 v68, v213, v68, vcc
	v_cmp_le_i32_e32 vcc, v215, v198
	v_add_u32_e32 v215, 9, v159
	s_nop 0
	v_cndmask_b32_e32 v84, v213, v84, vcc
	v_cmp_le_i32_e32 vcc, v215, v198
	v_add_u32_e32 v215, 41, v159
	s_nop 0
	v_cndmask_b32_e32 v69, v213, v69, vcc
	v_cmp_le_i32_e32 vcc, v215, v198
	v_add_u32_e32 v215, 10, v159
	s_nop 0
	v_cndmask_b32_e32 v85, v213, v85, vcc
	v_cmp_le_i32_e32 vcc, v215, v198
	v_add_u32_e32 v215, 42, v159
	s_nop 0
	v_cndmask_b32_e32 v70, v213, v70, vcc
	v_cmp_le_i32_e32 vcc, v215, v198
	v_add_u32_e32 v215, 11, v159
	s_nop 0
	v_cndmask_b32_e32 v86, v213, v86, vcc
	v_cmp_le_i32_e32 vcc, v215, v198
	v_add_u32_e32 v215, 43, v159
	s_nop 0
	v_cndmask_b32_e32 v71, v213, v71, vcc
	v_cmp_le_i32_e32 vcc, v215, v198
	v_add_u32_e32 v215, 16, v159
	s_nop 0
	v_cndmask_b32_e32 v87, v213, v87, vcc
	v_cmp_le_i32_e32 vcc, v215, v198
	v_add_u32_e32 v215, 48, v159
	s_nop 0
	v_cndmask_b32_e32 v72, v213, v72, vcc
	v_cmp_le_i32_e32 vcc, v215, v198
	v_add_u32_e32 v215, 17, v159
	s_nop 0
	v_cndmask_b32_e32 v88, v213, v88, vcc
	v_cmp_le_i32_e32 vcc, v215, v198
	v_add_u32_e32 v215, 49, v159
	s_nop 0
	v_cndmask_b32_e32 v73, v213, v73, vcc
	v_cmp_le_i32_e32 vcc, v215, v198
	v_add_u32_e32 v215, 18, v159
	s_nop 0
	v_cndmask_b32_e32 v89, v213, v89, vcc
	v_cmp_le_i32_e32 vcc, v215, v198
	v_add_u32_e32 v215, 50, v159
	s_nop 0
	v_cndmask_b32_e32 v74, v213, v74, vcc
	v_cmp_le_i32_e32 vcc, v215, v198
	v_add_u32_e32 v215, 19, v159
	s_nop 0
	v_cndmask_b32_e32 v90, v213, v90, vcc
	v_cmp_le_i32_e32 vcc, v215, v198
	v_add_u32_e32 v215, 51, v159
	s_nop 0
	v_cndmask_b32_e32 v75, v213, v75, vcc
	v_cmp_le_i32_e32 vcc, v215, v198
	v_add_u32_e32 v215, 24, v159
	s_nop 0
	v_cndmask_b32_e32 v91, v213, v91, vcc
	v_cmp_le_i32_e32 vcc, v215, v198
	v_add_u32_e32 v215, 56, v159
	s_nop 0
	v_cndmask_b32_e32 v76, v213, v76, vcc
	v_cmp_le_i32_e32 vcc, v215, v198
	v_add_u32_e32 v215, 25, v159
	s_nop 0
	v_cndmask_b32_e32 v92, v213, v92, vcc
	v_cmp_le_i32_e32 vcc, v215, v198
	v_add_u32_e32 v215, 57, v159
	s_nop 0
	v_cndmask_b32_e32 v77, v213, v77, vcc
	v_cmp_le_i32_e32 vcc, v215, v198
	v_add_u32_e32 v215, 26, v159
	s_nop 0
	v_cndmask_b32_e32 v93, v213, v93, vcc
	v_cmp_le_i32_e32 vcc, v215, v198
	v_add_u32_e32 v215, 58, v159
	s_nop 0
	v_cndmask_b32_e32 v78, v213, v78, vcc
	v_cmp_le_i32_e32 vcc, v215, v198
	v_add_u32_e32 v215, 27, v159
	v_add_u32_e32 v159, 59, v159
	v_cndmask_b32_e32 v94, v213, v94, vcc
	v_cmp_le_i32_e32 vcc, v215, v198
	s_nop 1
	v_cndmask_b32_e32 v79, v213, v79, vcc
	v_cmp_le_i32_e32 vcc, v159, v198
	s_nop 1
	v_cndmask_b32_e32 v95, v213, v95, vcc

; template <int MODE, bool SAMPLE>
; __device__ __forceinline__ void attn_unit(const Params& p, char* lds, int b, int h, int qb) {
;     ...
;                 f32x16 s0, s1;
; #pragma unroll
;                 for (int r = 0; r < 16; ++r) { p0[r] = __builtin_amdgcn_exp2f(fminf(p0[r], 100.f)); p1[r] = __builtin_amdgcn_exp2f(fminf(p1[r], 100.f));
;                     s0[r] = __builtin_amdgcn_rcpf(1.f + p0[r]); s1[r] = __builtin_amdgcn_rcpf(1.f + p1[r]); }
;                 float run = carry, bs[8];
; #pragma unroll
;                 for (int i = 7; i >= 0; --i) { const f32x16& S = (i >= 4) ? s1 : s0; const int rb = 4 * (i & 3);
;                     const float gs = (S[rb] * S[rb + 1]) * (S[rb + 2] * S[rb + 3]);
;                     auto rr = __builtin_amdgcn_permlane32_swap(__float_as_uint(gs), __float_as_uint(gs), false, false);
;                     const float glo = __uint_as_float(rr[0]), ghi = __uint_as_float(rr[1]);
;                     const float exH = run; run *= ghi; const float exL = run; run *= glo;
;                     bs[i] = hi ? exH : exL; }
;                 carry = run;
.LBB0_781:
	s_nop 10
	v_max_f32_e32 v67, v67, v67
	v_min_f32_e32 v67, 0x42c80000, v67
	v_exp_f32_e32 v219, v67
	v_max_f32_e32 v67, v84, v84
	v_min_f32_e32 v67, 0x42c80000, v67
	v_exp_f32_e32 v84, v67
	v_max_f32_e32 v67, v68, v68
	v_max_f32_e32 v68, v85, v85
	v_min_f32_e32 v68, 0x42c80000, v68
	v_exp_f32_e32 v85, v68
	v_max_f32_e32 v68, v69, v69
	v_max_f32_e32 v69, v86, v86
	v_min_f32_e32 v69, 0x42c80000, v69
	v_exp_f32_e32 v86, v69
	v_max_f32_e32 v69, v70, v70
	v_max_f32_e32 v70, v87, v87
	v_min_f32_e32 v70, 0x42c80000, v70
	v_exp_f32_e32 v87, v70
	v_max_f32_e32 v70, v71, v71
	v_max_f32_e32 v71, v88, v88
	v_min_f32_e32 v71, 0x42c80000, v71
	v_exp_f32_e32 v88, v71
	v_max_f32_e32 v71, v72, v72
	v_max_f32_e32 v72, v89, v89
	v_min_f32_e32 v72, 0x42c80000, v72
	v_exp_f32_e32 v89, v72
	v_max_f32_e32 v72, v73, v73
	v_max_f32_e32 v73, v90, v90
	v_min_f32_e32 v73, 0x42c80000, v73
	v_exp_f32_e32 v90, v73
	v_max_f32_e32 v73, v74, v74
	v_max_f32_e32 v74, v91, v91
	v_min_f32_e32 v74, 0x42c80000, v74
	v_exp_f32_e32 v91, v74
	v_max_f32_e32 v74, v75, v75
	v_max_f32_e32 v75, v92, v92
	v_min_f32_e32 v75, 0x42c80000, v75
	v_exp_f32_e32 v92, v75
	v_max_f32_e32 v75, v76, v76
	v_max_f32_e32 v76, v93, v93
	v_min_f32_e32 v76, 0x42c80000, v76
	v_exp_f32_e32 v93, v76
	v_max_f32_e32 v76, v77, v77
	v_max_f32_e32 v77, v94, v94
	v_min_f32_e32 v77, 0x42c80000, v77
	v_min_f32_e32 v75, 0x42c80000, v75
	v_exp_f32_e32 v94, v77
	v_max_f32_e32 v77, v78, v78
	v_exp_f32_e32 v237, v75
	v_min_f32_e32 v77, 0x42c80000, v77
	v_max_f32_e32 v79, v79, v79
	v_min_f32_e32 v76, 0x42c80000, v76
	v_exp_f32_e32 v241, v77
	v_min_f32_e32 v79, 0x42c80000, v79
	v_exp_f32_e32 v239, v76
	v_max_f32_e32 v78, v95, v95
	v_exp_f32_e32 v95, v79
	v_min_f32_e32 v71, 0x42c80000, v71
	v_add_f32_e32 v75, 1.0, v237
	v_exp_f32_e32 v229, v71
	v_rcp_f32_e32 v240, v75
	v_add_f32_e32 v75, 1.0, v93
	v_add_f32_e32 v77, 1.0, v241
	v_min_f32_e32 v72, 0x42c80000, v72
	v_min_f32_e32 v73, 0x42c80000, v73
	v_min_f32_e32 v74, 0x42c80000, v74
	v_rcp_f32_e32 v76, v75
	v_add_f32_e32 v75, 1.0, v239
	v_rcp_f32_e32 v244, v77
	v_add_f32_e32 v77, 1.0, v95
	v_exp_f32_e32 v231, v72
	v_exp_f32_e32 v233, v73
	v_exp_f32_e32 v235, v74
	v_rcp_f32_e32 v242, v75
	v_rcp_f32_e32 v245, v77
	v_min_f32_e32 v67, 0x42c80000, v67
	v_add_f32_e32 v71, 1.0, v229
	v_max_f32_e32 v81, v81, v81
	v_exp_f32_e32 v221, v67
	v_rcp_f32_e32 v232, v71
	v_add_f32_e32 v71, 1.0, v89
	v_min_f32_e32 v78, 0x42c80000, v78
	v_min_f32_e32 v81, 0x42c80000, v81
	v_min_f32_e32 v68, 0x42c80000, v68
	v_min_f32_e32 v69, 0x42c80000, v69
	v_min_f32_e32 v70, 0x42c80000, v70
	v_rcp_f32_e32 v72, v71
	v_add_f32_e32 v71, 1.0, v231
	v_add_f32_e32 v73, 1.0, v233
	v_add_f32_e32 v74, 1.0, v235
	v_exp_f32_e32 v243, v78
	v_mul_f32_e32 v78, v240, v242
	v_mul_f32_e32 v79, v244, v245
	v_exp_f32_e32 v214, v81
	v_max_f32_e32 v81, v82, v82
	v_exp_f32_e32 v223, v68
	v_exp_f32_e32 v225, v69
	v_exp_f32_e32 v227, v70
	v_rcp_f32_e32 v234, v71
	v_rcp_f32_e32 v236, v73
	v_rcp_f32_e32 v238, v74
	v_mul_f32_e32 v78, v78, v79
	v_min_f32_e32 v81, 0x42c80000, v81
	v_max_f32_e32 v66, v66, v66
	v_mov_b32_e32 v79, v78
	v_max_f32_e32 v64, v64, v64
	v_exp_f32_e32 v82, v81
	v_min_f32_e32 v66, 0x42c80000, v66
	v_max_f32_e32 v81, v83, v83
	v_add_f32_e32 v67, 1.0, v221
	v_permlane32_swap_b32_e32 v78, v79
	v_min_f32_e32 v64, 0x42c80000, v64
	v_max_f32_e32 v65, v65, v65
	v_exp_f32_e32 v217, v66
	v_min_f32_e32 v81, 0x42c80000, v81
	v_rcp_f32_e32 v224, v67
	v_add_f32_e32 v67, 1.0, v85
	v_mul_f32_e32 v79, v147, v79
	v_exp_f32_e32 v159, v64
	v_min_f32_e32 v65, 0x42c80000, v65
	v_exp_f32_e32 v83, v81
	v_rcp_f32_e32 v68, v67
	v_add_f32_e32 v67, 1.0, v223
	v_add_f32_e32 v69, 1.0, v225
	v_add_f32_e32 v70, 1.0, v227
	v_mul_f32_e32 v78, v79, v78
	v_cndmask_b32_e64 v147, v147, v79, s[12:13]
	v_mul_f32_e32 v79, v232, v234
	v_mul_f32_e32 v246, v236, v238
	v_exp_f32_e32 v215, v65
	v_rcp_f32_e32 v226, v67
	v_rcp_f32_e32 v228, v69
	v_rcp_f32_e32 v230, v70
	v_mul_f32_e32 v79, v79, v246
	v_max_f32_e32 v80, v80, v80
	v_mov_b32_e32 v246, v79
	v_min_f32_e32 v80, 0x42c80000, v80
	v_add_f32_e32 v66, 1.0, v217
	v_permlane32_swap_b32_e32 v79, v246
	v_exp_f32_e32 v149, v80
	v_add_f32_e32 v80, 1.0, v159
	v_add_f32_e32 v65, 1.0, v214
	v_rcp_f32_e32 v220, v66
	v_add_f32_e32 v66, 1.0, v83
	v_mul_f32_e32 v246, v78, v246
	v_rcp_f32_e32 v216, v80
	v_rcp_f32_e32 v80, v65
	v_add_f32_e32 v65, 1.0, v215
	v_rcp_f32_e32 v81, v66
	v_add_f32_e32 v66, 1.0, v219
	v_mul_f32_e32 v79, v246, v79
	v_cndmask_b32_e64 v246, v78, v246, s[12:13]
	v_mul_f32_e32 v78, v224, v226
	v_mul_f32_e32 v247, v228, v230
	v_rcp_f32_e32 v218, v65
	v_rcp_f32_e32 v222, v66
	v_mul_f32_e32 v78, v78, v247
	v_mov_b32_e32 v247, v78
	s_nop 1
	v_permlane32_swap_b32_e32 v78, v247
	v_mul_f32_e32 v247, v79, v247
	v_add_f32_e32 v74, 1.0, v92
	v_add_f32_e32 v75, 1.0, v94
	v_add_f32_e32 v77, 1.0, v243
	v_mul_f32_e32 v78, v247, v78
	v_cndmask_b32_e64 v247, v79, v247, s[12:13]
	v_mul_f32_e32 v79, v216, v218
	v_mul_f32_e32 v248, v220, v222
	v_rcp_f32_e32 v74, v74
	v_rcp_f32_e32 v75, v75
	v_rcp_f32_e32 v77, v77
	v_mul_f32_e32 v79, v79, v248
	v_mov_b32_e32 v248, v79
	s_nop 1
	v_permlane32_swap_b32_e32 v79, v248
	v_mul_f32_e32 v248, v78, v248
	v_add_f32_e32 v70, 1.0, v88
	v_add_f32_e32 v71, 1.0, v90
	v_add_f32_e32 v73, 1.0, v91
	v_mul_f32_e32 v249, v248, v79
	v_cndmask_b32_e64 v248, v78, v248, s[12:13]
	v_pk_mul_f32 v[78:79], v[74:75], v[76:77]
	v_rcp_f32_e32 v70, v70
	v_rcp_f32_e32 v71, v71
	v_rcp_f32_e32 v73, v73
	v_pk_mul_f32 v[78:79], v[78:79], v[78:79] op_sel:[0,1] op_sel_hi:[1,0]
	v_add_f32_e32 v66, 1.0, v84
	v_mov_b32_e32 v79, v78
	s_nop 1
	v_permlane32_swap_b32_e32 v78, v79
	v_mul_f32_e32 v79, v249, v79
; #define SBAR() __builtin_amdgcn_sched_barrier(0)
; template <int OFF> __device__ __forceinline__ s16x4 tr_read(int vb) { s16x4 r; asm volatile("ds_read_b64_tr_b16 %0, %1 offset:%2" : "=&v"(r) : "v"(vb), "i"(OFF) : "memory"); return r; }
; template <int D0> __device__ __forceinline__ void pv_one(f32x16& od, int vb, bf16x8 pa0, bf16x8 pa1, bf16x8 pa2, bf16x8 pa3) {
;     const s16x4 l0 = tr_read<v_rd_off(D0, 0, 0)>(vb), h0 = tr_read<v_rd_off(D0, 0, 1)>(vb), l1 = tr_read<v_rd_off(D0, 1, 0)>(vb), h1 = tr_read<v_rd_off(D0, 1, 1)>(vb);
;     const s16x4 l2 = tr_read<v_rd_off(D0, 2, 0)>(vb), h2 = tr_read<v_rd_off(D0, 2, 1)>(vb), l3 = tr_read<v_rd_off(D0, 3, 0)>(vb), h3 = tr_read<v_rd_off(D0, 3, 1)>(vb);
;     asm volatile("s_waitcnt lgkmcnt(0)" ::: "memory"); SBAR();
;     ...
;     od = __builtin_amdgcn_mfma_f32_32x32x16_bf16(pa0, PKV(l0, h0), od, 0, 0, 0);
;     od = __builtin_amdgcn_mfma_f32_32x32x16_bf16(pa1, PKV(l1, h1), od, 0, 0, 0);
;     od = __builtin_amdgcn_mfma_f32_32x32x16_bf16(pa2, PKV(l2, h2), od, 0, 0, 0);
;     od = __builtin_amdgcn_mfma_f32_32x32x16_bf16(pa3, PKV(l3, h3), od, 0, 0, 0);
;     ...
; }
; __device__ __forceinline__ void pv_d0(f32x16* o, int vb, bf16x8 pa0, bf16x8 pa1, bf16x8 pa2, bf16x8 pa3) {
;     pv_one<0>(o[0], vb, pa0, pa1, pa2, pa3); pv_one<1>(o[1], vb, pa0, pa1, pa2, pa3); pv_one<2>(o[2], vb, pa0, pa1, pa2, pa3); pv_one<3>(o[3], vb, pa0, pa1, pa2, pa3);
; }
; template <int MODE, bool SAMPLE>
; __device__ __forceinline__ void attn_unit(const Params& p, char* lds, int b, int h, int qb) {
;     ...
;                 carry = run;
; #pragma unroll
;                 for (int i = 0; i < 8; ++i) { f32x16& S = (i >= 4) ? s1 : s0; f32x16& Z = (i >= 4) ? p1 : p0; const int rb = 4 * (i & 3);
;                     const float i3 = bs[i] * S[rb + 3], i2 = i3 * S[rb + 2], i1 = i2 * S[rb + 1], i0 = i1 * S[rb];
;                     Z[rb + 3] *= i3; Z[rb + 2] *= i2; Z[rb + 1] *= i1; Z[rb] *= i0; }
;             }
;             PK4(p0, 0, pa0); PK4(p0, 8, pa1); PK4(p1, 0, pa2); PK4(p1, 8, pa3);
;             pv_d0(o, vb, pa0, pa1, pa2, pa3);
	v_add_f32_e32 v67, 1.0, v86
	v_add_f32_e32 v69, 1.0, v87
	v_mul_f32_e32 v250, v79, v78
	v_cndmask_b32_e64 v249, v249, v79, s[12:13]
	v_pk_mul_f32 v[78:79], v[70:71], v[72:73]
	v_rcp_f32_e32 v66, v66
	v_rcp_f32_e32 v67, v67
	v_rcp_f32_e32 v69, v69
	v_pk_mul_f32 v[78:79], v[78:79], v[78:79] op_sel:[0,1] op_sel_hi:[1,0]
	v_add_f32_e32 v64, 1.0, v149
	v_mov_b32_e32 v79, v78
	s_nop 1
	v_permlane32_swap_b32_e32 v78, v79
	v_mul_f32_e32 v79, v250, v79
	v_add_f32_e32 v65, 1.0, v82
	v_mul_f32_e32 v251, v79, v78
	v_cndmask_b32_e64 v250, v250, v79, s[12:13]
	v_pk_mul_f32 v[78:79], v[66:67], v[68:69]
	v_rcp_f32_e32 v64, v64
	v_rcp_f32_e32 v65, v65
	v_pk_mul_f32 v[78:79], v[78:79], v[78:79] op_sel:[0,1] op_sel_hi:[1,0]
	v_mul_f32_e32 v73, v73, v250
	v_mov_b32_e32 v79, v78
	s_nop 1
	v_permlane32_swap_b32_e32 v78, v79
	v_mul_f32_e32 v79, v251, v79
	v_mul_f32_e32 v252, v79, v78
	v_cndmask_b32_e64 v251, v251, v79, s[12:13]
	v_pk_mul_f32 v[78:79], v[64:65], v[80:81]
	v_mul_f32_e32 v69, v69, v251
	v_pk_mul_f32 v[78:79], v[78:79], v[78:79] op_sel:[0,1] op_sel_hi:[1,0]
	v_mul_f32_e32 v67, v67, v69
	v_mov_b32_e32 v79, v78
	s_nop 1
	v_permlane32_swap_b32_e32 v78, v79
	v_mul_f32_e32 v79, v252, v79
	v_cndmask_b32_e64 v252, v252, v79, s[12:13]
	v_mul_f32_e32 v81, v81, v252
	v_mul_f32_e32 v65, v65, v81
	v_mul_f32_e32 v77, v77, v249
	v_mul_f32_e32 v80, v80, v65
	v_mul_f32_e32 v65, v82, v65
	v_mul_f32_e32 v68, v68, v67
	v_mul_f32_e32 v71, v71, v73
	v_mul_f32_e32 v75, v75, v77
	v_mul_f32_e32 v82, v222, v248
	v_mul_f32_e32 v81, v83, v81
	v_mul_f32_e32 v66, v66, v68
	v_mul_f32_e32 v67, v86, v67
	v_mul_f32_e32 v72, v72, v71
	v_mul_f32_e32 v71, v90, v71
	v_mul_f32_e32 v76, v76, v75
	v_mul_f32_e32 v75, v94, v75
	v_mul_f32_e32 v83, v220, v82
	v_mul_f32_e32 v86, v230, v247
	v_mul_f32_e32 v90, v238, v246
	v_mul_f32_e32 v94, v245, v147
	v_mul_f32_e32 v64, v64, v80
	v_mul_f32_e32 v69, v87, v69
	v_mul_f32_e32 v66, v84, v66
	v_mul_f32_e32 v70, v70, v72
	v_mul_f32_e32 v73, v91, v73
	v_mul_f32_e32 v74, v74, v76
	v_mul_f32_e32 v84, v218, v83
	v_mul_f32_e32 v87, v228, v86
	v_mul_f32_e32 v91, v236, v90
	v_mul_f32_e32 v147, v244, v94
	v_mul_f32_e32 v64, v149, v64
	v_mul_f32_e32 v68, v85, v68
	v_mul_f32_e32 v70, v88, v70
	v_mul_f32_e32 v74, v92, v74
	v_mul_f32_e32 v85, v216, v84
	v_mul_f32_e32 v88, v226, v87
	v_mul_f32_e32 v92, v234, v91
	v_mul_f32_e32 v149, v242, v147
	v_mul_f32_e32 v80, v214, v80
	v_mul_f32_e32 v72, v89, v72
	v_mul_f32_e32 v77, v243, v77
	v_mul_f32_e32 v76, v93, v76
	v_mul_f32_e32 v85, v159, v85
	v_mul_f32_e32 v89, v224, v88
	v_mul_f32_e32 v93, v232, v92
	v_mul_f32_e32 v159, v240, v149
	v_mul_f32_e32 v82, v219, v82
	v_mul_f32_e32 v83, v217, v83
	v_mul_f32_e32 v84, v215, v84
	v_mul_f32_e32 v86, v227, v86
	v_mul_f32_e32 v87, v225, v87
	v_mul_f32_e32 v88, v223, v88
	v_mul_f32_e32 v89, v221, v89
	v_mul_f32_e32 v90, v235, v90
	v_mul_f32_e32 v91, v233, v91
	v_mul_f32_e32 v92, v231, v92
	v_mul_f32_e32 v93, v229, v93
	v_mul_f32_e32 v94, v95, v94
	v_mul_f32_e32 v95, v241, v147
	v_mul_f32_e32 v149, v239, v149
	v_mul_f32_e32 v159, v237, v159
	v_mul_f32_e32 v147, v79, v78
	v_cvt_pk_bf16_f32 v64, v64, v80
	v_cvt_pk_bf16_f32 v65, v65, v81
	v_cvt_pk_bf16_f32 v66, v66, v68
	v_cvt_pk_bf16_f32 v67, v67, v69
	v_cvt_pk_bf16_f32 v68, v70, v72
	v_cvt_pk_bf16_f32 v69, v71, v73
	v_cvt_pk_bf16_f32 v70, v74, v76
	v_cvt_pk_bf16_f32 v71, v75, v77
	v_cvt_pk_bf16_f32 v72, v85, v84
	v_cvt_pk_bf16_f32 v73, v83, v82
	v_cvt_pk_bf16_f32 v74, v89, v88
	v_cvt_pk_bf16_f32 v75, v87, v86
	v_cvt_pk_bf16_f32 v76, v93, v92
	v_cvt_pk_bf16_f32 v77, v91, v90
	v_cvt_pk_bf16_f32 v78, v159, v149
	v_cvt_pk_bf16_f32 v79, v95, v94
	ds_read_b64_tr_b16 v[80:81], v179 offset:0
	ds_read_b64_tr_b16 v[82:83], v179 offset:0x800
	ds_read_b64_tr_b16 v[84:85], v179 offset:0x1000
	ds_read_b64_tr_b16 v[86:87], v179 offset:0x1800
	ds_read_b64_tr_b16 v[88:89], v179 offset:0x2000
	ds_read_b64_tr_b16 v[90:91], v179 offset:0x2800
	ds_read_b64_tr_b16 v[92:93], v179 offset:0x3000
	ds_read_b64_tr_b16 v[94:95], v179 offset:0x3800
	s_waitcnt lgkmcnt(0)
	s_nop 0
	v_permlane32_swap_b32_e32 v64, v66
	v_permlane32_swap_b32_e32 v65, v67
	v_permlane32_swap_b32_e32 v68, v70
	v_permlane32_swap_b32_e32 v69, v71
	v_permlane32_swap_b32_e32 v72, v74
	v_permlane32_swap_b32_e32 v73, v75
	v_permlane32_swap_b32_e32 v76, v78
	v_permlane32_swap_b32_e32 v77, v79
	s_setprio 1
	v_mfma_f32_32x32x16_bf16 v[48:63], v[64:67], v[80:83], v[48:63]
	ds_read_b64_tr_b16 v[80:81], v179 offset:0x200
	ds_read_b64_tr_b16 v[82:83], v179 offset:0xa00
	v_mfma_f32_32x32x16_bf16 v[48:63], v[68:71], v[84:87], v[48:63]
	ds_read_b64_tr_b16 v[84:85], v179 offset:0x1200
	ds_read_b64_tr_b16 v[86:87], v179 offset:0x1a00
	v_mfma_f32_32x32x16_bf16 v[48:63], v[72:75], v[88:91], v[48:63]
	ds_read_b64_tr_b16 v[88:89], v179 offset:0x2200
	ds_read_b64_tr_b16 v[90:91], v179 offset:0x2a00
	v_mfma_f32_32x32x16_bf16 v[48:63], v[76:79], v[92:95], v[48:63]
	ds_read_b64_tr_b16 v[92:93], v179 offset:0x3200
	ds_read_b64_tr_b16 v[94:95], v179 offset:0x3a00
	s_waitcnt lgkmcnt(0)
	v_mfma_f32_32x32x16_bf16 v[32:47], v[64:67], v[80:83], v[32:47]
	ds_read_b64_tr_b16 v[80:81], v179 offset:0x400
	ds_read_b64_tr_b16 v[82:83], v179 offset:0xc00
	v_mfma_f32_32x32x16_bf16 v[32:47], v[68:71], v[84:87], v[32:47]
	ds_read_b64_tr_b16 v[84:85], v179 offset:0x1400
	ds_read_b64_tr_b16 v[86:87], v179 offset:0x1c00
	v_mfma_f32_32x32x16_bf16 v[32:47], v[72:75], v[88:91], v[32:47]
	ds_read_b64_tr_b16 v[88:89], v179 offset:0x2400
	ds_read_b64_tr_b16 v[90:91], v179 offset:0x2c00
	v_mfma_f32_32x32x16_bf16 v[32:47], v[76:79], v[92:95], v[32:47]
	ds_read_b64_tr_b16 v[92:93], v179 offset:0x3400
	ds_read_b64_tr_b16 v[94:95], v179 offset:0x3c00
	s_waitcnt lgkmcnt(0)
	v_mfma_f32_32x32x16_bf16 v[16:31], v[64:67], v[80:83], v[16:31]
	ds_read_b64_tr_b16 v[80:81], v179 offset:0x600
	ds_read_b64_tr_b16 v[82:83], v179 offset:0xe00
	v_mfma_f32_32x32x16_bf16 v[16:31], v[68:71], v[84:87], v[16:31]
	ds_read_b64_tr_b16 v[84:85], v179 offset:0x1600
	ds_read_b64_tr_b16 v[86:87], v179 offset:0x1e00
	v_mfma_f32_32x32x16_bf16 v[16:31], v[72:75], v[88:91], v[16:31]
	ds_read_b64_tr_b16 v[88:89], v179 offset:0x2600
	ds_read_b64_tr_b16 v[90:91], v179 offset:0x2e00
	v_mfma_f32_32x32x16_bf16 v[16:31], v[76:79], v[92:95], v[16:31]
	ds_read_b64_tr_b16 v[92:93], v179 offset:0x3600
	ds_read_b64_tr_b16 v[94:95], v179 offset:0x3e00
	s_waitcnt lgkmcnt(0)
	v_mfma_f32_32x32x16_bf16 v[0:15], v[64:67], v[80:83], v[0:15]
	v_mfma_f32_32x32x16_bf16 v[0:15], v[68:71], v[84:87], v[0:15]
	v_mfma_f32_32x32x16_bf16 v[0:15], v[72:75], v[88:91], v[0:15]
	v_mfma_f32_32x32x16_bf16 v[0:15], v[76:79], v[92:95], v[0:15]
	s_setprio 0

; __device__ __forceinline__ int crow(int r, int hi) { return (r & 3) + 8 * (r >> 2) + 4 * hi; }
; __device__ __forceinline__ void qkt(f32x16& p0, f32x16& p1, const char* Ks, const char* Qs, int r32, int hi) {
; #pragma unroll
;     for (int d0 = 0; d0 < 8; ++d0) { const int cb = (d0 * 16 + hi * 8) * 2;
;         const bf16x8 qv = *reinterpret_cast<const bf16x8*>(Qs + KSWZ(r32, cb));
;         const bf16x8 b0 = *reinterpret_cast<const bf16x8*>(Ks + KSWZ(r32, cb));
;         const bf16x8 b1 = *reinterpret_cast<const bf16x8*>(Ks + KSWZ(32 + r32, cb));
;         p0 = __builtin_amdgcn_mfma_f32_32x32x16_bf16(b0, qv, p0, 0, 0, 0);
;         p1 = __builtin_amdgcn_mfma_f32_32x32x16_bf16(b1, qv, p1, 0, 0, 0); }
; }
; template <int MODE, bool SAMPLE>
; __device__ __forceinline__ void attn_unit(const Params& p, char* lds, int b, int h, int qb) {
;     ...
;             } else {
;                 p0 = f32x16{}; p1 = f32x16{};
;                 qkt(p0, p1, Kt, Qs, r32, hi);
;                 if (j == jd) {
; #pragma unroll
;                     for (int r = 0; r < 16; ++r) { const int kp = j * 64 + crow(r, hi); if (kp >= qpos) p0[r] = -1e30f; if (kp + 32 >= qpos) p1[r] = -1e30f; } }
.Lstg_6:
	v_add_u32_e32 v72, 0, v181
	ds_read_b128 v[64:67], v72 offset:16384
	v_add_u32_e32 v68, s10, v181
	ds_read_b128 v[68:71], v68
	v_add_u32_e32 v149, 0, v182
	v_add_u32_e32 v159, s10, v182
	ds_read_b128 v[218:221], v159
	v_add_u32_e32 v159, s10, v184
	s_cmp_lg_u32 s97, s33
	s_waitcnt lgkmcnt(1)
	s_setprio 1
	v_mfma_f32_32x32x16_bf16 v[80:95], v[64:67], v[68:71], 0
	ds_read_b128 v[64:67], v72 offset:24576
	ds_read_b128 v[214:217], v149 offset:16384
	s_waitcnt lgkmcnt(0)
	v_mfma_f32_32x32x16_bf16 v[80:95], v[214:217], v[218:221], v[80:95]
	ds_read_b128 v[214:217], v149 offset:24576
	v_add_u32_e32 v149, 0, v184
	v_mfma_f32_32x32x16_bf16 v[64:79], v[64:67], v[68:71], 0
	s_waitcnt lgkmcnt(0)
	v_mfma_f32_32x32x16_bf16 v[64:79], v[214:217], v[218:221], v[64:79]
	ds_read_b128 v[214:217], v149 offset:16384
	ds_read_b128 v[218:221], v159
	v_add_u32_e32 v159, s10, v185
	s_waitcnt lgkmcnt(0)
	v_mfma_f32_32x32x16_bf16 v[80:95], v[214:217], v[218:221], v[80:95]
	ds_read_b128 v[214:217], v149 offset:24576
	v_add_u32_e32 v149, 0, v185
	s_waitcnt lgkmcnt(0)
	v_mfma_f32_32x32x16_bf16 v[64:79], v[214:217], v[218:221], v[64:79]
	ds_read_b128 v[214:217], v149 offset:16384
	ds_read_b128 v[218:221], v159
	v_add_u32_e32 v159, s10, v186
	s_waitcnt lgkmcnt(0)
	v_mfma_f32_32x32x16_bf16 v[80:95], v[214:217], v[218:221], v[80:95]
	ds_read_b128 v[214:217], v149 offset:24576
	v_add_u32_e32 v149, 0, v186
	s_waitcnt lgkmcnt(0)
	v_mfma_f32_32x32x16_bf16 v[64:79], v[214:217], v[218:221], v[64:79]
	ds_read_b128 v[214:217], v149 offset:16384
	ds_read_b128 v[218:221], v159
	v_add_u32_e32 v159, s10, v187
	s_waitcnt lgkmcnt(0)
	v_mfma_f32_32x32x16_bf16 v[80:95], v[214:217], v[218:221], v[80:95]
	ds_read_b128 v[214:217], v149 offset:24576
	v_add_u32_e32 v149, 0, v187
	s_waitcnt lgkmcnt(0)
	v_mfma_f32_32x32x16_bf16 v[64:79], v[214:217], v[218:221], v[64:79]
	ds_read_b128 v[214:217], v149 offset:16384
	ds_read_b128 v[218:221], v159
	v_add_u32_e32 v159, s10, v188
	s_waitcnt lgkmcnt(0)
	v_mfma_f32_32x32x16_bf16 v[80:95], v[214:217], v[218:221], v[80:95]
	ds_read_b128 v[214:217], v149 offset:24576
	v_add_u32_e32 v149, 0, v188
	s_waitcnt lgkmcnt(0)
	v_mfma_f32_32x32x16_bf16 v[64:79], v[214:217], v[218:221], v[64:79]
	ds_read_b128 v[214:217], v149 offset:16384
	ds_read_b128 v[218:221], v159
	v_add_u32_e32 v159, s10, v189
	s_waitcnt lgkmcnt(0)
	v_mfma_f32_32x32x16_bf16 v[80:95], v[214:217], v[218:221], v[80:95]
	ds_read_b128 v[214:217], v149 offset:24576
	v_add_u32_e32 v149, 0, v189
	s_waitcnt lgkmcnt(0)
	v_mfma_f32_32x32x16_bf16 v[64:79], v[214:217], v[218:221], v[64:79]
	ds_read_b128 v[214:217], v149 offset:16384
	ds_read_b128 v[218:221], v159
	s_waitcnt lgkmcnt(0)
	v_mfma_f32_32x32x16_bf16 v[80:95], v[214:217], v[218:221], v[80:95]
	ds_read_b128 v[214:217], v149 offset:24576
	s_waitcnt lgkmcnt(0)
	v_mfma_f32_32x32x16_bf16 v[64:79], v[214:217], v[218:221], v[64:79]
	s_setprio 0
	s_cbranch_scc1 .LBB0_789
	s_or_b64 s[78:79], s[74:75], s[70:71]
	s_nop 6
	v_cndmask_b32_e64 v94, v213, v94, s[78:79]
	s_or_b64 s[78:79], s[78:79], s[66:67]
	v_cndmask_b32_e64 v93, v213, v93, s[78:79]
	s_or_b64 s[78:79], s[78:79], s[62:63]
	v_cndmask_b32_e64 v92, v213, v92, s[78:79]
	s_or_b64 s[78:79], s[78:79], s[58:59]
	v_cndmask_b32_e64 v91, v213, v91, s[78:79]
	s_or_b64 s[78:79], s[78:79], s[54:55]
	v_cndmask_b32_e64 v90, v213, v90, s[78:79]
	s_or_b64 s[78:79], s[78:79], s[50:51]
	v_cndmask_b32_e64 v89, v213, v89, s[78:79]
	s_or_b64 s[78:79], s[78:79], s[46:47]
	v_cndmask_b32_e64 v88, v213, v88, s[78:79]
	s_or_b64 s[78:79], s[78:79], s[42:43]
	v_cndmask_b32_e64 v87, v213, v87, s[78:79]
	s_or_b64 s[78:79], s[78:79], s[38:39]
	v_cndmask_b32_e64 v86, v213, v86, s[78:79]
	s_or_b64 s[78:79], s[78:79], s[34:35]
	v_cndmask_b32_e64 v85, v213, v85, s[78:79]
	s_or_b64 s[78:79], s[78:79], s[28:29]
	v_cndmask_b32_e64 v84, v213, v84, s[78:79]
	s_or_b64 s[78:79], s[78:79], s[24:25]
	v_cndmask_b32_e64 v83, v213, v83, s[78:79]
	s_or_b64 s[78:79], s[78:79], s[20:21]
	v_cndmask_b32_e64 v82, v213, v82, s[78:79]
	s_or_b64 s[78:79], s[78:79], s[16:17]
	v_cndmask_b32_e64 v81, v213, v81, s[78:79]
	s_or_b64 s[78:79], s[78:79], vcc
	v_cndmask_b32_e64 v80, v213, v80, s[78:79]
	s_or_b64 s[78:79], s[76:77], s[72:73]
	v_cndmask_b32_e64 v78, v213, v78, s[78:79]
	s_or_b64 s[78:79], s[78:79], s[68:69]
	v_cndmask_b32_e64 v77, v213, v77, s[78:79]
	s_or_b64 s[78:79], s[78:79], s[64:65]
	v_cndmask_b32_e64 v76, v213, v76, s[78:79]
	s_or_b64 s[78:79], s[78:79], s[60:61]
	v_cndmask_b32_e64 v75, v213, v75, s[78:79]
	s_or_b64 s[78:79], s[78:79], s[56:57]
	v_cndmask_b32_e64 v74, v213, v74, s[78:79]
	s_or_b64 s[78:79], s[78:79], s[52:53]
	v_cndmask_b32_e64 v73, v213, v73, s[78:79]
	s_or_b64 s[78:79], s[78:79], s[48:49]
	v_cndmask_b32_e64 v72, v213, v72, s[78:79]
	s_or_b64 s[78:79], s[78:79], s[44:45]
	v_cndmask_b32_e64 v71, v213, v71, s[78:79]
	s_or_b64 s[78:79], s[78:79], s[40:41]
	v_cndmask_b32_e64 v70, v213, v70, s[78:79]
	s_or_b64 s[78:79], s[78:79], s[36:37]
	v_cndmask_b32_e64 v69, v213, v69, s[78:79]
	s_or_b64 s[78:79], s[78:79], s[30:31]
	v_cndmask_b32_e64 v68, v213, v68, s[78:79]
	s_or_b64 s[78:79], s[78:79], s[26:27]
	v_cndmask_b32_e64 v67, v213, v67, s[78:79]
	s_or_b64 s[78:79], s[78:79], s[22:23]
	v_cndmask_b32_e64 v66, v213, v66, s[78:79]
	s_or_b64 s[78:79], s[78:79], s[18:19]
	v_cndmask_b32_e64 v65, v213, v65, s[78:79]
	s_or_b64 s[78:79], s[78:79], s[0:1]
	v_cndmask_b32_e64 v95, v213, v95, s[74:75]
	v_cndmask_b32_e64 v79, v213, v79, s[76:77]
	v_cndmask_b32_e64 v64, v213, v64, s[78:79]
; template <int MODE, bool SAMPLE>
; __device__ __forceinline__ void attn_unit(const Params& p, char* lds, int b, int h, int qb) {
;     ...
;                 f32x16 s0, s1;
; #pragma unroll
;                 for (int r = 0; r < 16; ++r) { p0[r] = __builtin_amdgcn_exp2f(fminf(p0[r], 100.f)); p1[r] = __builtin_amdgcn_exp2f(fminf(p1[r], 100.f));
;                     s0[r] = __builtin_amdgcn_rcpf(1.f + p0[r]); s1[r] = __builtin_amdgcn_rcpf(1.f + p1[r]); }
;                 float run = carry, bs[8];
; #pragma unroll
;                 for (int i = 7; i >= 0; --i) { const f32x16& S = (i >= 4) ? s1 : s0; const int rb = 4 * (i & 3);
;                     const float gs = (S[rb] * S[rb + 1]) * (S[rb + 2] * S[rb + 3]);
;                     auto rr = __builtin_amdgcn_permlane32_swap(__float_as_uint(gs), __float_as_uint(gs), false, false);
;                     const float glo = __uint_as_float(rr[0]), ghi = __uint_as_float(rr[1]);
;                     const float exH = run; run *= ghi; const float exL = run; run *= glo;
;                     bs[i] = hi ? exH : exL; }
;                 carry = run;
.LBB0_789:
	s_nop 10
	v_max_f32_e32 v67, v67, v67
	v_min_f32_e32 v67, 0x42c80000, v67
	v_exp_f32_e32 v219, v67
	v_max_f32_e32 v67, v84, v84
	v_min_f32_e32 v67, 0x42c80000, v67
	v_exp_f32_e32 v84, v67
	v_max_f32_e32 v67, v68, v68
	v_max_f32_e32 v68, v85, v85
	v_min_f32_e32 v68, 0x42c80000, v68
	v_exp_f32_e32 v85, v68
	v_max_f32_e32 v68, v69, v69
	v_max_f32_e32 v69, v86, v86
	v_min_f32_e32 v69, 0x42c80000, v69
	v_exp_f32_e32 v86, v69
	v_max_f32_e32 v69, v70, v70
	v_max_f32_e32 v70, v87, v87
	v_min_f32_e32 v70, 0x42c80000, v70
	v_exp_f32_e32 v87, v70
	v_max_f32_e32 v70, v71, v71
	v_max_f32_e32 v71, v88, v88
	v_min_f32_e32 v71, 0x42c80000, v71
	v_exp_f32_e32 v88, v71
	v_max_f32_e32 v71, v72, v72
	v_max_f32_e32 v72, v89, v89
	v_min_f32_e32 v72, 0x42c80000, v72
	v_exp_f32_e32 v89, v72
	v_max_f32_e32 v72, v73, v73
	v_max_f32_e32 v73, v90, v90
	v_min_f32_e32 v73, 0x42c80000, v73
	v_exp_f32_e32 v90, v73
	v_max_f32_e32 v73, v74, v74
	v_max_f32_e32 v74, v91, v91
	v_min_f32_e32 v74, 0x42c80000, v74
	v_exp_f32_e32 v91, v74
	v_max_f32_e32 v74, v75, v75
	v_max_f32_e32 v75, v92, v92
	v_min_f32_e32 v75, 0x42c80000, v75
	v_exp_f32_e32 v92, v75
	v_max_f32_e32 v75, v76, v76
	v_max_f32_e32 v76, v93, v93
	v_min_f32_e32 v76, 0x42c80000, v76
	v_exp_f32_e32 v93, v76
	v_max_f32_e32 v76, v77, v77
	v_max_f32_e32 v77, v94, v94
	v_min_f32_e32 v77, 0x42c80000, v77
	v_min_f32_e32 v75, 0x42c80000, v75
	v_exp_f32_e32 v94, v77
	v_max_f32_e32 v77, v78, v78
	v_exp_f32_e32 v237, v75
	v_min_f32_e32 v77, 0x42c80000, v77
	v_max_f32_e32 v79, v79, v79
	v_min_f32_e32 v76, 0x42c80000, v76
	v_exp_f32_e32 v241, v77
	v_min_f32_e32 v79, 0x42c80000, v79
	v_exp_f32_e32 v239, v76
	v_max_f32_e32 v78, v95, v95
	v_exp_f32_e32 v95, v79
	v_min_f32_e32 v71, 0x42c80000, v71
	v_add_f32_e32 v75, 1.0, v237
	v_exp_f32_e32 v229, v71
	v_rcp_f32_e32 v240, v75
	v_add_f32_e32 v75, 1.0, v93
	v_add_f32_e32 v77, 1.0, v241
	v_min_f32_e32 v72, 0x42c80000, v72
	v_min_f32_e32 v73, 0x42c80000, v73
	v_min_f32_e32 v74, 0x42c80000, v74
	v_rcp_f32_e32 v76, v75
	v_add_f32_e32 v75, 1.0, v239
	v_rcp_f32_e32 v244, v77
	v_add_f32_e32 v77, 1.0, v95
	v_exp_f32_e32 v231, v72
	v_exp_f32_e32 v233, v73
	v_exp_f32_e32 v235, v74
	v_rcp_f32_e32 v242, v75
	v_rcp_f32_e32 v245, v77
	v_min_f32_e32 v67, 0x42c80000, v67
	v_add_f32_e32 v71, 1.0, v229
	v_max_f32_e32 v81, v81, v81
	v_exp_f32_e32 v221, v67
	v_rcp_f32_e32 v232, v71
	v_add_f32_e32 v71, 1.0, v89
	v_min_f32_e32 v78, 0x42c80000, v78
	v_min_f32_e32 v81, 0x42c80000, v81
	v_min_f32_e32 v68, 0x42c80000, v68
	v_min_f32_e32 v69, 0x42c80000, v69
	v_min_f32_e32 v70, 0x42c80000, v70
	v_rcp_f32_e32 v72, v71
	v_add_f32_e32 v71, 1.0, v231
	v_add_f32_e32 v73, 1.0, v233
	v_add_f32_e32 v74, 1.0, v235
	v_exp_f32_e32 v243, v78
	v_mul_f32_e32 v78, v240, v242
	v_mul_f32_e32 v79, v244, v245
	v_exp_f32_e32 v214, v81
	v_max_f32_e32 v81, v82, v82
	v_exp_f32_e32 v223, v68
	v_exp_f32_e32 v225, v69
	v_exp_f32_e32 v227, v70
	v_rcp_f32_e32 v234, v71
	v_rcp_f32_e32 v236, v73
	v_rcp_f32_e32 v238, v74
	v_mul_f32_e32 v78, v78, v79
	v_min_f32_e32 v81, 0x42c80000, v81
	v_max_f32_e32 v66, v66, v66
	v_mov_b32_e32 v79, v78
	v_max_f32_e32 v64, v64, v64
	v_exp_f32_e32 v82, v81
	v_min_f32_e32 v66, 0x42c80000, v66
	v_max_f32_e32 v81, v83, v83
	v_add_f32_e32 v67, 1.0, v221
	v_permlane32_swap_b32_e32 v78, v79
	v_min_f32_e32 v64, 0x42c80000, v64
	v_max_f32_e32 v65, v65, v65
	v_exp_f32_e32 v217, v66
	v_min_f32_e32 v81, 0x42c80000, v81
	v_rcp_f32_e32 v224, v67
	v_add_f32_e32 v67, 1.0, v85
	v_mul_f32_e32 v79, v147, v79
	v_exp_f32_e32 v159, v64
	v_min_f32_e32 v65, 0x42c80000, v65
	v_exp_f32_e32 v83, v81
	v_rcp_f32_e32 v68, v67
	v_add_f32_e32 v67, 1.0, v223
	v_add_f32_e32 v69, 1.0, v225
	v_add_f32_e32 v70, 1.0, v227
	v_mul_f32_e32 v78, v79, v78
	v_cndmask_b32_e64 v147, v147, v79, s[12:13]
	v_mul_f32_e32 v79, v232, v234
	v_mul_f32_e32 v246, v236, v238
	v_exp_f32_e32 v215, v65
	v_rcp_f32_e32 v226, v67
	v_rcp_f32_e32 v228, v69
	v_rcp_f32_e32 v230, v70
	v_mul_f32_e32 v79, v79, v246
	v_max_f32_e32 v80, v80, v80
	v_mov_b32_e32 v246, v79
	v_min_f32_e32 v80, 0x42c80000, v80
	v_add_f32_e32 v66, 1.0, v217
	v_permlane32_swap_b32_e32 v79, v246
	v_exp_f32_e32 v149, v80
	v_add_f32_e32 v80, 1.0, v159
	v_add_f32_e32 v65, 1.0, v214
	v_rcp_f32_e32 v220, v66
	v_add_f32_e32 v66, 1.0, v83
	v_mul_f32_e32 v246, v78, v246
	v_rcp_f32_e32 v216, v80
	v_rcp_f32_e32 v80, v65
	v_add_f32_e32 v65, 1.0, v215
	v_rcp_f32_e32 v81, v66
	v_add_f32_e32 v66, 1.0, v219
	v_mul_f32_e32 v79, v246, v79
	v_cndmask_b32_e64 v246, v78, v246, s[12:13]
	v_mul_f32_e32 v78, v224, v226
	v_mul_f32_e32 v247, v228, v230
	v_rcp_f32_e32 v218, v65
	v_rcp_f32_e32 v222, v66
	v_mul_f32_e32 v78, v78, v247
	v_mov_b32_e32 v247, v78
	s_nop 1
	v_permlane32_swap_b32_e32 v78, v247
	v_mul_f32_e32 v247, v79, v247
	v_add_f32_e32 v74, 1.0, v92
	v_add_f32_e32 v75, 1.0, v94
	v_add_f32_e32 v77, 1.0, v243
	v_mul_f32_e32 v78, v247, v78
	v_cndmask_b32_e64 v247, v79, v247, s[12:13]
	v_mul_f32_e32 v79, v216, v218
	v_mul_f32_e32 v248, v220, v222
	v_rcp_f32_e32 v74, v74
	v_rcp_f32_e32 v75, v75
	v_rcp_f32_e32 v77, v77
	v_mul_f32_e32 v79, v79, v248
	v_mov_b32_e32 v248, v79
	s_nop 1
	v_permlane32_swap_b32_e32 v79, v248
	v_mul_f32_e32 v248, v78, v248
	v_add_f32_e32 v70, 1.0, v88
	v_add_f32_e32 v71, 1.0, v90
	v_add_f32_e32 v73, 1.0, v91
	v_mul_f32_e32 v249, v248, v79
	v_cndmask_b32_e64 v248, v78, v248, s[12:13]
	v_pk_mul_f32 v[78:79], v[74:75], v[76:77]
	v_rcp_f32_e32 v70, v70
	v_rcp_f32_e32 v71, v71
	v_rcp_f32_e32 v73, v73
	v_pk_mul_f32 v[78:79], v[78:79], v[78:79] op_sel:[0,1] op_sel_hi:[1,0]
	v_add_f32_e32 v66, 1.0, v84
	v_mov_b32_e32 v79, v78
	s_nop 1
	v_permlane32_swap_b32_e32 v78, v79
	v_mul_f32_e32 v79, v249, v79
; #define SBAR() __builtin_amdgcn_sched_barrier(0)
; template <int OFF> __device__ __forceinline__ s16x4 tr_read(int vb) { s16x4 r; asm volatile("ds_read_b64_tr_b16 %0, %1 offset:%2" : "=&v"(r) : "v"(vb), "i"(OFF) : "memory"); return r; }
; template <int D0> __device__ __forceinline__ void pv_one(f32x16& od, int vb, bf16x8 pa0, bf16x8 pa1, bf16x8 pa2, bf16x8 pa3) {
;     const s16x4 l0 = tr_read<v_rd_off(D0, 0, 0)>(vb), h0 = tr_read<v_rd_off(D0, 0, 1)>(vb), l1 = tr_read<v_rd_off(D0, 1, 0)>(vb), h1 = tr_read<v_rd_off(D0, 1, 1)>(vb);
;     const s16x4 l2 = tr_read<v_rd_off(D0, 2, 0)>(vb), h2 = tr_read<v_rd_off(D0, 2, 1)>(vb), l3 = tr_read<v_rd_off(D0, 3, 0)>(vb), h3 = tr_read<v_rd_off(D0, 3, 1)>(vb);
;     asm volatile("s_waitcnt lgkmcnt(0)" ::: "memory"); SBAR();
;     ...
;     od = __builtin_amdgcn_mfma_f32_32x32x16_bf16(pa0, PKV(l0, h0), od, 0, 0, 0);
;     od = __builtin_amdgcn_mfma_f32_32x32x16_bf16(pa1, PKV(l1, h1), od, 0, 0, 0);
;     od = __builtin_amdgcn_mfma_f32_32x32x16_bf16(pa2, PKV(l2, h2), od, 0, 0, 0);
;     od = __builtin_amdgcn_mfma_f32_32x32x16_bf16(pa3, PKV(l3, h3), od, 0, 0, 0);
;     ...
; }
; __device__ __forceinline__ void pv_d0(f32x16* o, int vb, bf16x8 pa0, bf16x8 pa1, bf16x8 pa2, bf16x8 pa3) {
;     pv_one<0>(o[0], vb, pa0, pa1, pa2, pa3); pv_one<1>(o[1], vb, pa0, pa1, pa2, pa3); pv_one<2>(o[2], vb, pa0, pa1, pa2, pa3); pv_one<3>(o[3], vb, pa0, pa1, pa2, pa3);
; }
; template <int MODE, bool SAMPLE>
; __device__ __forceinline__ void attn_unit(const Params& p, char* lds, int b, int h, int qb) {
;     ...
;                 carry = run;
; #pragma unroll
;                 for (int i = 0; i < 8; ++i) { f32x16& S = (i >= 4) ? s1 : s0; f32x16& Z = (i >= 4) ? p1 : p0; const int rb = 4 * (i & 3);
;                     const float i3 = bs[i] * S[rb + 3], i2 = i3 * S[rb + 2], i1 = i2 * S[rb + 1], i0 = i1 * S[rb];
;                     Z[rb + 3] *= i3; Z[rb + 2] *= i2; Z[rb + 1] *= i1; Z[rb] *= i0; }
;             }
;             PK4(p0, 0, pa0); PK4(p0, 8, pa1); PK4(p1, 0, pa2); PK4(p1, 8, pa3);
;             pv_d0(o, vb, pa0, pa1, pa2, pa3);
	v_add_f32_e32 v67, 1.0, v86
	v_add_f32_e32 v69, 1.0, v87
	v_mul_f32_e32 v250, v79, v78
	v_cndmask_b32_e64 v249, v249, v79, s[12:13]
	v_pk_mul_f32 v[78:79], v[70:71], v[72:73]
	v_rcp_f32_e32 v66, v66
	v_rcp_f32_e32 v67, v67
	v_rcp_f32_e32 v69, v69
	v_pk_mul_f32 v[78:79], v[78:79], v[78:79] op_sel:[0,1] op_sel_hi:[1,0]
	v_add_f32_e32 v64, 1.0, v149
	v_mov_b32_e32 v79, v78
	s_nop 1
	v_permlane32_swap_b32_e32 v78, v79
	v_mul_f32_e32 v79, v250, v79
	v_add_f32_e32 v65, 1.0, v82
	v_mul_f32_e32 v251, v79, v78
	v_cndmask_b32_e64 v250, v250, v79, s[12:13]
	v_pk_mul_f32 v[78:79], v[66:67], v[68:69]
	v_rcp_f32_e32 v64, v64
	v_rcp_f32_e32 v65, v65
	v_pk_mul_f32 v[78:79], v[78:79], v[78:79] op_sel:[0,1] op_sel_hi:[1,0]
	v_mul_f32_e32 v73, v73, v250
	v_mov_b32_e32 v79, v78
	s_nop 1
	v_permlane32_swap_b32_e32 v78, v79
	v_mul_f32_e32 v79, v251, v79
	v_mul_f32_e32 v252, v79, v78
	v_cndmask_b32_e64 v251, v251, v79, s[12:13]
	v_pk_mul_f32 v[78:79], v[64:65], v[80:81]
	v_mul_f32_e32 v69, v69, v251
	v_pk_mul_f32 v[78:79], v[78:79], v[78:79] op_sel:[0,1] op_sel_hi:[1,0]
	v_mul_f32_e32 v67, v67, v69
	v_mov_b32_e32 v79, v78
	s_nop 1
	v_permlane32_swap_b32_e32 v78, v79
	v_mul_f32_e32 v79, v252, v79
	v_cndmask_b32_e64 v252, v252, v79, s[12:13]
	v_mul_f32_e32 v81, v81, v252
	v_mul_f32_e32 v65, v65, v81
	v_mul_f32_e32 v77, v77, v249
	v_mul_f32_e32 v80, v80, v65
	v_mul_f32_e32 v65, v82, v65
	v_mul_f32_e32 v68, v68, v67
	v_mul_f32_e32 v71, v71, v73
	v_mul_f32_e32 v75, v75, v77
	v_mul_f32_e32 v82, v222, v248
	v_mul_f32_e32 v81, v83, v81
	v_mul_f32_e32 v66, v66, v68
	v_mul_f32_e32 v67, v86, v67
	v_mul_f32_e32 v72, v72, v71
	v_mul_f32_e32 v71, v90, v71
	v_mul_f32_e32 v76, v76, v75
	v_mul_f32_e32 v75, v94, v75
	v_mul_f32_e32 v83, v220, v82
	v_mul_f32_e32 v86, v230, v247
	v_mul_f32_e32 v90, v238, v246
	v_mul_f32_e32 v94, v245, v147
	v_mul_f32_e32 v64, v64, v80
	v_mul_f32_e32 v69, v87, v69
	v_mul_f32_e32 v66, v84, v66
	v_mul_f32_e32 v70, v70, v72
	v_mul_f32_e32 v73, v91, v73
	v_mul_f32_e32 v74, v74, v76
	v_mul_f32_e32 v84, v218, v83
	v_mul_f32_e32 v87, v228, v86
	v_mul_f32_e32 v91, v236, v90
	v_mul_f32_e32 v147, v244, v94
	v_mul_f32_e32 v64, v149, v64
	v_mul_f32_e32 v68, v85, v68
	v_mul_f32_e32 v70, v88, v70
	v_mul_f32_e32 v74, v92, v74
	v_mul_f32_e32 v85, v216, v84
	v_mul_f32_e32 v88, v226, v87
	v_mul_f32_e32 v92, v234, v91
	v_mul_f32_e32 v149, v242, v147
	v_mul_f32_e32 v80, v214, v80
	v_mul_f32_e32 v72, v89, v72
	v_mul_f32_e32 v77, v243, v77
	v_mul_f32_e32 v76, v93, v76
	v_mul_f32_e32 v85, v159, v85
	v_mul_f32_e32 v89, v224, v88
	v_mul_f32_e32 v93, v232, v92
	v_mul_f32_e32 v159, v240, v149
	v_mul_f32_e32 v82, v219, v82
	v_mul_f32_e32 v83, v217, v83
	v_mul_f32_e32 v84, v215, v84
	v_mul_f32_e32 v86, v227, v86
	v_mul_f32_e32 v87, v225, v87
	v_mul_f32_e32 v88, v223, v88
	v_mul_f32_e32 v89, v221, v89
	v_mul_f32_e32 v90, v235, v90
	v_mul_f32_e32 v91, v233, v91
	v_mul_f32_e32 v92, v231, v92
	v_mul_f32_e32 v93, v229, v93
	v_mul_f32_e32 v94, v95, v94
	v_mul_f32_e32 v95, v241, v147
	v_mul_f32_e32 v149, v239, v149
	v_mul_f32_e32 v159, v237, v159
	v_mul_f32_e32 v147, v79, v78
	v_cvt_pk_bf16_f32 v64, v64, v80
	v_cvt_pk_bf16_f32 v65, v65, v81
	v_cvt_pk_bf16_f32 v66, v66, v68
	v_cvt_pk_bf16_f32 v67, v67, v69
	v_cvt_pk_bf16_f32 v68, v70, v72
	v_cvt_pk_bf16_f32 v69, v71, v73
	v_cvt_pk_bf16_f32 v70, v74, v76
	v_cvt_pk_bf16_f32 v71, v75, v77
	v_cvt_pk_bf16_f32 v72, v85, v84
	v_cvt_pk_bf16_f32 v73, v83, v82
	v_cvt_pk_bf16_f32 v74, v89, v88
	v_cvt_pk_bf16_f32 v75, v87, v86
	v_cvt_pk_bf16_f32 v76, v93, v92
	v_cvt_pk_bf16_f32 v77, v91, v90
	v_cvt_pk_bf16_f32 v78, v159, v149
	v_cvt_pk_bf16_f32 v79, v95, v94
	ds_read_b64_tr_b16 v[80:81], v190 offset:0
	ds_read_b64_tr_b16 v[82:83], v190 offset:0x800
	ds_read_b64_tr_b16 v[84:85], v190 offset:0x1000
	ds_read_b64_tr_b16 v[86:87], v190 offset:0x1800
	ds_read_b64_tr_b16 v[88:89], v190 offset:0x2000
	ds_read_b64_tr_b16 v[90:91], v190 offset:0x2800
	ds_read_b64_tr_b16 v[92:93], v190 offset:0x3000
	ds_read_b64_tr_b16 v[94:95], v190 offset:0x3800
	s_waitcnt lgkmcnt(0)
	s_nop 0
	v_permlane32_swap_b32_e32 v64, v66
	v_permlane32_swap_b32_e32 v65, v67
	v_permlane32_swap_b32_e32 v68, v70
	v_permlane32_swap_b32_e32 v69, v71
	v_permlane32_swap_b32_e32 v72, v74
	v_permlane32_swap_b32_e32 v73, v75
	v_permlane32_swap_b32_e32 v76, v78
	v_permlane32_swap_b32_e32 v77, v79
	s_setprio 1
	v_mfma_f32_32x32x16_bf16 v[48:63], v[64:67], v[80:83], v[48:63]
	ds_read_b64_tr_b16 v[80:81], v190 offset:0x200
	ds_read_b64_tr_b16 v[82:83], v190 offset:0xa00
	v_mfma_f32_32x32x16_bf16 v[48:63], v[68:71], v[84:87], v[48:63]
	ds_read_b64_tr_b16 v[84:85], v190 offset:0x1200
	ds_read_b64_tr_b16 v[86:87], v190 offset:0x1a00
	v_mfma_f32_32x32x16_bf16 v[48:63], v[72:75], v[88:91], v[48:63]
	ds_read_b64_tr_b16 v[88:89], v190 offset:0x2200
	ds_read_b64_tr_b16 v[90:91], v190 offset:0x2a00
	v_mfma_f32_32x32x16_bf16 v[48:63], v[76:79], v[92:95], v[48:63]
	ds_read_b64_tr_b16 v[92:93], v190 offset:0x3200
	ds_read_b64_tr_b16 v[94:95], v190 offset:0x3a00
	s_waitcnt lgkmcnt(0)
	v_mfma_f32_32x32x16_bf16 v[32:47], v[64:67], v[80:83], v[32:47]
	ds_read_b64_tr_b16 v[80:81], v190 offset:0x400
	ds_read_b64_tr_b16 v[82:83], v190 offset:0xc00
	v_mfma_f32_32x32x16_bf16 v[32:47], v[68:71], v[84:87], v[32:47]
	ds_read_b64_tr_b16 v[84:85], v190 offset:0x1400
	ds_read_b64_tr_b16 v[86:87], v190 offset:0x1c00
	v_mfma_f32_32x32x16_bf16 v[32:47], v[72:75], v[88:91], v[32:47]
	ds_read_b64_tr_b16 v[88:89], v190 offset:0x2400
	ds_read_b64_tr_b16 v[90:91], v190 offset:0x2c00
	v_mfma_f32_32x32x16_bf16 v[32:47], v[76:79], v[92:95], v[32:47]
	ds_read_b64_tr_b16 v[92:93], v190 offset:0x3400
	ds_read_b64_tr_b16 v[94:95], v190 offset:0x3c00
	s_waitcnt lgkmcnt(0)
	v_mfma_f32_32x32x16_bf16 v[16:31], v[64:67], v[80:83], v[16:31]
	ds_read_b64_tr_b16 v[80:81], v190 offset:0x600
	ds_read_b64_tr_b16 v[82:83], v190 offset:0xe00
	v_mfma_f32_32x32x16_bf16 v[16:31], v[68:71], v[84:87], v[16:31]
	ds_read_b64_tr_b16 v[84:85], v190 offset:0x1600
	ds_read_b64_tr_b16 v[86:87], v190 offset:0x1e00
	v_mfma_f32_32x32x16_bf16 v[16:31], v[72:75], v[88:91], v[16:31]
	ds_read_b64_tr_b16 v[88:89], v190 offset:0x2600
	ds_read_b64_tr_b16 v[90:91], v190 offset:0x2e00
	v_mfma_f32_32x32x16_bf16 v[16:31], v[76:79], v[92:95], v[16:31]
	ds_read_b64_tr_b16 v[92:93], v190 offset:0x3600
	ds_read_b64_tr_b16 v[94:95], v190 offset:0x3e00
	s_waitcnt lgkmcnt(0)
	v_mfma_f32_32x32x16_bf16 v[0:15], v[64:67], v[80:83], v[0:15]
	v_mfma_f32_32x32x16_bf16 v[0:15], v[68:71], v[84:87], v[0:15]
	v_mfma_f32_32x32x16_bf16 v[0:15], v[72:75], v[88:91], v[0:15]
	v_mfma_f32_32x32x16_bf16 v[0:15], v[76:79], v[92:95], v[0:15]
	s_setprio 0

; __device__ __forceinline__ int crow(int r, int hi) { return (r & 3) + 8 * (r >> 2) + 4 * hi; }
; __device__ __forceinline__ void qkt(f32x16& p0, f32x16& p1, const char* Ks, const char* Qs, int r32, int hi) {
; #pragma unroll
;     for (int d0 = 0; d0 < 8; ++d0) { const int cb = (d0 * 16 + hi * 8) * 2;
;         const bf16x8 qv = *reinterpret_cast<const bf16x8*>(Qs + KSWZ(r32, cb));
;         const bf16x8 b0 = *reinterpret_cast<const bf16x8*>(Ks + KSWZ(r32, cb));
;         const bf16x8 b1 = *reinterpret_cast<const bf16x8*>(Ks + KSWZ(32 + r32, cb));
;         p0 = __builtin_amdgcn_mfma_f32_32x32x16_bf16(b0, qv, p0, 0, 0, 0);
;         p1 = __builtin_amdgcn_mfma_f32_32x32x16_bf16(b1, qv, p1, 0, 0, 0); }
; }
; template <int MODE, bool SAMPLE>
; __device__ __forceinline__ void attn_unit(const Params& p, char* lds, int b, int h, int qb) {
;     ...
;             } else {
;                 p0 = f32x16{}; p1 = f32x16{};
;                 qkt(p0, p1, Kt, Qs, r32, hi);
;                 if (j == jd) {
; #pragma unroll
;                     for (int r = 0; r < 16; ++r) { const int kp = j * 64 + crow(r, hi); if (kp >= qpos) p0[r] = -1e30f; if (kp + 32 >= qpos) p1[r] = -1e30f; } }
.Lstg_7:
	v_add_u32_e32 v72, 0, v181
	ds_read_b128 v[64:67], v72
	v_add_u32_e32 v68, s10, v181
	ds_read_b128 v[68:71], v68
	v_add_u32_e32 v149, 0, v182
	v_add_u32_e32 v159, s10, v182
	ds_read_b128 v[218:221], v159
	v_add_u32_e32 v159, s10, v184
	s_cmp_lg_u32 s11, s33
	s_waitcnt lgkmcnt(1)
	s_setprio 1
	v_mfma_f32_32x32x16_bf16 v[80:95], v[64:67], v[68:71], 0
	ds_read_b128 v[64:67], v72 offset:8192
	ds_read_b128 v[214:217], v149
	s_waitcnt lgkmcnt(0)
	v_mfma_f32_32x32x16_bf16 v[80:95], v[214:217], v[218:221], v[80:95]
	ds_read_b128 v[214:217], v149 offset:8192
	v_add_u32_e32 v149, 0, v184
	v_mfma_f32_32x32x16_bf16 v[64:79], v[64:67], v[68:71], 0
	s_waitcnt lgkmcnt(0)
	v_mfma_f32_32x32x16_bf16 v[64:79], v[214:217], v[218:221], v[64:79]
	ds_read_b128 v[214:217], v149
	ds_read_b128 v[218:221], v159
	v_add_u32_e32 v159, s10, v185
	s_waitcnt lgkmcnt(0)
	v_mfma_f32_32x32x16_bf16 v[80:95], v[214:217], v[218:221], v[80:95]
	ds_read_b128 v[214:217], v149 offset:8192
	v_add_u32_e32 v149, 0, v185
	s_waitcnt lgkmcnt(0)
	v_mfma_f32_32x32x16_bf16 v[64:79], v[214:217], v[218:221], v[64:79]
	ds_read_b128 v[214:217], v149
	ds_read_b128 v[218:221], v159
	v_add_u32_e32 v159, s10, v186
	s_waitcnt lgkmcnt(0)
	v_mfma_f32_32x32x16_bf16 v[80:95], v[214:217], v[218:221], v[80:95]
	ds_read_b128 v[214:217], v149 offset:8192
	v_add_u32_e32 v149, 0, v186
	s_waitcnt lgkmcnt(0)
	v_mfma_f32_32x32x16_bf16 v[64:79], v[214:217], v[218:221], v[64:79]
	ds_read_b128 v[214:217], v149
	ds_read_b128 v[218:221], v159
	v_add_u32_e32 v159, s10, v187
	s_waitcnt lgkmcnt(0)
	v_mfma_f32_32x32x16_bf16 v[80:95], v[214:217], v[218:221], v[80:95]
	ds_read_b128 v[214:217], v149 offset:8192
	v_add_u32_e32 v149, 0, v187
	s_waitcnt lgkmcnt(0)
	v_mfma_f32_32x32x16_bf16 v[64:79], v[214:217], v[218:221], v[64:79]
	ds_read_b128 v[214:217], v149
	ds_read_b128 v[218:221], v159
	v_add_u32_e32 v159, s10, v188
	s_waitcnt lgkmcnt(0)
	v_mfma_f32_32x32x16_bf16 v[80:95], v[214:217], v[218:221], v[80:95]
	ds_read_b128 v[214:217], v149 offset:8192
	v_add_u32_e32 v149, 0, v188
	s_waitcnt lgkmcnt(0)
	v_mfma_f32_32x32x16_bf16 v[64:79], v[214:217], v[218:221], v[64:79]
	ds_read_b128 v[214:217], v149
	ds_read_b128 v[218:221], v159
	v_add_u32_e32 v159, s10, v189
	s_waitcnt lgkmcnt(0)
	v_mfma_f32_32x32x16_bf16 v[80:95], v[214:217], v[218:221], v[80:95]
	ds_read_b128 v[214:217], v149 offset:8192
	v_add_u32_e32 v149, 0, v189
	s_waitcnt lgkmcnt(0)
	v_mfma_f32_32x32x16_bf16 v[64:79], v[214:217], v[218:221], v[64:79]
	ds_read_b128 v[214:217], v149
	ds_read_b128 v[218:221], v159
	s_waitcnt lgkmcnt(0)
	v_mfma_f32_32x32x16_bf16 v[80:95], v[214:217], v[218:221], v[80:95]
	ds_read_b128 v[214:217], v149 offset:8192
	s_waitcnt lgkmcnt(0)
	v_mfma_f32_32x32x16_bf16 v[64:79], v[214:217], v[218:221], v[64:79]
	s_setprio 0
	s_cbranch_scc1 .LBB0_781
	s_or_b64 s[78:79], s[74:75], s[70:71]
	s_nop 6
	v_cndmask_b32_e64 v94, v213, v94, s[78:79]
	s_or_b64 s[78:79], s[78:79], s[66:67]
	v_cndmask_b32_e64 v93, v213, v93, s[78:79]
	s_or_b64 s[78:79], s[78:79], s[62:63]
	v_cndmask_b32_e64 v92, v213, v92, s[78:79]
	s_or_b64 s[78:79], s[78:79], s[58:59]
	v_cndmask_b32_e64 v91, v213, v91, s[78:79]
	s_or_b64 s[78:79], s[78:79], s[54:55]
	v_cndmask_b32_e64 v90, v213, v90, s[78:79]
	s_or_b64 s[78:79], s[78:79], s[50:51]
	v_cndmask_b32_e64 v89, v213, v89, s[78:79]
	s_or_b64 s[78:79], s[78:79], s[46:47]
	v_cndmask_b32_e64 v88, v213, v88, s[78:79]
	s_or_b64 s[78:79], s[78:79], s[42:43]
	v_cndmask_b32_e64 v87, v213, v87, s[78:79]
	s_or_b64 s[78:79], s[78:79], s[38:39]
	v_cndmask_b32_e64 v86, v213, v86, s[78:79]
	s_or_b64 s[78:79], s[78:79], s[34:35]
	v_cndmask_b32_e64 v85, v213, v85, s[78:79]
	s_or_b64 s[78:79], s[78:79], s[28:29]
	v_cndmask_b32_e64 v84, v213, v84, s[78:79]
	s_or_b64 s[78:79], s[78:79], s[24:25]
	v_cndmask_b32_e64 v83, v213, v83, s[78:79]
	s_or_b64 s[78:79], s[78:79], s[20:21]
	v_cndmask_b32_e64 v82, v213, v82, s[78:79]
	s_or_b64 s[78:79], s[78:79], s[16:17]
	v_cndmask_b32_e64 v81, v213, v81, s[78:79]
	s_or_b64 s[78:79], s[78:79], vcc
	v_cndmask_b32_e64 v80, v213, v80, s[78:79]
	s_or_b64 s[78:79], s[76:77], s[72:73]
	v_cndmask_b32_e64 v78, v213, v78, s[78:79]
	s_or_b64 s[78:79], s[78:79], s[68:69]
	v_cndmask_b32_e64 v77, v213, v77, s[78:79]
	s_or_b64 s[78:79], s[78:79], s[64:65]
	v_cndmask_b32_e64 v76, v213, v76, s[78:79]
	s_or_b64 s[78:79], s[78:79], s[60:61]
	v_cndmask_b32_e64 v75, v213, v75, s[78:79]
	s_or_b64 s[78:79], s[78:79], s[56:57]
	v_cndmask_b32_e64 v74, v213, v74, s[78:79]
	s_or_b64 s[78:79], s[78:79], s[52:53]
	v_cndmask_b32_e64 v73, v213, v73, s[78:79]
	s_or_b64 s[78:79], s[78:79], s[48:49]
	v_cndmask_b32_e64 v72, v213, v72, s[78:79]
	s_or_b64 s[78:79], s[78:79], s[44:45]
	v_cndmask_b32_e64 v71, v213, v71, s[78:79]
	s_or_b64 s[78:79], s[78:79], s[40:41]
	v_cndmask_b32_e64 v70, v213, v70, s[78:79]
	s_or_b64 s[78:79], s[78:79], s[36:37]
	v_cndmask_b32_e64 v69, v213, v69, s[78:79]
	s_or_b64 s[78:79], s[78:79], s[30:31]
	v_cndmask_b32_e64 v68, v213, v68, s[78:79]
	s_or_b64 s[78:79], s[78:79], s[26:27]
	v_cndmask_b32_e64 v67, v213, v67, s[78:79]
	s_or_b64 s[78:79], s[78:79], s[22:23]
	v_cndmask_b32_e64 v66, v213, v66, s[78:79]
	s_or_b64 s[78:79], s[78:79], s[18:19]
	v_cndmask_b32_e64 v65, v213, v65, s[78:79]
	s_or_b64 s[78:79], s[78:79], s[0:1]
	v_cndmask_b32_e64 v95, v213, v95, s[74:75]
	v_cndmask_b32_e64 v79, v213, v79, s[76:77]
	v_cndmask_b32_e64 v64, v213, v64, s[78:79]
	s_branch .LBB0_781
